# v10 plus static priority: per-segment s_setprio flips deleted in the 10 GEMM K loops, waves 4-7 raised to priority 1 once before each loop
# speedup vs baseline: 1.0077x; 1.0077x over previous
.LBB0_232:
	s_ashr_i32 s25, s24, 31
	s_lshl_b64 s[26:27], s[24:25], 21
	s_add_u32 s26, s46, s26
	s_addc_u32 s27, s47, s27
	s_and_b64 s[28:29], s[2:3], exec
	s_cselect_b32 s25, s27, s35
	s_cselect_b32 s64, s26, s34
	s_ashr_i32 s23, s22, 31
	s_lshl_b64 s[28:29], s[22:23], 21
	s_add_u32 s28, s48, s28
	s_addc_u32 s29, s49, s29
	s_and_b64 s[38:39], s[2:3], exec
	s_cselect_b32 s23, s29, s37
	s_cselect_b32 s65, s28, s36
	s_add_u32 s66, s36, 0x100
	s_addc_u32 s67, s37, 0
	s_add_u32 s34, s34, 0x100080
	v_mov_b32_e32 v0, 0
	s_addc_u32 s35, s35, 0
	s_mov_b32 s68, -2
	v_mov_b32_e32 v1, v0
	v_mov_b32_e32 v2, v0
	v_mov_b32_e32 v3, v0
	v_mov_b32_e32 v4, v0
	v_mov_b32_e32 v5, v0
	v_mov_b32_e32 v6, v0
	v_mov_b32_e32 v7, v0
	v_mov_b32_e32 v12, v0
	v_mov_b32_e32 v13, v0
	v_mov_b32_e32 v14, v0
	v_mov_b32_e32 v15, v0
	v_mov_b32_e32 v20, v0
	v_mov_b32_e32 v21, v0
	v_mov_b32_e32 v22, v0
	v_mov_b32_e32 v23, v0
	v_mov_b32_e32 v28, v0
	v_mov_b32_e32 v29, v0
	v_mov_b32_e32 v30, v0
	v_mov_b32_e32 v31, v0
	v_mov_b32_e32 v36, v0
	v_mov_b32_e32 v37, v0
	v_mov_b32_e32 v38, v0
	v_mov_b32_e32 v39, v0
	v_mov_b32_e32 v44, v0
	v_mov_b32_e32 v45, v0
	v_mov_b32_e32 v46, v0
	v_mov_b32_e32 v47, v0
	v_mov_b32_e32 v52, v0
	v_mov_b32_e32 v53, v0
	v_mov_b32_e32 v54, v0
	v_mov_b32_e32 v55, v0
	v_mov_b32_e32 v8, v0
	v_mov_b32_e32 v9, v0
	v_mov_b32_e32 v10, v0
	v_mov_b32_e32 v11, v0
	v_mov_b32_e32 v16, v0
	v_mov_b32_e32 v17, v0
	v_mov_b32_e32 v18, v0
	v_mov_b32_e32 v19, v0
	v_mov_b32_e32 v24, v0
	v_mov_b32_e32 v25, v0
	v_mov_b32_e32 v26, v0
	v_mov_b32_e32 v27, v0
	v_mov_b32_e32 v32, v0
	v_mov_b32_e32 v33, v0
	v_mov_b32_e32 v34, v0
	v_mov_b32_e32 v35, v0
	v_mov_b32_e32 v40, v0
	v_mov_b32_e32 v41, v0
	v_mov_b32_e32 v42, v0
	v_mov_b32_e32 v43, v0
	v_mov_b32_e32 v48, v0
	v_mov_b32_e32 v49, v0
	v_mov_b32_e32 v50, v0
	v_mov_b32_e32 v51, v0
	v_mov_b32_e32 v56, v0
	v_mov_b32_e32 v57, v0
	v_mov_b32_e32 v58, v0
	v_mov_b32_e32 v59, v0
	v_mov_b32_e32 v60, v0
	v_mov_b32_e32 v61, v0
	v_mov_b32_e32 v62, v0
	v_mov_b32_e32 v63, v0
	v_mov_b32_e32 v64, v0
	v_mov_b32_e32 v65, v0
	v_mov_b32_e32 v66, v0
	v_mov_b32_e32 v67, v0
	v_mov_b32_e32 v68, v0
	v_mov_b32_e32 v69, v0
	v_mov_b32_e32 v70, v0
	v_mov_b32_e32 v71, v0
	v_mov_b32_e32 v80, v0
	v_mov_b32_e32 v81, v0
	v_mov_b32_e32 v82, v0
	v_mov_b32_e32 v83, v0
	v_mov_b32_e32 v84, v0
	v_mov_b32_e32 v85, v0
	v_mov_b32_e32 v86, v0
	v_mov_b32_e32 v87, v0
	v_mov_b32_e32 v96, v0
	v_mov_b32_e32 v97, v0
	v_mov_b32_e32 v98, v0
	v_mov_b32_e32 v99, v0
	v_mov_b32_e32 v100, v0
	v_mov_b32_e32 v101, v0
	v_mov_b32_e32 v102, v0
	v_mov_b32_e32 v103, v0
	v_mov_b32_e32 v112, v0
	v_mov_b32_e32 v113, v0
	v_mov_b32_e32 v114, v0
	v_mov_b32_e32 v115, v0
	v_mov_b32_e32 v116, v0
	v_mov_b32_e32 v117, v0
	v_mov_b32_e32 v118, v0
	v_mov_b32_e32 v119, v0
	v_mov_b32_e32 v72, v0
	v_mov_b32_e32 v73, v0
	v_mov_b32_e32 v74, v0
	v_mov_b32_e32 v75, v0
	v_mov_b32_e32 v76, v0
	v_mov_b32_e32 v77, v0
	v_mov_b32_e32 v78, v0
	v_mov_b32_e32 v79, v0
	v_mov_b32_e32 v88, v0
	v_mov_b32_e32 v89, v0
	v_mov_b32_e32 v90, v0
	v_mov_b32_e32 v91, v0
	v_mov_b32_e32 v92, v0
	v_mov_b32_e32 v93, v0
	v_mov_b32_e32 v94, v0
	v_mov_b32_e32 v95, v0
	v_mov_b32_e32 v104, v0
	v_mov_b32_e32 v105, v0
	v_mov_b32_e32 v106, v0
	v_mov_b32_e32 v107, v0
	v_mov_b32_e32 v108, v0
	v_mov_b32_e32 v109, v0
	v_mov_b32_e32 v110, v0
	v_mov_b32_e32 v111, v0
	v_mov_b32_e32 v120, v0
	v_mov_b32_e32 v121, v0
	v_mov_b32_e32 v122, v0
	v_mov_b32_e32 v123, v0
	v_mov_b32_e32 v124, v0
	v_mov_b32_e32 v125, v0
	v_mov_b32_e32 v126, v0
	v_mov_b32_e32 v127, v0
	s_cmp_ge_u32 s81, 4
	s_cbranch_scc0 .Lsp_skip0
	s_setprio 1
.Lsp_skip0:
.LBB0_233:
	ds_read_b128 v[162:165], v155
	ds_read_b128 v[166:169], v155 offset:1024
	ds_read_b128 v[170:173], v155 offset:2048
	ds_read_b128 v[174:177], v155 offset:3072
	ds_read_b128 v[178:181], v158
	ds_read_b128 v[182:185], v158 offset:1024
	ds_read_b128 v[186:189], v158 offset:2048
	ds_read_b128 v[190:193], v158 offset:3072
	s_add_u32 s36, s34, 0xfff00080
	s_addc_u32 s37, s35, -1
	s_cmp_eq_u32 s68, 60
	s_cselect_b32 s39, s25, s37
	s_cselect_b32 s38, s64, s36
	s_cselect_b32 s37, s23, s67
	s_cselect_b32 s36, s65, s66
	v_lshl_add_u64 v[144:145], s[34:35], 0, v[138:139]
	s_add_i32 m0, s31, 0xc000
	ds_read_b128 v[194:197], v159
	ds_read_b128 v[198:201], v159 offset:1024
	ds_read_b128 v[202:205], v159 offset:2048
	ds_read_b128 v[206:209], v159 offset:3072
	ds_read_b128 v[210:213], v159 offset:4096
	ds_read_b128 v[214:217], v159 offset:5120
	ds_read_b128 v[218:221], v159 offset:6144
	ds_read_b128 v[222:225], v159 offset:7168
	global_load_lds_dwordx4 v[144:145], off
	v_lshl_add_u64 v[144:145], s[34:35], 0, v[136:137]
	s_add_i32 m0, s31, 0xe000
	s_nop 0
	global_load_lds_dwordx4 v[144:145], off
	s_waitcnt vmcnt(8)
	s_waitcnt lgkmcnt(0)
	s_barrier
	s_waitcnt lgkmcnt(0)
	v_mfma_f32_16x16x32_bf16 v[124:127], v[162:165], v[194:197], v[124:127]
	v_mfma_f32_16x16x32_bf16 v[120:123], v[170:173], v[194:197], v[120:123]
	v_mfma_f32_16x16x32_bf16 v[108:111], v[162:165], v[202:205], v[108:111]
	v_mfma_f32_16x16x32_bf16 v[104:107], v[170:173], v[202:205], v[104:107]
	v_mfma_f32_16x16x32_bf16 v[92:95], v[162:165], v[210:213], v[92:95]
	v_mfma_f32_16x16x32_bf16 v[88:91], v[170:173], v[210:213], v[88:91]
	v_mfma_f32_16x16x32_bf16 v[76:79], v[162:165], v[218:221], v[76:79]
	v_mfma_f32_16x16x32_bf16 v[72:75], v[170:173], v[218:221], v[72:75]
	v_mfma_f32_16x16x32_bf16 v[124:127], v[166:169], v[198:201], v[124:127]
	v_mfma_f32_16x16x32_bf16 v[120:123], v[174:177], v[198:201], v[120:123]
	v_mfma_f32_16x16x32_bf16 v[108:111], v[166:169], v[206:209], v[108:111]
	v_mfma_f32_16x16x32_bf16 v[104:107], v[174:177], v[206:209], v[104:107]
	v_mfma_f32_16x16x32_bf16 v[92:95], v[166:169], v[214:217], v[92:95]
	v_mfma_f32_16x16x32_bf16 v[88:91], v[174:177], v[214:217], v[88:91]
	v_mfma_f32_16x16x32_bf16 v[76:79], v[166:169], v[222:225], v[76:79]
	v_mfma_f32_16x16x32_bf16 v[72:75], v[174:177], v[222:225], v[72:75]
	v_mfma_f32_16x16x32_bf16 v[116:119], v[178:181], v[194:197], v[116:119]
	v_mfma_f32_16x16x32_bf16 v[112:115], v[186:189], v[194:197], v[112:115]
	v_mfma_f32_16x16x32_bf16 v[100:103], v[178:181], v[202:205], v[100:103]
	v_mfma_f32_16x16x32_bf16 v[96:99], v[186:189], v[202:205], v[96:99]
	v_mfma_f32_16x16x32_bf16 v[84:87], v[178:181], v[210:213], v[84:87]
	v_mfma_f32_16x16x32_bf16 v[80:83], v[186:189], v[210:213], v[80:83]
	v_mfma_f32_16x16x32_bf16 v[68:71], v[178:181], v[218:221], v[68:71]
	v_mfma_f32_16x16x32_bf16 v[64:67], v[186:189], v[218:221], v[64:67]
	v_mfma_f32_16x16x32_bf16 v[116:119], v[182:185], v[198:201], v[116:119]
	v_mfma_f32_16x16x32_bf16 v[112:115], v[190:193], v[198:201], v[112:115]
	v_mfma_f32_16x16x32_bf16 v[100:103], v[182:185], v[206:209], v[100:103]
	v_mfma_f32_16x16x32_bf16 v[96:99], v[190:193], v[206:209], v[96:99]
	v_mfma_f32_16x16x32_bf16 v[84:87], v[182:185], v[214:217], v[84:87]
	v_mfma_f32_16x16x32_bf16 v[80:83], v[190:193], v[214:217], v[80:83]
	v_mfma_f32_16x16x32_bf16 v[68:71], v[182:185], v[222:225], v[68:71]
	v_mfma_f32_16x16x32_bf16 v[64:67], v[190:193], v[222:225], v[64:67]
	s_barrier
	s_add_i32 s69, s57, s40
	v_lshl_add_u64 v[144:145], s[36:37], 0, v[130:131]
	s_mov_b32 m0, s69
	ds_read_b128 v[194:197], v159 offset:16384
	ds_read_b128 v[198:201], v159 offset:17408
	ds_read_b128 v[202:205], v159 offset:18432
	ds_read_b128 v[206:209], v159 offset:19456
	ds_read_b128 v[210:213], v159 offset:20480
	ds_read_b128 v[214:217], v159 offset:21504
	ds_read_b128 v[218:221], v159 offset:22528
	ds_read_b128 v[222:225], v159 offset:23552
	global_load_lds_dwordx4 v[144:145], off
	s_add_i32 m0, s69, 0x2000
	s_add_u32 s70, s36, 0x100000
	v_lshl_add_u64 v[150:151], s[36:37], 0, v[134:135]
	s_addc_u32 s71, s37, 0
	s_add_i32 s69, s58, s40
	global_load_lds_dwordx4 v[150:151], off
	v_lshl_add_u64 v[156:157], s[70:71], 0, v[130:131]
	s_mov_b32 m0, s69
	v_lshl_add_u64 v[226:227], s[38:39], 0, v[132:133]
	global_load_lds_dwordx4 v[156:157], off
	v_lshl_add_u64 v[156:157], s[70:71], 0, v[134:135]
	s_add_i32 m0, s69, 0x2000
	s_nop 0
	global_load_lds_dwordx4 v[156:157], off
	v_lshl_add_u64 v[156:157], s[38:39], 0, v[128:129]
	s_mov_b32 m0, s31
	s_nop 0
	global_load_lds_dwordx4 v[156:157], off
	s_mov_b32 m0, s50
	s_nop 0
	global_load_lds_dwordx4 v[226:227], off
	s_waitcnt vmcnt(8)
	s_waitcnt lgkmcnt(0)
	s_barrier
	s_waitcnt lgkmcnt(0)
	v_mfma_f32_16x16x32_bf16 v[60:63], v[162:165], v[194:197], v[60:63]
	v_mfma_f32_16x16x32_bf16 v[56:59], v[170:173], v[194:197], v[56:59]
	v_mfma_f32_16x16x32_bf16 v[48:51], v[162:165], v[202:205], v[48:51]
	v_mfma_f32_16x16x32_bf16 v[40:43], v[170:173], v[202:205], v[40:43]
	v_mfma_f32_16x16x32_bf16 v[32:35], v[162:165], v[210:213], v[32:35]
	v_mfma_f32_16x16x32_bf16 v[24:27], v[170:173], v[210:213], v[24:27]
	v_mfma_f32_16x16x32_bf16 v[16:19], v[162:165], v[218:221], v[16:19]
	v_mfma_f32_16x16x32_bf16 v[8:11], v[170:173], v[218:221], v[8:11]
	v_mfma_f32_16x16x32_bf16 v[60:63], v[166:169], v[198:201], v[60:63]
	v_mfma_f32_16x16x32_bf16 v[56:59], v[174:177], v[198:201], v[56:59]
	v_mfma_f32_16x16x32_bf16 v[48:51], v[166:169], v[206:209], v[48:51]
	v_mfma_f32_16x16x32_bf16 v[40:43], v[174:177], v[206:209], v[40:43]
	v_mfma_f32_16x16x32_bf16 v[32:35], v[166:169], v[214:217], v[32:35]
	v_mfma_f32_16x16x32_bf16 v[24:27], v[174:177], v[214:217], v[24:27]
	v_mfma_f32_16x16x32_bf16 v[16:19], v[166:169], v[222:225], v[16:19]
	v_mfma_f32_16x16x32_bf16 v[8:11], v[174:177], v[222:225], v[8:11]
	v_mfma_f32_16x16x32_bf16 v[52:55], v[178:181], v[194:197], v[52:55]
	v_mfma_f32_16x16x32_bf16 v[44:47], v[186:189], v[194:197], v[44:47]
	v_mfma_f32_16x16x32_bf16 v[36:39], v[178:181], v[202:205], v[36:39]
	v_mfma_f32_16x16x32_bf16 v[28:31], v[186:189], v[202:205], v[28:31]
	v_mfma_f32_16x16x32_bf16 v[20:23], v[178:181], v[210:213], v[20:23]
	v_mfma_f32_16x16x32_bf16 v[12:15], v[186:189], v[210:213], v[12:15]
	v_mfma_f32_16x16x32_bf16 v[4:7], v[178:181], v[218:221], v[4:7]
	v_mfma_f32_16x16x32_bf16 v[0:3], v[186:189], v[218:221], v[0:3]
	v_mfma_f32_16x16x32_bf16 v[52:55], v[182:185], v[198:201], v[52:55]
	v_mfma_f32_16x16x32_bf16 v[44:47], v[190:193], v[198:201], v[44:47]
	v_mfma_f32_16x16x32_bf16 v[36:39], v[182:185], v[206:209], v[36:39]
	v_mfma_f32_16x16x32_bf16 v[28:31], v[190:193], v[206:209], v[28:31]
	v_mfma_f32_16x16x32_bf16 v[20:23], v[182:185], v[214:217], v[20:23]
	v_mfma_f32_16x16x32_bf16 v[12:15], v[190:193], v[214:217], v[12:15]
	v_mfma_f32_16x16x32_bf16 v[4:7], v[182:185], v[222:225], v[4:7]
	v_mfma_f32_16x16x32_bf16 v[0:3], v[190:193], v[222:225], v[0:3]
	s_barrier
	s_add_i32 s69, 0, 0x18000
	v_add_u32_e32 v146, s69, v149
	s_add_i32 s70, 0, 0x1c000
	ds_read_b128 v[162:165], v146
	ds_read_b128 v[166:169], v146 offset:1024
	ds_read_b128 v[170:173], v146 offset:2048
	ds_read_b128 v[174:177], v146 offset:3072
	v_add_u32_e32 v146, s70, v149
	ds_read_b128 v[178:181], v146
	ds_read_b128 v[182:185], v146 offset:1024
	ds_read_b128 v[186:189], v146 offset:2048
	ds_read_b128 v[190:193], v146 offset:3072
	s_add_u32 s38, s38, 0x100000
	s_addc_u32 s39, s39, 0
	s_mov_b32 m0, s51
	v_lshl_add_u64 v[228:229], s[38:39], 0, v[128:129]
	ds_read_b128 v[194:197], v159 offset:32768
	ds_read_b128 v[198:201], v159 offset:33792
	ds_read_b128 v[202:205], v159 offset:34816
	ds_read_b128 v[206:209], v159 offset:35840
	ds_read_b128 v[210:213], v159 offset:36864
	ds_read_b128 v[214:217], v159 offset:37888
	ds_read_b128 v[218:221], v159 offset:38912
	ds_read_b128 v[222:225], v159 offset:39936
	global_load_lds_dwordx4 v[228:229], off
	v_lshl_add_u64 v[228:229], s[38:39], 0, v[132:133]
	s_mov_b32 m0, s52
	s_nop 0
	global_load_lds_dwordx4 v[228:229], off
	s_waitcnt vmcnt(8)
	s_waitcnt lgkmcnt(0)
	s_barrier
	s_waitcnt lgkmcnt(0)
	v_mfma_f32_16x16x32_bf16 v[124:127], v[162:165], v[194:197], v[124:127]
	v_mfma_f32_16x16x32_bf16 v[120:123], v[170:173], v[194:197], v[120:123]
	v_mfma_f32_16x16x32_bf16 v[108:111], v[162:165], v[202:205], v[108:111]
	v_mfma_f32_16x16x32_bf16 v[104:107], v[170:173], v[202:205], v[104:107]
	v_mfma_f32_16x16x32_bf16 v[92:95], v[162:165], v[210:213], v[92:95]
	v_mfma_f32_16x16x32_bf16 v[88:91], v[170:173], v[210:213], v[88:91]
	v_mfma_f32_16x16x32_bf16 v[76:79], v[162:165], v[218:221], v[76:79]
	v_mfma_f32_16x16x32_bf16 v[72:75], v[170:173], v[218:221], v[72:75]
	v_mfma_f32_16x16x32_bf16 v[124:127], v[166:169], v[198:201], v[124:127]
	v_mfma_f32_16x16x32_bf16 v[120:123], v[174:177], v[198:201], v[120:123]
	v_mfma_f32_16x16x32_bf16 v[108:111], v[166:169], v[206:209], v[108:111]
	v_mfma_f32_16x16x32_bf16 v[104:107], v[174:177], v[206:209], v[104:107]
	v_mfma_f32_16x16x32_bf16 v[92:95], v[166:169], v[214:217], v[92:95]
	v_mfma_f32_16x16x32_bf16 v[88:91], v[174:177], v[214:217], v[88:91]
	v_mfma_f32_16x16x32_bf16 v[76:79], v[166:169], v[222:225], v[76:79]
	v_mfma_f32_16x16x32_bf16 v[72:75], v[174:177], v[222:225], v[72:75]
	v_mfma_f32_16x16x32_bf16 v[116:119], v[178:181], v[194:197], v[116:119]
	v_mfma_f32_16x16x32_bf16 v[112:115], v[186:189], v[194:197], v[112:115]
	v_mfma_f32_16x16x32_bf16 v[100:103], v[178:181], v[202:205], v[100:103]
	v_mfma_f32_16x16x32_bf16 v[96:99], v[186:189], v[202:205], v[96:99]
	v_mfma_f32_16x16x32_bf16 v[84:87], v[178:181], v[210:213], v[84:87]
	v_mfma_f32_16x16x32_bf16 v[80:83], v[186:189], v[210:213], v[80:83]
	v_mfma_f32_16x16x32_bf16 v[68:71], v[178:181], v[218:221], v[68:71]
	v_mfma_f32_16x16x32_bf16 v[64:67], v[186:189], v[218:221], v[64:67]
	v_mfma_f32_16x16x32_bf16 v[116:119], v[182:185], v[198:201], v[116:119]
	v_mfma_f32_16x16x32_bf16 v[112:115], v[190:193], v[198:201], v[112:115]
	v_mfma_f32_16x16x32_bf16 v[100:103], v[182:185], v[206:209], v[100:103]
	v_mfma_f32_16x16x32_bf16 v[96:99], v[190:193], v[206:209], v[96:99]
	v_mfma_f32_16x16x32_bf16 v[84:87], v[182:185], v[214:217], v[84:87]
	v_mfma_f32_16x16x32_bf16 v[80:83], v[190:193], v[214:217], v[80:83]
	v_mfma_f32_16x16x32_bf16 v[68:71], v[182:185], v[222:225], v[68:71]
	v_mfma_f32_16x16x32_bf16 v[64:67], v[190:193], v[222:225], v[64:67]
	s_barrier
	s_add_i32 s38, s69, s40
	v_lshl_add_u64 v[144:145], v[144:145], 0, s[12:13]
	s_mov_b32 m0, s38
	ds_read_b128 v[194:197], v159 offset:49152
	ds_read_b128 v[198:201], v159 offset:50176
	ds_read_b128 v[202:205], v159 offset:51200
	ds_read_b128 v[206:209], v159 offset:52224
	ds_read_b128 v[210:213], v159 offset:53248
	ds_read_b128 v[214:217], v159 offset:54272
	ds_read_b128 v[218:221], v159 offset:55296
	ds_read_b128 v[222:225], v159 offset:56320
	global_load_lds_dwordx4 v[144:145], off
	s_add_i32 m0, s38, 0x2000
	s_add_u32 s36, s36, 0x100080
	v_lshl_add_u64 v[144:145], v[150:151], 0, s[12:13]
	s_addc_u32 s37, s37, 0
	s_add_i32 s38, s70, s40
	global_load_lds_dwordx4 v[144:145], off
	v_lshl_add_u64 v[144:145], s[36:37], 0, v[130:131]
	s_mov_b32 m0, s38
	s_nop 0
	global_load_lds_dwordx4 v[144:145], off
	v_lshl_add_u64 v[144:145], s[36:37], 0, v[134:135]
	s_add_i32 m0, s38, 0x2000
	s_nop 0
	global_load_lds_dwordx4 v[144:145], off
	v_lshl_add_u64 v[144:145], v[156:157], 0, s[12:13]
	s_mov_b32 m0, s54
	s_nop 0
	global_load_lds_dwordx4 v[144:145], off
	v_lshl_add_u64 v[144:145], v[226:227], 0, s[12:13]
	s_mov_b32 m0, s55
	s_nop 0
	global_load_lds_dwordx4 v[144:145], off
	s_waitcnt vmcnt(8)
	s_waitcnt lgkmcnt(0)
	s_barrier
	s_waitcnt lgkmcnt(0)
	v_mfma_f32_16x16x32_bf16 v[60:63], v[162:165], v[194:197], v[60:63]
	v_mfma_f32_16x16x32_bf16 v[56:59], v[170:173], v[194:197], v[56:59]
	v_mfma_f32_16x16x32_bf16 v[48:51], v[162:165], v[202:205], v[48:51]
	v_mfma_f32_16x16x32_bf16 v[40:43], v[170:173], v[202:205], v[40:43]
	v_mfma_f32_16x16x32_bf16 v[32:35], v[162:165], v[210:213], v[32:35]
	v_mfma_f32_16x16x32_bf16 v[24:27], v[170:173], v[210:213], v[24:27]
	v_mfma_f32_16x16x32_bf16 v[16:19], v[162:165], v[218:221], v[16:19]
	v_mfma_f32_16x16x32_bf16 v[8:11], v[170:173], v[218:221], v[8:11]
	v_mfma_f32_16x16x32_bf16 v[60:63], v[166:169], v[198:201], v[60:63]
	v_mfma_f32_16x16x32_bf16 v[56:59], v[174:177], v[198:201], v[56:59]
	v_mfma_f32_16x16x32_bf16 v[48:51], v[166:169], v[206:209], v[48:51]
	v_mfma_f32_16x16x32_bf16 v[40:43], v[174:177], v[206:209], v[40:43]
	v_mfma_f32_16x16x32_bf16 v[32:35], v[166:169], v[214:217], v[32:35]
	v_mfma_f32_16x16x32_bf16 v[24:27], v[174:177], v[214:217], v[24:27]
	v_mfma_f32_16x16x32_bf16 v[16:19], v[166:169], v[222:225], v[16:19]
	v_mfma_f32_16x16x32_bf16 v[8:11], v[174:177], v[222:225], v[8:11]
	v_mfma_f32_16x16x32_bf16 v[52:55], v[178:181], v[194:197], v[52:55]
	v_mfma_f32_16x16x32_bf16 v[44:47], v[186:189], v[194:197], v[44:47]
	v_mfma_f32_16x16x32_bf16 v[36:39], v[178:181], v[202:205], v[36:39]
	v_mfma_f32_16x16x32_bf16 v[28:31], v[186:189], v[202:205], v[28:31]
	v_mfma_f32_16x16x32_bf16 v[20:23], v[178:181], v[210:213], v[20:23]
	v_mfma_f32_16x16x32_bf16 v[12:15], v[186:189], v[210:213], v[12:15]
	v_mfma_f32_16x16x32_bf16 v[4:7], v[178:181], v[218:221], v[4:7]
	v_mfma_f32_16x16x32_bf16 v[0:3], v[186:189], v[218:221], v[0:3]
	v_mfma_f32_16x16x32_bf16 v[52:55], v[182:185], v[198:201], v[52:55]
	v_mfma_f32_16x16x32_bf16 v[44:47], v[190:193], v[198:201], v[44:47]
	v_mfma_f32_16x16x32_bf16 v[36:39], v[182:185], v[206:209], v[36:39]
	v_mfma_f32_16x16x32_bf16 v[28:31], v[190:193], v[206:209], v[28:31]
	v_mfma_f32_16x16x32_bf16 v[20:23], v[182:185], v[214:217], v[20:23]
	v_mfma_f32_16x16x32_bf16 v[12:15], v[190:193], v[214:217], v[12:15]
	v_mfma_f32_16x16x32_bf16 v[4:7], v[182:185], v[222:225], v[4:7]
	v_mfma_f32_16x16x32_bf16 v[0:3], v[190:193], v[222:225], v[0:3]
	s_barrier
	s_add_i32 s68, s68, 2
	s_add_u32 s66, s66, 0x100
	s_addc_u32 s67, s67, 0
	s_add_u32 s34, s34, 0x100
	s_addc_u32 s35, s35, 0
	s_cmp_gt_u32 s68, 61
	s_cbranch_scc0 .LBB0_233
	s_setprio 0
	s_and_b64 vcc, exec, s[14:15]
	s_cbranch_vccz .LBB0_236
	s_barrier

.LBB0_253:
	s_add_u32 s65, s26, 0x100
	v_mov_b32_e32 v0, 0
	s_addc_u32 s66, s27, 0
	s_mov_b32 s67, -2
	v_mov_b32_e32 v1, v0
	v_mov_b32_e32 v2, v0
	v_mov_b32_e32 v3, v0
	v_mov_b32_e32 v4, v0
	v_mov_b32_e32 v5, v0
	v_mov_b32_e32 v6, v0
	v_mov_b32_e32 v7, v0
	v_mov_b32_e32 v8, v0
	v_mov_b32_e32 v9, v0
	v_mov_b32_e32 v10, v0
	v_mov_b32_e32 v11, v0
	v_mov_b32_e32 v16, v0
	v_mov_b32_e32 v17, v0
	v_mov_b32_e32 v18, v0
	v_mov_b32_e32 v19, v0
	v_mov_b32_e32 v24, v0
	v_mov_b32_e32 v25, v0
	v_mov_b32_e32 v26, v0
	v_mov_b32_e32 v27, v0
	v_mov_b32_e32 v32, v0
	v_mov_b32_e32 v33, v0
	v_mov_b32_e32 v34, v0
	v_mov_b32_e32 v35, v0
	v_mov_b32_e32 v40, v0
	v_mov_b32_e32 v41, v0
	v_mov_b32_e32 v42, v0
	v_mov_b32_e32 v43, v0
	v_mov_b32_e32 v48, v0
	v_mov_b32_e32 v49, v0
	v_mov_b32_e32 v50, v0
	v_mov_b32_e32 v51, v0
	v_mov_b32_e32 v12, v0
	v_mov_b32_e32 v13, v0
	v_mov_b32_e32 v14, v0
	v_mov_b32_e32 v15, v0
	v_mov_b32_e32 v20, v0
	v_mov_b32_e32 v21, v0
	v_mov_b32_e32 v22, v0
	v_mov_b32_e32 v23, v0
	v_mov_b32_e32 v28, v0
	v_mov_b32_e32 v29, v0
	v_mov_b32_e32 v30, v0
	v_mov_b32_e32 v31, v0
	v_mov_b32_e32 v36, v0
	v_mov_b32_e32 v37, v0
	v_mov_b32_e32 v38, v0
	v_mov_b32_e32 v39, v0
	v_mov_b32_e32 v44, v0
	v_mov_b32_e32 v45, v0
	v_mov_b32_e32 v46, v0
	v_mov_b32_e32 v47, v0
	v_mov_b32_e32 v52, v0
	v_mov_b32_e32 v53, v0
	v_mov_b32_e32 v54, v0
	v_mov_b32_e32 v55, v0
	v_mov_b32_e32 v56, v0
	v_mov_b32_e32 v57, v0
	v_mov_b32_e32 v58, v0
	v_mov_b32_e32 v59, v0
	v_mov_b32_e32 v60, v0
	v_mov_b32_e32 v61, v0
	v_mov_b32_e32 v62, v0
	v_mov_b32_e32 v63, v0
	v_mov_b32_e32 v64, v0
	v_mov_b32_e32 v65, v0
	v_mov_b32_e32 v66, v0
	v_mov_b32_e32 v67, v0
	v_mov_b32_e32 v68, v0
	v_mov_b32_e32 v69, v0
	v_mov_b32_e32 v70, v0
	v_mov_b32_e32 v71, v0
	v_mov_b32_e32 v72, v0
	v_mov_b32_e32 v73, v0
	v_mov_b32_e32 v74, v0
	v_mov_b32_e32 v75, v0
	v_mov_b32_e32 v80, v0
	v_mov_b32_e32 v81, v0
	v_mov_b32_e32 v82, v0
	v_mov_b32_e32 v83, v0
	v_mov_b32_e32 v88, v0
	v_mov_b32_e32 v89, v0
	v_mov_b32_e32 v90, v0
	v_mov_b32_e32 v91, v0
	v_mov_b32_e32 v96, v0
	v_mov_b32_e32 v97, v0
	v_mov_b32_e32 v98, v0
	v_mov_b32_e32 v99, v0
	v_mov_b32_e32 v104, v0
	v_mov_b32_e32 v105, v0
	v_mov_b32_e32 v106, v0
	v_mov_b32_e32 v107, v0
	v_mov_b32_e32 v112, v0
	v_mov_b32_e32 v113, v0
	v_mov_b32_e32 v114, v0
	v_mov_b32_e32 v115, v0
	v_mov_b32_e32 v76, v0
	v_mov_b32_e32 v77, v0
	v_mov_b32_e32 v78, v0
	v_mov_b32_e32 v79, v0
	v_mov_b32_e32 v84, v0
	v_mov_b32_e32 v85, v0
	v_mov_b32_e32 v86, v0
	v_mov_b32_e32 v87, v0
	v_mov_b32_e32 v92, v0
	v_mov_b32_e32 v93, v0
	v_mov_b32_e32 v94, v0
	v_mov_b32_e32 v95, v0
	v_mov_b32_e32 v100, v0
	v_mov_b32_e32 v101, v0
	v_mov_b32_e32 v102, v0
	v_mov_b32_e32 v103, v0
	v_mov_b32_e32 v108, v0
	v_mov_b32_e32 v109, v0
	v_mov_b32_e32 v110, v0
	v_mov_b32_e32 v111, v0
	v_mov_b32_e32 v116, v0
	v_mov_b32_e32 v117, v0
	v_mov_b32_e32 v118, v0
	v_mov_b32_e32 v119, v0
	v_mov_b32_e32 v120, v0
	v_mov_b32_e32 v121, v0
	v_mov_b32_e32 v122, v0
	v_mov_b32_e32 v123, v0
	v_mov_b32_e32 v124, v0
	v_mov_b32_e32 v125, v0
	v_mov_b32_e32 v126, v0
	v_mov_b32_e32 v127, v0
	s_cmp_ge_u32 s81, 4
	s_cbranch_scc0 .Lsp_skip1
	s_setprio 1
.Lsp_skip1:
.LBB0_254:
	ds_read_b128 v[152:155], v149
	ds_read_b128 v[156:159], v149 offset:1024
	ds_read_b128 v[160:163], v149 offset:2048
	ds_read_b128 v[164:167], v149 offset:3072
	ds_read_b128 v[168:171], v150
	ds_read_b128 v[172:175], v150 offset:1024
	ds_read_b128 v[176:179], v150 offset:2048
	ds_read_b128 v[180:183], v150 offset:3072
	s_add_u32 s26, s24, 0x100
	s_addc_u32 s27, s25, 0
	s_cmp_eq_u32 s67, 8
	s_cselect_b32 s31, s1, s27
	s_cselect_b32 s30, s0, s26
	s_cselect_b32 s29, s23, s66
	s_cselect_b32 s28, s22, s65
	v_lshl_add_u64 v[144:145], s[24:25], 0, v[138:139]
	s_add_i32 m0, s46, 0xc000
	ds_read_b128 v[184:187], v151
	ds_read_b128 v[188:191], v151 offset:1024
	ds_read_b128 v[192:195], v151 offset:2048
	ds_read_b128 v[196:199], v151 offset:3072
	ds_read_b128 v[200:203], v151 offset:4096
	ds_read_b128 v[204:207], v151 offset:5120
	ds_read_b128 v[208:211], v151 offset:6144
	ds_read_b128 v[212:215], v151 offset:7168
	global_load_lds_dwordx4 v[144:145], off
	v_lshl_add_u64 v[144:145], s[24:25], 0, v[136:137]
	s_add_i32 m0, s46, 0xe000
	s_nop 0
	global_load_lds_dwordx4 v[144:145], off
	s_waitcnt vmcnt(8)
	s_waitcnt lgkmcnt(0)
	s_barrier
	s_waitcnt lgkmcnt(0)
	v_mfma_f32_16x16x32_bf16 v[124:127], v[152:155], v[184:187], v[124:127]
	v_mfma_f32_16x16x32_bf16 v[120:123], v[160:163], v[184:187], v[120:123]
	v_mfma_f32_16x16x32_bf16 v[116:119], v[152:155], v[192:195], v[116:119]
	v_mfma_f32_16x16x32_bf16 v[108:111], v[160:163], v[192:195], v[108:111]
	v_mfma_f32_16x16x32_bf16 v[100:103], v[152:155], v[200:203], v[100:103]
	v_mfma_f32_16x16x32_bf16 v[92:95], v[160:163], v[200:203], v[92:95]
	v_mfma_f32_16x16x32_bf16 v[84:87], v[152:155], v[208:211], v[84:87]
	v_mfma_f32_16x16x32_bf16 v[76:79], v[160:163], v[208:211], v[76:79]
	v_mfma_f32_16x16x32_bf16 v[124:127], v[156:159], v[188:191], v[124:127]
	v_mfma_f32_16x16x32_bf16 v[120:123], v[164:167], v[188:191], v[120:123]
	v_mfma_f32_16x16x32_bf16 v[116:119], v[156:159], v[196:199], v[116:119]
	v_mfma_f32_16x16x32_bf16 v[108:111], v[164:167], v[196:199], v[108:111]
	v_mfma_f32_16x16x32_bf16 v[100:103], v[156:159], v[204:207], v[100:103]
	v_mfma_f32_16x16x32_bf16 v[92:95], v[164:167], v[204:207], v[92:95]
	v_mfma_f32_16x16x32_bf16 v[84:87], v[156:159], v[212:215], v[84:87]
	v_mfma_f32_16x16x32_bf16 v[76:79], v[164:167], v[212:215], v[76:79]
	v_mfma_f32_16x16x32_bf16 v[112:115], v[168:171], v[184:187], v[112:115]
	v_mfma_f32_16x16x32_bf16 v[104:107], v[176:179], v[184:187], v[104:107]
	v_mfma_f32_16x16x32_bf16 v[96:99], v[168:171], v[192:195], v[96:99]
	v_mfma_f32_16x16x32_bf16 v[88:91], v[176:179], v[192:195], v[88:91]
	v_mfma_f32_16x16x32_bf16 v[80:83], v[168:171], v[200:203], v[80:83]
	v_mfma_f32_16x16x32_bf16 v[72:75], v[176:179], v[200:203], v[72:75]
	v_mfma_f32_16x16x32_bf16 v[68:71], v[168:171], v[208:211], v[68:71]
	v_mfma_f32_16x16x32_bf16 v[64:67], v[176:179], v[208:211], v[64:67]
	v_mfma_f32_16x16x32_bf16 v[112:115], v[172:175], v[188:191], v[112:115]
	v_mfma_f32_16x16x32_bf16 v[104:107], v[180:183], v[188:191], v[104:107]
	v_mfma_f32_16x16x32_bf16 v[96:99], v[172:175], v[196:199], v[96:99]
	v_mfma_f32_16x16x32_bf16 v[88:91], v[180:183], v[196:199], v[88:91]
	v_mfma_f32_16x16x32_bf16 v[80:83], v[172:175], v[204:207], v[80:83]
	v_mfma_f32_16x16x32_bf16 v[72:75], v[180:183], v[204:207], v[72:75]
	v_mfma_f32_16x16x32_bf16 v[68:71], v[172:175], v[212:215], v[68:71]
	v_mfma_f32_16x16x32_bf16 v[64:67], v[180:183], v[212:215], v[64:67]
	s_barrier
	s_add_i32 s24, s55, s40
	v_lshl_add_u64 v[144:145], s[28:29], 0, v[132:133]
	s_mov_b32 m0, s24
	ds_read_b128 v[184:187], v151 offset:16384
	ds_read_b128 v[188:191], v151 offset:17408
	ds_read_b128 v[192:195], v151 offset:18432
	ds_read_b128 v[196:199], v151 offset:19456
	ds_read_b128 v[200:203], v151 offset:20480
	ds_read_b128 v[204:207], v151 offset:21504
	ds_read_b128 v[208:211], v151 offset:22528
	ds_read_b128 v[212:215], v151 offset:23552
	global_load_lds_dwordx4 v[144:145], off
	s_add_i32 m0, s24, 0x2000
	s_add_u32 s24, s28, 0x30000
	v_lshl_add_u64 v[216:217], s[28:29], 0, v[128:129]
	s_addc_u32 s25, s29, 0
	s_add_i32 s68, s56, s40
	global_load_lds_dwordx4 v[216:217], off
	v_lshl_add_u64 v[218:219], s[24:25], 0, v[132:133]
	s_mov_b32 m0, s68
	v_lshl_add_u64 v[220:221], s[30:31], 0, v[130:131]
	global_load_lds_dwordx4 v[218:219], off
	v_lshl_add_u64 v[218:219], s[24:25], 0, v[128:129]
	s_add_i32 m0, s68, 0x2000
	s_nop 0
	global_load_lds_dwordx4 v[218:219], off
	v_lshl_add_u64 v[218:219], s[30:31], 0, v[134:135]
	s_mov_b32 m0, s46
	s_nop 0
	global_load_lds_dwordx4 v[218:219], off
	s_mov_b32 m0, s47
	s_nop 0
	global_load_lds_dwordx4 v[220:221], off
	s_waitcnt vmcnt(8)
	s_waitcnt lgkmcnt(0)
	s_barrier
	s_waitcnt lgkmcnt(0)
	v_mfma_f32_16x16x32_bf16 v[60:63], v[152:155], v[184:187], v[60:63]
	v_mfma_f32_16x16x32_bf16 v[56:59], v[160:163], v[184:187], v[56:59]
	v_mfma_f32_16x16x32_bf16 v[52:55], v[152:155], v[192:195], v[52:55]
	v_mfma_f32_16x16x32_bf16 v[44:47], v[160:163], v[192:195], v[44:47]
	v_mfma_f32_16x16x32_bf16 v[36:39], v[152:155], v[200:203], v[36:39]
	v_mfma_f32_16x16x32_bf16 v[28:31], v[160:163], v[200:203], v[28:31]
	v_mfma_f32_16x16x32_bf16 v[20:23], v[152:155], v[208:211], v[20:23]
	v_mfma_f32_16x16x32_bf16 v[12:15], v[160:163], v[208:211], v[12:15]
	v_mfma_f32_16x16x32_bf16 v[60:63], v[156:159], v[188:191], v[60:63]
	v_mfma_f32_16x16x32_bf16 v[56:59], v[164:167], v[188:191], v[56:59]
	v_mfma_f32_16x16x32_bf16 v[52:55], v[156:159], v[196:199], v[52:55]
	v_mfma_f32_16x16x32_bf16 v[44:47], v[164:167], v[196:199], v[44:47]
	v_mfma_f32_16x16x32_bf16 v[36:39], v[156:159], v[204:207], v[36:39]
	v_mfma_f32_16x16x32_bf16 v[28:31], v[164:167], v[204:207], v[28:31]
	v_mfma_f32_16x16x32_bf16 v[20:23], v[156:159], v[212:215], v[20:23]
	v_mfma_f32_16x16x32_bf16 v[12:15], v[164:167], v[212:215], v[12:15]
	v_mfma_f32_16x16x32_bf16 v[48:51], v[168:171], v[184:187], v[48:51]
	v_mfma_f32_16x16x32_bf16 v[40:43], v[176:179], v[184:187], v[40:43]
	v_mfma_f32_16x16x32_bf16 v[32:35], v[168:171], v[192:195], v[32:35]
	v_mfma_f32_16x16x32_bf16 v[24:27], v[176:179], v[192:195], v[24:27]
	v_mfma_f32_16x16x32_bf16 v[16:19], v[168:171], v[200:203], v[16:19]
	v_mfma_f32_16x16x32_bf16 v[8:11], v[176:179], v[200:203], v[8:11]
	v_mfma_f32_16x16x32_bf16 v[4:7], v[168:171], v[208:211], v[4:7]
	v_mfma_f32_16x16x32_bf16 v[0:3], v[176:179], v[208:211], v[0:3]
	v_mfma_f32_16x16x32_bf16 v[48:51], v[172:175], v[188:191], v[48:51]
	v_mfma_f32_16x16x32_bf16 v[40:43], v[180:183], v[188:191], v[40:43]
	v_mfma_f32_16x16x32_bf16 v[32:35], v[172:175], v[196:199], v[32:35]
	v_mfma_f32_16x16x32_bf16 v[24:27], v[180:183], v[196:199], v[24:27]
	v_mfma_f32_16x16x32_bf16 v[16:19], v[172:175], v[204:207], v[16:19]
	v_mfma_f32_16x16x32_bf16 v[8:11], v[180:183], v[204:207], v[8:11]
	v_mfma_f32_16x16x32_bf16 v[4:7], v[172:175], v[212:215], v[4:7]
	v_mfma_f32_16x16x32_bf16 v[0:3], v[180:183], v[212:215], v[0:3]
	s_barrier
	s_add_i32 s68, 0, 0x18000
	s_add_i32 s69, 0, 0x1c000
	v_add_u32_e32 v164, s68, v147
	v_add_u32_e32 v180, s69, v147
	ds_read_b128 v[152:155], v164
	ds_read_b128 v[156:159], v164 offset:1024
	ds_read_b128 v[160:163], v164 offset:2048
	ds_read_b128 v[164:167], v164 offset:3072
	ds_read_b128 v[168:171], v180
	ds_read_b128 v[172:175], v180 offset:1024
	ds_read_b128 v[176:179], v180 offset:2048
	ds_read_b128 v[180:183], v180 offset:3072
	s_add_u32 s24, s30, 0xc0000
	s_addc_u32 s25, s31, 0
	s_mov_b32 m0, s48
	v_lshl_add_u64 v[222:223], s[24:25], 0, v[134:135]
	ds_read_b128 v[184:187], v151 offset:32768
	ds_read_b128 v[188:191], v151 offset:33792
	ds_read_b128 v[192:195], v151 offset:34816
	ds_read_b128 v[196:199], v151 offset:35840
	ds_read_b128 v[200:203], v151 offset:36864
	ds_read_b128 v[204:207], v151 offset:37888
	ds_read_b128 v[208:211], v151 offset:38912
	ds_read_b128 v[212:215], v151 offset:39936
	global_load_lds_dwordx4 v[222:223], off
	v_lshl_add_u64 v[222:223], s[24:25], 0, v[130:131]
	s_mov_b32 m0, s49
	s_nop 0
	global_load_lds_dwordx4 v[222:223], off
	s_waitcnt vmcnt(8)
	s_waitcnt lgkmcnt(0)
	s_barrier
	s_waitcnt lgkmcnt(0)
	v_mfma_f32_16x16x32_bf16 v[124:127], v[152:155], v[184:187], v[124:127]
	v_mfma_f32_16x16x32_bf16 v[120:123], v[160:163], v[184:187], v[120:123]
	v_mfma_f32_16x16x32_bf16 v[116:119], v[152:155], v[192:195], v[116:119]
	v_mfma_f32_16x16x32_bf16 v[108:111], v[160:163], v[192:195], v[108:111]
	v_mfma_f32_16x16x32_bf16 v[100:103], v[152:155], v[200:203], v[100:103]
	v_mfma_f32_16x16x32_bf16 v[92:95], v[160:163], v[200:203], v[92:95]
	v_mfma_f32_16x16x32_bf16 v[84:87], v[152:155], v[208:211], v[84:87]
	v_mfma_f32_16x16x32_bf16 v[76:79], v[160:163], v[208:211], v[76:79]
	v_mfma_f32_16x16x32_bf16 v[124:127], v[156:159], v[188:191], v[124:127]
	v_mfma_f32_16x16x32_bf16 v[120:123], v[164:167], v[188:191], v[120:123]
	v_mfma_f32_16x16x32_bf16 v[116:119], v[156:159], v[196:199], v[116:119]
	v_mfma_f32_16x16x32_bf16 v[108:111], v[164:167], v[196:199], v[108:111]
	v_mfma_f32_16x16x32_bf16 v[100:103], v[156:159], v[204:207], v[100:103]
	v_mfma_f32_16x16x32_bf16 v[92:95], v[164:167], v[204:207], v[92:95]
	v_mfma_f32_16x16x32_bf16 v[84:87], v[156:159], v[212:215], v[84:87]
	v_mfma_f32_16x16x32_bf16 v[76:79], v[164:167], v[212:215], v[76:79]
	v_mfma_f32_16x16x32_bf16 v[112:115], v[168:171], v[184:187], v[112:115]
	v_mfma_f32_16x16x32_bf16 v[104:107], v[176:179], v[184:187], v[104:107]
	v_mfma_f32_16x16x32_bf16 v[96:99], v[168:171], v[192:195], v[96:99]
	v_mfma_f32_16x16x32_bf16 v[88:91], v[176:179], v[192:195], v[88:91]
	v_mfma_f32_16x16x32_bf16 v[80:83], v[168:171], v[200:203], v[80:83]
	v_mfma_f32_16x16x32_bf16 v[72:75], v[176:179], v[200:203], v[72:75]
	v_mfma_f32_16x16x32_bf16 v[68:71], v[168:171], v[208:211], v[68:71]
	v_mfma_f32_16x16x32_bf16 v[64:67], v[176:179], v[208:211], v[64:67]
	v_mfma_f32_16x16x32_bf16 v[112:115], v[172:175], v[188:191], v[112:115]
	v_mfma_f32_16x16x32_bf16 v[104:107], v[180:183], v[188:191], v[104:107]
	v_mfma_f32_16x16x32_bf16 v[96:99], v[172:175], v[196:199], v[96:99]
	v_mfma_f32_16x16x32_bf16 v[88:91], v[180:183], v[196:199], v[88:91]
	v_mfma_f32_16x16x32_bf16 v[80:83], v[172:175], v[204:207], v[80:83]
	v_mfma_f32_16x16x32_bf16 v[72:75], v[180:183], v[204:207], v[72:75]
	v_mfma_f32_16x16x32_bf16 v[68:71], v[172:175], v[212:215], v[68:71]
	v_mfma_f32_16x16x32_bf16 v[64:67], v[180:183], v[212:215], v[64:67]
	s_barrier
	s_add_i32 s24, s68, s40
	v_lshl_add_u64 v[144:145], v[144:145], 0, s[10:11]
	s_mov_b32 m0, s24
	ds_read_b128 v[184:187], v151 offset:49152
	ds_read_b128 v[188:191], v151 offset:50176
	ds_read_b128 v[192:195], v151 offset:51200
	ds_read_b128 v[196:199], v151 offset:52224
	ds_read_b128 v[200:203], v151 offset:53248
	ds_read_b128 v[204:207], v151 offset:54272
	ds_read_b128 v[208:211], v151 offset:55296
	ds_read_b128 v[212:215], v151 offset:56320
	global_load_lds_dwordx4 v[144:145], off
	s_add_i32 m0, s24, 0x2000
	s_add_u32 s24, s28, 0x30080
	v_lshl_add_u64 v[144:145], v[216:217], 0, s[10:11]
	s_addc_u32 s25, s29, 0
	s_add_i32 s28, s69, s40
	global_load_lds_dwordx4 v[144:145], off
	v_lshl_add_u64 v[144:145], s[24:25], 0, v[132:133]
	s_mov_b32 m0, s28
	s_nop 0
	global_load_lds_dwordx4 v[144:145], off
	v_lshl_add_u64 v[144:145], s[24:25], 0, v[128:129]
	s_add_i32 m0, s28, 0x2000
	s_nop 0
	global_load_lds_dwordx4 v[144:145], off
	v_lshl_add_u64 v[144:145], v[218:219], 0, s[10:11]
	s_mov_b32 m0, s52
	s_nop 0
	global_load_lds_dwordx4 v[144:145], off
	v_lshl_add_u64 v[144:145], v[220:221], 0, s[10:11]
	s_mov_b32 m0, s53
	s_nop 0
	global_load_lds_dwordx4 v[144:145], off
	s_waitcnt vmcnt(8)
	s_waitcnt lgkmcnt(0)
	s_barrier
	s_waitcnt lgkmcnt(0)
	v_mfma_f32_16x16x32_bf16 v[60:63], v[152:155], v[184:187], v[60:63]
	v_mfma_f32_16x16x32_bf16 v[56:59], v[160:163], v[184:187], v[56:59]
	v_mfma_f32_16x16x32_bf16 v[52:55], v[152:155], v[192:195], v[52:55]
	v_mfma_f32_16x16x32_bf16 v[44:47], v[160:163], v[192:195], v[44:47]
	v_mfma_f32_16x16x32_bf16 v[36:39], v[152:155], v[200:203], v[36:39]
	v_mfma_f32_16x16x32_bf16 v[28:31], v[160:163], v[200:203], v[28:31]
	v_mfma_f32_16x16x32_bf16 v[20:23], v[152:155], v[208:211], v[20:23]
	v_mfma_f32_16x16x32_bf16 v[12:15], v[160:163], v[208:211], v[12:15]
	v_mfma_f32_16x16x32_bf16 v[60:63], v[156:159], v[188:191], v[60:63]
	v_mfma_f32_16x16x32_bf16 v[56:59], v[164:167], v[188:191], v[56:59]
	v_mfma_f32_16x16x32_bf16 v[52:55], v[156:159], v[196:199], v[52:55]
	v_mfma_f32_16x16x32_bf16 v[44:47], v[164:167], v[196:199], v[44:47]
	v_mfma_f32_16x16x32_bf16 v[36:39], v[156:159], v[204:207], v[36:39]
	v_mfma_f32_16x16x32_bf16 v[28:31], v[164:167], v[204:207], v[28:31]
	v_mfma_f32_16x16x32_bf16 v[20:23], v[156:159], v[212:215], v[20:23]
	v_mfma_f32_16x16x32_bf16 v[12:15], v[164:167], v[212:215], v[12:15]
	v_mfma_f32_16x16x32_bf16 v[48:51], v[168:171], v[184:187], v[48:51]
	v_mfma_f32_16x16x32_bf16 v[40:43], v[176:179], v[184:187], v[40:43]
	v_mfma_f32_16x16x32_bf16 v[32:35], v[168:171], v[192:195], v[32:35]
	v_mfma_f32_16x16x32_bf16 v[24:27], v[176:179], v[192:195], v[24:27]
	v_mfma_f32_16x16x32_bf16 v[16:19], v[168:171], v[200:203], v[16:19]
	v_mfma_f32_16x16x32_bf16 v[8:11], v[176:179], v[200:203], v[8:11]
	v_mfma_f32_16x16x32_bf16 v[4:7], v[168:171], v[208:211], v[4:7]
	v_mfma_f32_16x16x32_bf16 v[0:3], v[176:179], v[208:211], v[0:3]
	v_mfma_f32_16x16x32_bf16 v[48:51], v[172:175], v[188:191], v[48:51]
	v_mfma_f32_16x16x32_bf16 v[40:43], v[180:183], v[188:191], v[40:43]
	v_mfma_f32_16x16x32_bf16 v[32:35], v[172:175], v[196:199], v[32:35]
	v_mfma_f32_16x16x32_bf16 v[24:27], v[180:183], v[196:199], v[24:27]
	v_mfma_f32_16x16x32_bf16 v[16:19], v[172:175], v[204:207], v[16:19]
	v_mfma_f32_16x16x32_bf16 v[8:11], v[180:183], v[204:207], v[8:11]
	v_mfma_f32_16x16x32_bf16 v[4:7], v[172:175], v[212:215], v[4:7]
	v_mfma_f32_16x16x32_bf16 v[0:3], v[180:183], v[212:215], v[0:3]
	s_barrier
	s_add_i32 s67, s67, 2
	s_add_u32 s65, s65, 0x100
	s_addc_u32 s66, s66, 0
	s_cmp_gt_u32 s67, 9
	s_mov_b64 s[24:25], s[26:27]
	s_cbranch_scc0 .LBB0_254
	s_setprio 0
	s_and_b64 vcc, exec, s[12:13]
	s_cbranch_vccz .LBB0_257
	s_barrier

.LBB0_280:
	s_ashr_i32 s23, s22, 31
	s_lshl_b64 s[24:25], s[22:23], 20
	s_add_u32 s24, s39, s24
	s_addc_u32 s25, s45, s25
	s_and_b64 s[26:27], s[2:3], exec
	s_cselect_b32 s23, s25, s35
	s_cselect_b32 s57, s24, s34
	s_ashr_i32 s21, s20, 31
	s_lshl_b64 s[26:27], s[20:21], 20
	s_add_u32 s26, s46, s26
	s_addc_u32 s27, s47, s27
	s_and_b64 s[36:37], s[2:3], exec
	s_cselect_b32 s21, s27, s31
	s_cselect_b32 s58, s26, s30
	s_add_u32 s59, s30, 0x100
	s_addc_u32 s60, s31, 0
	s_add_u32 s30, s34, 0x80080
	v_mov_b32_e32 v0, 0
	s_addc_u32 s31, s35, 0
	s_mov_b32 s61, -2
	v_mov_b32_e32 v1, v0
	v_mov_b32_e32 v2, v0
	v_mov_b32_e32 v3, v0
	v_mov_b32_e32 v4, v0
	v_mov_b32_e32 v5, v0
	v_mov_b32_e32 v6, v0
	v_mov_b32_e32 v7, v0
	v_mov_b32_e32 v16, v0
	v_mov_b32_e32 v17, v0
	v_mov_b32_e32 v18, v0
	v_mov_b32_e32 v19, v0
	v_mov_b32_e32 v20, v0
	v_mov_b32_e32 v21, v0
	v_mov_b32_e32 v22, v0
	v_mov_b32_e32 v23, v0
	v_mov_b32_e32 v32, v0
	v_mov_b32_e32 v33, v0
	v_mov_b32_e32 v34, v0
	v_mov_b32_e32 v35, v0
	v_mov_b32_e32 v36, v0
	v_mov_b32_e32 v37, v0
	v_mov_b32_e32 v38, v0
	v_mov_b32_e32 v39, v0
	v_mov_b32_e32 v48, v0
	v_mov_b32_e32 v49, v0
	v_mov_b32_e32 v50, v0
	v_mov_b32_e32 v51, v0
	v_mov_b32_e32 v52, v0
	v_mov_b32_e32 v53, v0
	v_mov_b32_e32 v54, v0
	v_mov_b32_e32 v55, v0
	v_mov_b32_e32 v8, v0
	v_mov_b32_e32 v9, v0
	v_mov_b32_e32 v10, v0
	v_mov_b32_e32 v11, v0
	v_mov_b32_e32 v12, v0
	v_mov_b32_e32 v13, v0
	v_mov_b32_e32 v14, v0
	v_mov_b32_e32 v15, v0
	v_mov_b32_e32 v24, v0
	v_mov_b32_e32 v25, v0
	v_mov_b32_e32 v26, v0
	v_mov_b32_e32 v27, v0
	v_mov_b32_e32 v28, v0
	v_mov_b32_e32 v29, v0
	v_mov_b32_e32 v30, v0
	v_mov_b32_e32 v31, v0
	v_mov_b32_e32 v40, v0
	v_mov_b32_e32 v41, v0
	v_mov_b32_e32 v42, v0
	v_mov_b32_e32 v43, v0
	v_mov_b32_e32 v44, v0
	v_mov_b32_e32 v45, v0
	v_mov_b32_e32 v46, v0
	v_mov_b32_e32 v47, v0
	v_mov_b32_e32 v56, v0
	v_mov_b32_e32 v57, v0
	v_mov_b32_e32 v58, v0
	v_mov_b32_e32 v59, v0
	v_mov_b32_e32 v60, v0
	v_mov_b32_e32 v61, v0
	v_mov_b32_e32 v62, v0
	v_mov_b32_e32 v63, v0
	v_mov_b32_e32 v64, v0
	v_mov_b32_e32 v65, v0
	v_mov_b32_e32 v66, v0
	v_mov_b32_e32 v67, v0
	v_mov_b32_e32 v68, v0
	v_mov_b32_e32 v69, v0
	v_mov_b32_e32 v70, v0
	v_mov_b32_e32 v71, v0
	v_mov_b32_e32 v80, v0
	v_mov_b32_e32 v81, v0
	v_mov_b32_e32 v82, v0
	v_mov_b32_e32 v83, v0
	v_mov_b32_e32 v84, v0
	v_mov_b32_e32 v85, v0
	v_mov_b32_e32 v86, v0
	v_mov_b32_e32 v87, v0
	v_mov_b32_e32 v96, v0
	v_mov_b32_e32 v97, v0
	v_mov_b32_e32 v98, v0
	v_mov_b32_e32 v99, v0
	v_mov_b32_e32 v100, v0
	v_mov_b32_e32 v101, v0
	v_mov_b32_e32 v102, v0
	v_mov_b32_e32 v103, v0
	v_mov_b32_e32 v112, v0
	v_mov_b32_e32 v113, v0
	v_mov_b32_e32 v114, v0
	v_mov_b32_e32 v115, v0
	v_mov_b32_e32 v116, v0
	v_mov_b32_e32 v117, v0
	v_mov_b32_e32 v118, v0
	v_mov_b32_e32 v119, v0
	v_mov_b32_e32 v72, v0
	v_mov_b32_e32 v73, v0
	v_mov_b32_e32 v74, v0
	v_mov_b32_e32 v75, v0
	v_mov_b32_e32 v76, v0
	v_mov_b32_e32 v77, v0
	v_mov_b32_e32 v78, v0
	v_mov_b32_e32 v79, v0
	v_mov_b32_e32 v88, v0
	v_mov_b32_e32 v89, v0
	v_mov_b32_e32 v90, v0
	v_mov_b32_e32 v91, v0
	v_mov_b32_e32 v92, v0
	v_mov_b32_e32 v93, v0
	v_mov_b32_e32 v94, v0
	v_mov_b32_e32 v95, v0
	v_mov_b32_e32 v104, v0
	v_mov_b32_e32 v105, v0
	v_mov_b32_e32 v106, v0
	v_mov_b32_e32 v107, v0
	v_mov_b32_e32 v108, v0
	v_mov_b32_e32 v109, v0
	v_mov_b32_e32 v110, v0
	v_mov_b32_e32 v111, v0
	v_mov_b32_e32 v120, v0
	v_mov_b32_e32 v121, v0
	v_mov_b32_e32 v122, v0
	v_mov_b32_e32 v123, v0
	v_mov_b32_e32 v124, v0
	v_mov_b32_e32 v125, v0
	v_mov_b32_e32 v126, v0
	v_mov_b32_e32 v127, v0
	s_cmp_ge_u32 s81, 4
	s_cbranch_scc0 .Lsp_skip2
	s_setprio 1
.Lsp_skip2:
.LBB0_281:
	ds_read_b128 v[144:147], v153
	ds_read_b128 v[156:159], v153 offset:1024
	ds_read_b128 v[160:163], v153 offset:2048
	ds_read_b128 v[164:167], v153 offset:3072
	ds_read_b128 v[168:171], v154
	ds_read_b128 v[172:175], v154 offset:1024
	ds_read_b128 v[176:179], v154 offset:2048
	ds_read_b128 v[180:183], v154 offset:3072
	s_add_u32 s34, s30, 0xfff80080
	s_addc_u32 s35, s31, -1
	s_cmp_eq_u32 s61, 28
	s_cselect_b32 s37, s23, s35
	s_cselect_b32 s36, s57, s34
	s_cselect_b32 s35, s21, s60
	s_cselect_b32 s34, s58, s59
	v_lshl_add_u64 v[148:149], s[30:31], 0, v[138:139]
	s_add_i32 m0, s29, 0xc000
	ds_read_b128 v[184:187], v155
	ds_read_b128 v[188:191], v155 offset:1024
	ds_read_b128 v[192:195], v155 offset:2048
	ds_read_b128 v[196:199], v155 offset:3072
	ds_read_b128 v[200:203], v155 offset:4096
	ds_read_b128 v[204:207], v155 offset:5120
	ds_read_b128 v[208:211], v155 offset:6144
	ds_read_b128 v[212:215], v155 offset:7168
	global_load_lds_dwordx4 v[148:149], off
	v_lshl_add_u64 v[148:149], s[30:31], 0, v[136:137]
	s_add_i32 m0, s29, 0xe000
	s_nop 0
	global_load_lds_dwordx4 v[148:149], off
	s_waitcnt vmcnt(8)
	s_waitcnt lgkmcnt(0)
	s_barrier
	s_waitcnt lgkmcnt(0)
	v_mfma_i32_16x16x64_i8 v[124:127], v[144:147], v[184:187], v[124:127]
	v_mfma_i32_16x16x64_i8 v[120:123], v[160:163], v[184:187], v[120:123]
	v_mfma_i32_16x16x64_i8 v[108:111], v[144:147], v[192:195], v[108:111]
	v_mfma_i32_16x16x64_i8 v[104:107], v[160:163], v[192:195], v[104:107]
	v_mfma_i32_16x16x64_i8 v[92:95], v[144:147], v[200:203], v[92:95]
	v_mfma_i32_16x16x64_i8 v[88:91], v[160:163], v[200:203], v[88:91]
	v_mfma_i32_16x16x64_i8 v[76:79], v[144:147], v[208:211], v[76:79]
	v_mfma_i32_16x16x64_i8 v[72:75], v[160:163], v[208:211], v[72:75]
	v_mfma_i32_16x16x64_i8 v[124:127], v[156:159], v[188:191], v[124:127]
	v_mfma_i32_16x16x64_i8 v[120:123], v[164:167], v[188:191], v[120:123]
	v_mfma_i32_16x16x64_i8 v[108:111], v[156:159], v[196:199], v[108:111]
	v_mfma_i32_16x16x64_i8 v[104:107], v[164:167], v[196:199], v[104:107]
	v_mfma_i32_16x16x64_i8 v[92:95], v[156:159], v[204:207], v[92:95]
	v_mfma_i32_16x16x64_i8 v[88:91], v[164:167], v[204:207], v[88:91]
	v_mfma_i32_16x16x64_i8 v[76:79], v[156:159], v[212:215], v[76:79]
	v_mfma_i32_16x16x64_i8 v[72:75], v[164:167], v[212:215], v[72:75]
	v_mfma_i32_16x16x64_i8 v[116:119], v[168:171], v[184:187], v[116:119]
	v_mfma_i32_16x16x64_i8 v[112:115], v[176:179], v[184:187], v[112:115]
	v_mfma_i32_16x16x64_i8 v[100:103], v[168:171], v[192:195], v[100:103]
	v_mfma_i32_16x16x64_i8 v[96:99], v[176:179], v[192:195], v[96:99]
	v_mfma_i32_16x16x64_i8 v[84:87], v[168:171], v[200:203], v[84:87]
	v_mfma_i32_16x16x64_i8 v[80:83], v[176:179], v[200:203], v[80:83]
	v_mfma_i32_16x16x64_i8 v[68:71], v[168:171], v[208:211], v[68:71]
	v_mfma_i32_16x16x64_i8 v[64:67], v[176:179], v[208:211], v[64:67]
	v_mfma_i32_16x16x64_i8 v[116:119], v[172:175], v[188:191], v[116:119]
	v_mfma_i32_16x16x64_i8 v[112:115], v[180:183], v[188:191], v[112:115]
	v_mfma_i32_16x16x64_i8 v[100:103], v[172:175], v[196:199], v[100:103]
	v_mfma_i32_16x16x64_i8 v[96:99], v[180:183], v[196:199], v[96:99]
	v_mfma_i32_16x16x64_i8 v[84:87], v[172:175], v[204:207], v[84:87]
	v_mfma_i32_16x16x64_i8 v[80:83], v[180:183], v[204:207], v[80:83]
	v_mfma_i32_16x16x64_i8 v[68:71], v[172:175], v[212:215], v[68:71]
	v_mfma_i32_16x16x64_i8 v[64:67], v[180:183], v[212:215], v[64:67]
	s_barrier
	s_add_i32 s62, s41, s40
	v_lshl_add_u64 v[148:149], s[34:35], 0, v[130:131]
	s_mov_b32 m0, s62
	ds_read_b128 v[184:187], v155 offset:16384
	ds_read_b128 v[188:191], v155 offset:17408
	ds_read_b128 v[192:195], v155 offset:18432
	ds_read_b128 v[196:199], v155 offset:19456
	ds_read_b128 v[200:203], v155 offset:20480
	ds_read_b128 v[204:207], v155 offset:21504
	ds_read_b128 v[208:211], v155 offset:22528
	ds_read_b128 v[212:215], v155 offset:23552
	global_load_lds_dwordx4 v[148:149], off
	s_add_i32 m0, s62, 0x2000
	s_add_u32 s62, s34, 0x80000
	v_lshl_add_u64 v[216:217], s[34:35], 0, v[134:135]
	s_addc_u32 s63, s35, 0
	s_add_i32 s64, s42, s40
	global_load_lds_dwordx4 v[216:217], off
	v_lshl_add_u64 v[218:219], s[62:63], 0, v[130:131]
	s_mov_b32 m0, s64
	v_lshl_add_u64 v[220:221], s[36:37], 0, v[132:133]
	global_load_lds_dwordx4 v[218:219], off
	v_lshl_add_u64 v[218:219], s[62:63], 0, v[134:135]
	s_add_i32 m0, s64, 0x2000
	s_nop 0
	global_load_lds_dwordx4 v[218:219], off
	v_lshl_add_u64 v[218:219], s[36:37], 0, v[128:129]
	s_mov_b32 m0, s29
	s_nop 0
	global_load_lds_dwordx4 v[218:219], off
	s_mov_b32 m0, s48
	s_nop 0
	global_load_lds_dwordx4 v[220:221], off
	s_waitcnt vmcnt(8)
	s_waitcnt lgkmcnt(0)
	s_barrier
	s_waitcnt lgkmcnt(0)
	v_mfma_i32_16x16x64_i8 v[60:63], v[144:147], v[184:187], v[60:63]
	v_mfma_i32_16x16x64_i8 v[56:59], v[160:163], v[184:187], v[56:59]
	v_mfma_i32_16x16x64_i8 v[44:47], v[144:147], v[192:195], v[44:47]
	v_mfma_i32_16x16x64_i8 v[40:43], v[160:163], v[192:195], v[40:43]
	v_mfma_i32_16x16x64_i8 v[28:31], v[144:147], v[200:203], v[28:31]
	v_mfma_i32_16x16x64_i8 v[24:27], v[160:163], v[200:203], v[24:27]
	v_mfma_i32_16x16x64_i8 v[12:15], v[144:147], v[208:211], v[12:15]
	v_mfma_i32_16x16x64_i8 v[8:11], v[160:163], v[208:211], v[8:11]
	v_mfma_i32_16x16x64_i8 v[60:63], v[156:159], v[188:191], v[60:63]
	v_mfma_i32_16x16x64_i8 v[56:59], v[164:167], v[188:191], v[56:59]
	v_mfma_i32_16x16x64_i8 v[44:47], v[156:159], v[196:199], v[44:47]
	v_mfma_i32_16x16x64_i8 v[40:43], v[164:167], v[196:199], v[40:43]
	v_mfma_i32_16x16x64_i8 v[28:31], v[156:159], v[204:207], v[28:31]
	v_mfma_i32_16x16x64_i8 v[24:27], v[164:167], v[204:207], v[24:27]
	v_mfma_i32_16x16x64_i8 v[12:15], v[156:159], v[212:215], v[12:15]
	v_mfma_i32_16x16x64_i8 v[8:11], v[164:167], v[212:215], v[8:11]
	v_mfma_i32_16x16x64_i8 v[52:55], v[168:171], v[184:187], v[52:55]
	v_mfma_i32_16x16x64_i8 v[48:51], v[176:179], v[184:187], v[48:51]
	v_mfma_i32_16x16x64_i8 v[36:39], v[168:171], v[192:195], v[36:39]
	v_mfma_i32_16x16x64_i8 v[32:35], v[176:179], v[192:195], v[32:35]
	v_mfma_i32_16x16x64_i8 v[20:23], v[168:171], v[200:203], v[20:23]
	v_mfma_i32_16x16x64_i8 v[16:19], v[176:179], v[200:203], v[16:19]
	v_mfma_i32_16x16x64_i8 v[4:7], v[168:171], v[208:211], v[4:7]
	v_mfma_i32_16x16x64_i8 v[0:3], v[176:179], v[208:211], v[0:3]
	v_mfma_i32_16x16x64_i8 v[52:55], v[172:175], v[188:191], v[52:55]
	v_mfma_i32_16x16x64_i8 v[48:51], v[180:183], v[188:191], v[48:51]
	v_mfma_i32_16x16x64_i8 v[36:39], v[172:175], v[196:199], v[36:39]
	v_mfma_i32_16x16x64_i8 v[32:35], v[180:183], v[196:199], v[32:35]
	v_mfma_i32_16x16x64_i8 v[20:23], v[172:175], v[204:207], v[20:23]
	v_mfma_i32_16x16x64_i8 v[16:19], v[180:183], v[204:207], v[16:19]
	v_mfma_i32_16x16x64_i8 v[4:7], v[172:175], v[212:215], v[4:7]
	v_mfma_i32_16x16x64_i8 v[0:3], v[180:183], v[212:215], v[0:3]
	s_barrier
	s_add_i32 s62, 0, 0x18000
	s_add_i32 s63, 0, 0x1c000
	v_add_u32_e32 v164, s62, v151
	v_add_u32_e32 v180, s63, v151
	ds_read_b128 v[144:147], v164
	ds_read_b128 v[156:159], v164 offset:1024
	ds_read_b128 v[160:163], v164 offset:2048
	ds_read_b128 v[164:167], v164 offset:3072
	ds_read_b128 v[168:171], v180
	ds_read_b128 v[172:175], v180 offset:1024
	ds_read_b128 v[176:179], v180 offset:2048
	ds_read_b128 v[180:183], v180 offset:3072
	s_add_u32 s36, s36, 0x80000
	s_addc_u32 s37, s37, 0
	s_mov_b32 m0, s49
	v_lshl_add_u64 v[222:223], s[36:37], 0, v[128:129]
	ds_read_b128 v[184:187], v155 offset:32768
	ds_read_b128 v[188:191], v155 offset:33792
	ds_read_b128 v[192:195], v155 offset:34816
	ds_read_b128 v[196:199], v155 offset:35840
	ds_read_b128 v[200:203], v155 offset:36864
	ds_read_b128 v[204:207], v155 offset:37888
	ds_read_b128 v[208:211], v155 offset:38912
	ds_read_b128 v[212:215], v155 offset:39936
	global_load_lds_dwordx4 v[222:223], off
	v_lshl_add_u64 v[222:223], s[36:37], 0, v[132:133]
	s_mov_b32 m0, s50
	s_nop 0
	global_load_lds_dwordx4 v[222:223], off
	s_waitcnt vmcnt(8)
	s_waitcnt lgkmcnt(0)
	s_barrier
	s_waitcnt lgkmcnt(0)
	v_mfma_i32_16x16x64_i8 v[124:127], v[144:147], v[184:187], v[124:127]
	v_mfma_i32_16x16x64_i8 v[120:123], v[160:163], v[184:187], v[120:123]
	v_mfma_i32_16x16x64_i8 v[108:111], v[144:147], v[192:195], v[108:111]
	v_mfma_i32_16x16x64_i8 v[104:107], v[160:163], v[192:195], v[104:107]
	v_mfma_i32_16x16x64_i8 v[92:95], v[144:147], v[200:203], v[92:95]
	v_mfma_i32_16x16x64_i8 v[88:91], v[160:163], v[200:203], v[88:91]
	v_mfma_i32_16x16x64_i8 v[76:79], v[144:147], v[208:211], v[76:79]
	v_mfma_i32_16x16x64_i8 v[72:75], v[160:163], v[208:211], v[72:75]
	v_mfma_i32_16x16x64_i8 v[124:127], v[156:159], v[188:191], v[124:127]
	v_mfma_i32_16x16x64_i8 v[120:123], v[164:167], v[188:191], v[120:123]
	v_mfma_i32_16x16x64_i8 v[108:111], v[156:159], v[196:199], v[108:111]
	v_mfma_i32_16x16x64_i8 v[104:107], v[164:167], v[196:199], v[104:107]
	v_mfma_i32_16x16x64_i8 v[92:95], v[156:159], v[204:207], v[92:95]
	v_mfma_i32_16x16x64_i8 v[88:91], v[164:167], v[204:207], v[88:91]
	v_mfma_i32_16x16x64_i8 v[76:79], v[156:159], v[212:215], v[76:79]
	v_mfma_i32_16x16x64_i8 v[72:75], v[164:167], v[212:215], v[72:75]
	v_mfma_i32_16x16x64_i8 v[116:119], v[168:171], v[184:187], v[116:119]
	v_mfma_i32_16x16x64_i8 v[112:115], v[176:179], v[184:187], v[112:115]
	v_mfma_i32_16x16x64_i8 v[100:103], v[168:171], v[192:195], v[100:103]
	v_mfma_i32_16x16x64_i8 v[96:99], v[176:179], v[192:195], v[96:99]
	v_mfma_i32_16x16x64_i8 v[84:87], v[168:171], v[200:203], v[84:87]
	v_mfma_i32_16x16x64_i8 v[80:83], v[176:179], v[200:203], v[80:83]
	v_mfma_i32_16x16x64_i8 v[68:71], v[168:171], v[208:211], v[68:71]
	v_mfma_i32_16x16x64_i8 v[64:67], v[176:179], v[208:211], v[64:67]
	v_mfma_i32_16x16x64_i8 v[116:119], v[172:175], v[188:191], v[116:119]
	v_mfma_i32_16x16x64_i8 v[112:115], v[180:183], v[188:191], v[112:115]
	v_mfma_i32_16x16x64_i8 v[100:103], v[172:175], v[196:199], v[100:103]
	v_mfma_i32_16x16x64_i8 v[96:99], v[180:183], v[196:199], v[96:99]
	v_mfma_i32_16x16x64_i8 v[84:87], v[172:175], v[204:207], v[84:87]
	v_mfma_i32_16x16x64_i8 v[80:83], v[180:183], v[204:207], v[80:83]
	v_mfma_i32_16x16x64_i8 v[68:71], v[172:175], v[212:215], v[68:71]
	v_mfma_i32_16x16x64_i8 v[64:67], v[180:183], v[212:215], v[64:67]
	s_barrier
	s_add_i32 s36, s62, s40
	v_lshl_add_u64 v[148:149], v[148:149], 0, s[6:7]
	s_mov_b32 m0, s36
	ds_read_b128 v[184:187], v155 offset:49152
	ds_read_b128 v[188:191], v155 offset:50176
	ds_read_b128 v[192:195], v155 offset:51200
	ds_read_b128 v[196:199], v155 offset:52224
	ds_read_b128 v[200:203], v155 offset:53248
	ds_read_b128 v[204:207], v155 offset:54272
	ds_read_b128 v[208:211], v155 offset:55296
	ds_read_b128 v[212:215], v155 offset:56320
	global_load_lds_dwordx4 v[148:149], off
	s_add_i32 m0, s36, 0x2000
	s_add_u32 s34, s34, 0x80080
	v_lshl_add_u64 v[148:149], v[216:217], 0, s[6:7]
	s_addc_u32 s35, s35, 0
	s_add_i32 s36, s63, s40
	global_load_lds_dwordx4 v[148:149], off
	v_lshl_add_u64 v[148:149], s[34:35], 0, v[130:131]
	s_mov_b32 m0, s36
	s_nop 0
	global_load_lds_dwordx4 v[148:149], off
	v_lshl_add_u64 v[148:149], s[34:35], 0, v[134:135]
	s_add_i32 m0, s36, 0x2000
	s_nop 0
	global_load_lds_dwordx4 v[148:149], off
	v_lshl_add_u64 v[148:149], v[218:219], 0, s[6:7]
	s_mov_b32 m0, s44
	s_nop 0
	global_load_lds_dwordx4 v[148:149], off
	v_lshl_add_u64 v[148:149], v[220:221], 0, s[6:7]
	s_mov_b32 m0, s52
	s_nop 0
	global_load_lds_dwordx4 v[148:149], off
	s_waitcnt vmcnt(8)
	s_waitcnt lgkmcnt(0)
	s_barrier
	s_waitcnt lgkmcnt(0)
	v_mfma_i32_16x16x64_i8 v[60:63], v[144:147], v[184:187], v[60:63]
	v_mfma_i32_16x16x64_i8 v[56:59], v[160:163], v[184:187], v[56:59]
	v_mfma_i32_16x16x64_i8 v[44:47], v[144:147], v[192:195], v[44:47]
	v_mfma_i32_16x16x64_i8 v[40:43], v[160:163], v[192:195], v[40:43]
	v_mfma_i32_16x16x64_i8 v[28:31], v[144:147], v[200:203], v[28:31]
	v_mfma_i32_16x16x64_i8 v[24:27], v[160:163], v[200:203], v[24:27]
	v_mfma_i32_16x16x64_i8 v[12:15], v[144:147], v[208:211], v[12:15]
	v_mfma_i32_16x16x64_i8 v[8:11], v[160:163], v[208:211], v[8:11]
	v_mfma_i32_16x16x64_i8 v[60:63], v[156:159], v[188:191], v[60:63]
	v_mfma_i32_16x16x64_i8 v[56:59], v[164:167], v[188:191], v[56:59]
	v_mfma_i32_16x16x64_i8 v[44:47], v[156:159], v[196:199], v[44:47]
	v_mfma_i32_16x16x64_i8 v[40:43], v[164:167], v[196:199], v[40:43]
	v_mfma_i32_16x16x64_i8 v[28:31], v[156:159], v[204:207], v[28:31]
	v_mfma_i32_16x16x64_i8 v[24:27], v[164:167], v[204:207], v[24:27]
	v_mfma_i32_16x16x64_i8 v[12:15], v[156:159], v[212:215], v[12:15]
	v_mfma_i32_16x16x64_i8 v[8:11], v[164:167], v[212:215], v[8:11]
	v_mfma_i32_16x16x64_i8 v[52:55], v[168:171], v[184:187], v[52:55]
	v_mfma_i32_16x16x64_i8 v[48:51], v[176:179], v[184:187], v[48:51]
	v_mfma_i32_16x16x64_i8 v[36:39], v[168:171], v[192:195], v[36:39]
	v_mfma_i32_16x16x64_i8 v[32:35], v[176:179], v[192:195], v[32:35]
	v_mfma_i32_16x16x64_i8 v[20:23], v[168:171], v[200:203], v[20:23]
	v_mfma_i32_16x16x64_i8 v[16:19], v[176:179], v[200:203], v[16:19]
	v_mfma_i32_16x16x64_i8 v[4:7], v[168:171], v[208:211], v[4:7]
	v_mfma_i32_16x16x64_i8 v[0:3], v[176:179], v[208:211], v[0:3]
	v_mfma_i32_16x16x64_i8 v[52:55], v[172:175], v[188:191], v[52:55]
	v_mfma_i32_16x16x64_i8 v[48:51], v[180:183], v[188:191], v[48:51]
	v_mfma_i32_16x16x64_i8 v[36:39], v[172:175], v[196:199], v[36:39]
	v_mfma_i32_16x16x64_i8 v[32:35], v[180:183], v[196:199], v[32:35]
	v_mfma_i32_16x16x64_i8 v[20:23], v[172:175], v[204:207], v[20:23]
	v_mfma_i32_16x16x64_i8 v[16:19], v[180:183], v[204:207], v[16:19]
	v_mfma_i32_16x16x64_i8 v[4:7], v[172:175], v[212:215], v[4:7]
	v_mfma_i32_16x16x64_i8 v[0:3], v[180:183], v[212:215], v[0:3]
	s_barrier
	s_add_i32 s61, s61, 2
	s_add_u32 s59, s59, 0x100
	s_addc_u32 s60, s60, 0
	s_add_u32 s30, s30, 0x100
	s_addc_u32 s31, s31, 0
	s_cmp_gt_u32 s61, 29
	s_cbranch_scc0 .LBB0_281
	s_setprio 0
	s_and_b64 vcc, exec, s[8:9]
	s_cbranch_vccz .LBB0_284
	s_barrier

.LBB0_450:
	s_ashr_i32 s21, s20, 31
	s_lshl_b64 s[22:23], s[20:21], 21
	s_add_u32 s22, s33, s22
	s_addc_u32 s23, s38, s23
	s_and_b64 s[24:25], s[4:5], exec
	s_cselect_b32 s21, s23, s35
	s_cselect_b32 s27, s22, s34
	s_ashr_i32 s19, s18, 31
	s_lshl_b64 s[24:25], s[18:19], 21
	s_add_u32 s24, s39, s24
	s_addc_u32 s25, s40, s25
	s_and_b64 s[36:37], s[4:5], exec
	s_cselect_b32 s19, s25, s31
	s_cselect_b32 s55, s24, s30
	s_add_u32 s56, s30, 0x100
	s_addc_u32 s57, s31, 0
	s_add_u32 s30, s34, 0x100080
	v_mov_b32_e32 v0, 0
	s_addc_u32 s31, s35, 0
	s_mov_b32 s58, -2
	s_waitcnt lgkmcnt(0)
	v_mov_b32_e32 v1, v0
	v_mov_b32_e32 v2, v0
	v_mov_b32_e32 v3, v0
	v_mov_b32_e32 v4, v0
	v_mov_b32_e32 v5, v0
	v_mov_b32_e32 v6, v0
	v_mov_b32_e32 v7, v0
	v_mov_b32_e32 v16, v0
	v_mov_b32_e32 v17, v0
	v_mov_b32_e32 v18, v0
	v_mov_b32_e32 v19, v0
	v_mov_b32_e32 v20, v0
	v_mov_b32_e32 v21, v0
	v_mov_b32_e32 v22, v0
	v_mov_b32_e32 v23, v0
	v_mov_b32_e32 v32, v0
	v_mov_b32_e32 v33, v0
	v_mov_b32_e32 v34, v0
	v_mov_b32_e32 v35, v0
	v_mov_b32_e32 v36, v0
	v_mov_b32_e32 v37, v0
	v_mov_b32_e32 v38, v0
	v_mov_b32_e32 v39, v0
	v_mov_b32_e32 v48, v0
	v_mov_b32_e32 v49, v0
	v_mov_b32_e32 v50, v0
	v_mov_b32_e32 v51, v0
	v_mov_b32_e32 v52, v0
	v_mov_b32_e32 v53, v0
	v_mov_b32_e32 v54, v0
	v_mov_b32_e32 v55, v0
	v_mov_b32_e32 v8, v0
	v_mov_b32_e32 v9, v0
	v_mov_b32_e32 v10, v0
	v_mov_b32_e32 v11, v0
	v_mov_b32_e32 v12, v0
	v_mov_b32_e32 v13, v0
	v_mov_b32_e32 v14, v0
	v_mov_b32_e32 v15, v0
	v_mov_b32_e32 v24, v0
	v_mov_b32_e32 v25, v0
	v_mov_b32_e32 v26, v0
	v_mov_b32_e32 v27, v0
	v_mov_b32_e32 v28, v0
	v_mov_b32_e32 v29, v0
	v_mov_b32_e32 v30, v0
	v_mov_b32_e32 v31, v0
	v_mov_b32_e32 v40, v0
	v_mov_b32_e32 v41, v0
	v_mov_b32_e32 v42, v0
	v_mov_b32_e32 v43, v0
	v_mov_b32_e32 v44, v0
	v_mov_b32_e32 v45, v0
	v_mov_b32_e32 v46, v0
	v_mov_b32_e32 v47, v0
	v_mov_b32_e32 v56, v0
	v_mov_b32_e32 v57, v0
	v_mov_b32_e32 v58, v0
	v_mov_b32_e32 v59, v0
	v_mov_b32_e32 v60, v0
	v_mov_b32_e32 v61, v0
	v_mov_b32_e32 v62, v0
	v_mov_b32_e32 v63, v0
	v_mov_b32_e32 v64, v0
	v_mov_b32_e32 v65, v0
	v_mov_b32_e32 v66, v0
	v_mov_b32_e32 v67, v0
	v_mov_b32_e32 v68, v0
	v_mov_b32_e32 v69, v0
	v_mov_b32_e32 v70, v0
	v_mov_b32_e32 v71, v0
	v_mov_b32_e32 v80, v0
	v_mov_b32_e32 v81, v0
	v_mov_b32_e32 v82, v0
	v_mov_b32_e32 v83, v0
	v_mov_b32_e32 v84, v0
	v_mov_b32_e32 v85, v0
	v_mov_b32_e32 v86, v0
	v_mov_b32_e32 v87, v0
	v_mov_b32_e32 v96, v0
	v_mov_b32_e32 v97, v0
	v_mov_b32_e32 v98, v0
	v_mov_b32_e32 v99, v0
	v_mov_b32_e32 v100, v0
	v_mov_b32_e32 v101, v0
	v_mov_b32_e32 v102, v0
	v_mov_b32_e32 v103, v0
	v_mov_b32_e32 v116, v0
	v_mov_b32_e32 v117, v0
	v_mov_b32_e32 v118, v0
	v_mov_b32_e32 v119, v0
	v_mov_b32_e32 v120, v0
	v_mov_b32_e32 v121, v0
	v_mov_b32_e32 v122, v0
	v_mov_b32_e32 v123, v0
	v_mov_b32_e32 v72, v0
	v_mov_b32_e32 v73, v0
	v_mov_b32_e32 v74, v0
	v_mov_b32_e32 v75, v0
	v_mov_b32_e32 v76, v0
	v_mov_b32_e32 v77, v0
	v_mov_b32_e32 v78, v0
	v_mov_b32_e32 v79, v0
	v_mov_b32_e32 v88, v0
	v_mov_b32_e32 v89, v0
	v_mov_b32_e32 v90, v0
	v_mov_b32_e32 v91, v0
	v_mov_b32_e32 v92, v0
	v_mov_b32_e32 v93, v0
	v_mov_b32_e32 v94, v0
	v_mov_b32_e32 v95, v0
	v_mov_b32_e32 v104, v0
	v_mov_b32_e32 v105, v0
	v_mov_b32_e32 v106, v0
	v_mov_b32_e32 v107, v0
	v_mov_b32_e32 v108, v0
	v_mov_b32_e32 v109, v0
	v_mov_b32_e32 v110, v0
	v_mov_b32_e32 v111, v0
	v_mov_b32_e32 v128, v0
	v_mov_b32_e32 v129, v0
	v_mov_b32_e32 v130, v0
	v_mov_b32_e32 v131, v0
	v_mov_b32_e32 v132, v0
	v_mov_b32_e32 v133, v0
	v_mov_b32_e32 v134, v0
	v_mov_b32_e32 v135, v0
	s_cmp_ge_u32 s81, 4
	s_cbranch_scc0 .Lsp_skip3
	s_setprio 1
.Lsp_skip3:
.LBB0_451:
	ds_read_b128 v[112:115], v193
	ds_read_b128 v[124:127], v193 offset:1024
	ds_read_b128 v[136:139], v193 offset:2048
	ds_read_b128 v[140:143], v193 offset:3072
	ds_read_b128 v[144:147], v194
	ds_read_b128 v[148:151], v194 offset:1024
	ds_read_b128 v[168:171], v194 offset:2048
	ds_read_b128 v[172:175], v194 offset:3072
	s_add_u32 s34, s30, 0xfff00080
	s_addc_u32 s35, s31, -1
	s_cmp_eq_u32 s58, 60
	s_cselect_b32 s37, s21, s35
	s_cselect_b32 s36, s27, s34
	s_cselect_b32 s35, s19, s57
	s_cselect_b32 s34, s55, s56
	v_lshl_add_u64 v[188:189], s[30:31], 0, v[162:163]
	s_add_i32 m0, s29, 0xc000
	ds_read_b128 v[176:179], v195
	ds_read_b128 v[180:183], v195 offset:1024
	ds_read_b128 v[184:187], v195 offset:2048
	ds_read_b128 v[200:203], v195 offset:3072
	ds_read_b128 v[204:207], v195 offset:4096
	ds_read_b128 v[208:211], v195 offset:5120
	ds_read_b128 v[212:215], v195 offset:6144
	ds_read_b128 v[216:219], v195 offset:7168
	global_load_lds_dwordx4 v[188:189], off
	v_lshl_add_u64 v[188:189], s[30:31], 0, v[160:161]
	s_add_i32 m0, s29, 0xe000
	s_nop 0
	global_load_lds_dwordx4 v[188:189], off
	s_waitcnt vmcnt(8)
	s_waitcnt lgkmcnt(0)
	s_barrier
	s_waitcnt lgkmcnt(0)
	v_mfma_f32_16x16x32_bf16 v[132:135], v[112:115], v[176:179], v[132:135]
	v_mfma_f32_16x16x32_bf16 v[128:131], v[136:139], v[176:179], v[128:131]
	v_mfma_f32_16x16x32_bf16 v[108:111], v[112:115], v[184:187], v[108:111]
	v_mfma_f32_16x16x32_bf16 v[104:107], v[136:139], v[184:187], v[104:107]
	v_mfma_f32_16x16x32_bf16 v[92:95], v[112:115], v[204:207], v[92:95]
	v_mfma_f32_16x16x32_bf16 v[88:91], v[136:139], v[204:207], v[88:91]
	v_mfma_f32_16x16x32_bf16 v[76:79], v[112:115], v[212:215], v[76:79]
	v_mfma_f32_16x16x32_bf16 v[72:75], v[136:139], v[212:215], v[72:75]
	v_mfma_f32_16x16x32_bf16 v[132:135], v[124:127], v[180:183], v[132:135]
	v_mfma_f32_16x16x32_bf16 v[128:131], v[140:143], v[180:183], v[128:131]
	v_mfma_f32_16x16x32_bf16 v[108:111], v[124:127], v[200:203], v[108:111]
	v_mfma_f32_16x16x32_bf16 v[104:107], v[140:143], v[200:203], v[104:107]
	v_mfma_f32_16x16x32_bf16 v[92:95], v[124:127], v[208:211], v[92:95]
	v_mfma_f32_16x16x32_bf16 v[88:91], v[140:143], v[208:211], v[88:91]
	v_mfma_f32_16x16x32_bf16 v[76:79], v[124:127], v[216:219], v[76:79]
	v_mfma_f32_16x16x32_bf16 v[72:75], v[140:143], v[216:219], v[72:75]
	v_mfma_f32_16x16x32_bf16 v[120:123], v[144:147], v[176:179], v[120:123]
	v_mfma_f32_16x16x32_bf16 v[116:119], v[168:171], v[176:179], v[116:119]
	v_mfma_f32_16x16x32_bf16 v[100:103], v[144:147], v[184:187], v[100:103]
	v_mfma_f32_16x16x32_bf16 v[96:99], v[168:171], v[184:187], v[96:99]
	v_mfma_f32_16x16x32_bf16 v[84:87], v[144:147], v[204:207], v[84:87]
	v_mfma_f32_16x16x32_bf16 v[80:83], v[168:171], v[204:207], v[80:83]
	v_mfma_f32_16x16x32_bf16 v[68:71], v[144:147], v[212:215], v[68:71]
	v_mfma_f32_16x16x32_bf16 v[64:67], v[168:171], v[212:215], v[64:67]
	v_mfma_f32_16x16x32_bf16 v[120:123], v[148:151], v[180:183], v[120:123]
	v_mfma_f32_16x16x32_bf16 v[116:119], v[172:175], v[180:183], v[116:119]
	v_mfma_f32_16x16x32_bf16 v[100:103], v[148:151], v[200:203], v[100:103]
	v_mfma_f32_16x16x32_bf16 v[96:99], v[172:175], v[200:203], v[96:99]
	v_mfma_f32_16x16x32_bf16 v[84:87], v[148:151], v[208:211], v[84:87]
	v_mfma_f32_16x16x32_bf16 v[80:83], v[172:175], v[208:211], v[80:83]
	v_mfma_f32_16x16x32_bf16 v[68:71], v[148:151], v[216:219], v[68:71]
	v_mfma_f32_16x16x32_bf16 v[64:67], v[172:175], v[216:219], v[64:67]
	s_barrier
	s_add_i32 s59, s50, s41
	v_lshl_add_u64 v[188:189], s[34:35], 0, v[154:155]
	s_mov_b32 m0, s59
	ds_read_b128 v[176:179], v195 offset:16384
	ds_read_b128 v[180:183], v195 offset:17408
	ds_read_b128 v[184:187], v195 offset:18432
	ds_read_b128 v[200:203], v195 offset:19456
	ds_read_b128 v[204:207], v195 offset:20480
	ds_read_b128 v[208:211], v195 offset:21504
	ds_read_b128 v[212:215], v195 offset:22528
	ds_read_b128 v[216:219], v195 offset:23552
	global_load_lds_dwordx4 v[188:189], off
	s_add_i32 m0, s59, 0x2000
	s_add_u32 s60, s34, 0x100000
	v_lshl_add_u64 v[220:221], s[34:35], 0, v[158:159]
	s_addc_u32 s61, s35, 0
	s_add_i32 s59, s51, s41
	global_load_lds_dwordx4 v[220:221], off
	v_lshl_add_u64 v[222:223], s[60:61], 0, v[154:155]
	s_mov_b32 m0, s59
	v_lshl_add_u64 v[224:225], s[36:37], 0, v[156:157]
	global_load_lds_dwordx4 v[222:223], off
	v_lshl_add_u64 v[222:223], s[60:61], 0, v[158:159]
	s_add_i32 m0, s59, 0x2000
	s_nop 0
	global_load_lds_dwordx4 v[222:223], off
	v_lshl_add_u64 v[222:223], s[36:37], 0, v[152:153]
	s_mov_b32 m0, s29
	s_nop 0
	global_load_lds_dwordx4 v[222:223], off
	s_mov_b32 m0, s42
	s_nop 0
	global_load_lds_dwordx4 v[224:225], off
	s_waitcnt vmcnt(8)
	s_waitcnt lgkmcnt(0)
	s_barrier
	s_waitcnt lgkmcnt(0)
	v_mfma_f32_16x16x32_bf16 v[60:63], v[112:115], v[176:179], v[60:63]
	v_mfma_f32_16x16x32_bf16 v[56:59], v[136:139], v[176:179], v[56:59]
	v_mfma_f32_16x16x32_bf16 v[44:47], v[112:115], v[184:187], v[44:47]
	v_mfma_f32_16x16x32_bf16 v[40:43], v[136:139], v[184:187], v[40:43]
	v_mfma_f32_16x16x32_bf16 v[28:31], v[112:115], v[204:207], v[28:31]
	v_mfma_f32_16x16x32_bf16 v[24:27], v[136:139], v[204:207], v[24:27]
	v_mfma_f32_16x16x32_bf16 v[12:15], v[112:115], v[212:215], v[12:15]
	v_mfma_f32_16x16x32_bf16 v[8:11], v[136:139], v[212:215], v[8:11]
	v_mfma_f32_16x16x32_bf16 v[60:63], v[124:127], v[180:183], v[60:63]
	v_mfma_f32_16x16x32_bf16 v[56:59], v[140:143], v[180:183], v[56:59]
	v_mfma_f32_16x16x32_bf16 v[44:47], v[124:127], v[200:203], v[44:47]
	v_mfma_f32_16x16x32_bf16 v[40:43], v[140:143], v[200:203], v[40:43]
	v_mfma_f32_16x16x32_bf16 v[28:31], v[124:127], v[208:211], v[28:31]
	v_mfma_f32_16x16x32_bf16 v[24:27], v[140:143], v[208:211], v[24:27]
	v_mfma_f32_16x16x32_bf16 v[12:15], v[124:127], v[216:219], v[12:15]
	v_mfma_f32_16x16x32_bf16 v[8:11], v[140:143], v[216:219], v[8:11]
	v_mfma_f32_16x16x32_bf16 v[52:55], v[144:147], v[176:179], v[52:55]
	v_mfma_f32_16x16x32_bf16 v[48:51], v[168:171], v[176:179], v[48:51]
	v_mfma_f32_16x16x32_bf16 v[36:39], v[144:147], v[184:187], v[36:39]
	v_mfma_f32_16x16x32_bf16 v[32:35], v[168:171], v[184:187], v[32:35]
	v_mfma_f32_16x16x32_bf16 v[20:23], v[144:147], v[204:207], v[20:23]
	v_mfma_f32_16x16x32_bf16 v[16:19], v[168:171], v[204:207], v[16:19]
	v_mfma_f32_16x16x32_bf16 v[4:7], v[144:147], v[212:215], v[4:7]
	v_mfma_f32_16x16x32_bf16 v[0:3], v[168:171], v[212:215], v[0:3]
	v_mfma_f32_16x16x32_bf16 v[52:55], v[148:151], v[180:183], v[52:55]
	v_mfma_f32_16x16x32_bf16 v[48:51], v[172:175], v[180:183], v[48:51]
	v_mfma_f32_16x16x32_bf16 v[36:39], v[148:151], v[200:203], v[36:39]
	v_mfma_f32_16x16x32_bf16 v[32:35], v[172:175], v[200:203], v[32:35]
	v_mfma_f32_16x16x32_bf16 v[20:23], v[148:151], v[208:211], v[20:23]
	v_mfma_f32_16x16x32_bf16 v[16:19], v[172:175], v[208:211], v[16:19]
	v_mfma_f32_16x16x32_bf16 v[4:7], v[148:151], v[216:219], v[4:7]
	v_mfma_f32_16x16x32_bf16 v[0:3], v[172:175], v[216:219], v[0:3]
	s_barrier
	s_add_i32 s59, 0, 0x18000
	s_add_i32 s60, 0, 0x1c000
	v_add_u32_e32 v140, s59, v191
	v_add_u32_e32 v172, s60, v191
	ds_read_b128 v[112:115], v140
	ds_read_b128 v[124:127], v140 offset:1024
	ds_read_b128 v[136:139], v140 offset:2048
	ds_read_b128 v[140:143], v140 offset:3072
	ds_read_b128 v[144:147], v172
	ds_read_b128 v[148:151], v172 offset:1024
	ds_read_b128 v[168:171], v172 offset:2048
	ds_read_b128 v[172:175], v172 offset:3072
	s_add_u32 s36, s36, 0x100000
	s_addc_u32 s37, s37, 0
	s_mov_b32 m0, s43
	v_lshl_add_u64 v[226:227], s[36:37], 0, v[152:153]
	ds_read_b128 v[176:179], v195 offset:32768
	ds_read_b128 v[180:183], v195 offset:33792
	ds_read_b128 v[184:187], v195 offset:34816
	ds_read_b128 v[200:203], v195 offset:35840
	ds_read_b128 v[204:207], v195 offset:36864
	ds_read_b128 v[208:211], v195 offset:37888
	ds_read_b128 v[212:215], v195 offset:38912
	ds_read_b128 v[216:219], v195 offset:39936
	global_load_lds_dwordx4 v[226:227], off
	v_lshl_add_u64 v[226:227], s[36:37], 0, v[156:157]
	s_mov_b32 m0, s44
	s_nop 0
	global_load_lds_dwordx4 v[226:227], off
	s_waitcnt vmcnt(8)
	s_waitcnt lgkmcnt(0)
	s_barrier
	s_waitcnt lgkmcnt(0)
	v_mfma_f32_16x16x32_bf16 v[132:135], v[112:115], v[176:179], v[132:135]
	v_mfma_f32_16x16x32_bf16 v[128:131], v[136:139], v[176:179], v[128:131]
	v_mfma_f32_16x16x32_bf16 v[108:111], v[112:115], v[184:187], v[108:111]
	v_mfma_f32_16x16x32_bf16 v[104:107], v[136:139], v[184:187], v[104:107]
	v_mfma_f32_16x16x32_bf16 v[92:95], v[112:115], v[204:207], v[92:95]
	v_mfma_f32_16x16x32_bf16 v[88:91], v[136:139], v[204:207], v[88:91]
	v_mfma_f32_16x16x32_bf16 v[76:79], v[112:115], v[212:215], v[76:79]
	v_mfma_f32_16x16x32_bf16 v[72:75], v[136:139], v[212:215], v[72:75]
	v_mfma_f32_16x16x32_bf16 v[132:135], v[124:127], v[180:183], v[132:135]
	v_mfma_f32_16x16x32_bf16 v[128:131], v[140:143], v[180:183], v[128:131]
	v_mfma_f32_16x16x32_bf16 v[108:111], v[124:127], v[200:203], v[108:111]
	v_mfma_f32_16x16x32_bf16 v[104:107], v[140:143], v[200:203], v[104:107]
	v_mfma_f32_16x16x32_bf16 v[92:95], v[124:127], v[208:211], v[92:95]
	v_mfma_f32_16x16x32_bf16 v[88:91], v[140:143], v[208:211], v[88:91]
	v_mfma_f32_16x16x32_bf16 v[76:79], v[124:127], v[216:219], v[76:79]
	v_mfma_f32_16x16x32_bf16 v[72:75], v[140:143], v[216:219], v[72:75]
	v_mfma_f32_16x16x32_bf16 v[120:123], v[144:147], v[176:179], v[120:123]
	v_mfma_f32_16x16x32_bf16 v[116:119], v[168:171], v[176:179], v[116:119]
	v_mfma_f32_16x16x32_bf16 v[100:103], v[144:147], v[184:187], v[100:103]
	v_mfma_f32_16x16x32_bf16 v[96:99], v[168:171], v[184:187], v[96:99]
	v_mfma_f32_16x16x32_bf16 v[84:87], v[144:147], v[204:207], v[84:87]
	v_mfma_f32_16x16x32_bf16 v[80:83], v[168:171], v[204:207], v[80:83]
	v_mfma_f32_16x16x32_bf16 v[68:71], v[144:147], v[212:215], v[68:71]
	v_mfma_f32_16x16x32_bf16 v[64:67], v[168:171], v[212:215], v[64:67]
	v_mfma_f32_16x16x32_bf16 v[120:123], v[148:151], v[180:183], v[120:123]
	v_mfma_f32_16x16x32_bf16 v[116:119], v[172:175], v[180:183], v[116:119]
	v_mfma_f32_16x16x32_bf16 v[100:103], v[148:151], v[200:203], v[100:103]
	v_mfma_f32_16x16x32_bf16 v[96:99], v[172:175], v[200:203], v[96:99]
	v_mfma_f32_16x16x32_bf16 v[84:87], v[148:151], v[208:211], v[84:87]
	v_mfma_f32_16x16x32_bf16 v[80:83], v[172:175], v[208:211], v[80:83]
	v_mfma_f32_16x16x32_bf16 v[68:71], v[148:151], v[216:219], v[68:71]
	v_mfma_f32_16x16x32_bf16 v[64:67], v[172:175], v[216:219], v[64:67]
	s_barrier
	s_add_i32 s36, s59, s41
	v_lshl_add_u64 v[188:189], v[188:189], 0, s[14:15]
	s_mov_b32 m0, s36
	ds_read_b128 v[176:179], v195 offset:49152
	ds_read_b128 v[180:183], v195 offset:50176
	ds_read_b128 v[184:187], v195 offset:51200
	ds_read_b128 v[200:203], v195 offset:52224
	ds_read_b128 v[204:207], v195 offset:53248
	ds_read_b128 v[208:211], v195 offset:54272
	ds_read_b128 v[212:215], v195 offset:55296
	ds_read_b128 v[216:219], v195 offset:56320
	global_load_lds_dwordx4 v[188:189], off
	s_add_i32 m0, s36, 0x2000
	s_add_u32 s34, s34, 0x100080
	v_lshl_add_u64 v[188:189], v[220:221], 0, s[14:15]
	s_addc_u32 s35, s35, 0
	s_add_i32 s36, s60, s41
	global_load_lds_dwordx4 v[188:189], off
	v_lshl_add_u64 v[188:189], s[34:35], 0, v[154:155]
	s_mov_b32 m0, s36
	s_nop 0
	global_load_lds_dwordx4 v[188:189], off
	v_lshl_add_u64 v[188:189], s[34:35], 0, v[158:159]
	s_add_i32 m0, s36, 0x2000
	s_nop 0
	global_load_lds_dwordx4 v[188:189], off
	v_lshl_add_u64 v[188:189], v[222:223], 0, s[14:15]
	s_mov_b32 m0, s46
	s_nop 0
	global_load_lds_dwordx4 v[188:189], off
	v_lshl_add_u64 v[188:189], v[224:225], 0, s[14:15]
	s_mov_b32 m0, s47
	s_nop 0
	global_load_lds_dwordx4 v[188:189], off
	s_waitcnt vmcnt(8)
	s_waitcnt lgkmcnt(0)
	s_barrier
	s_waitcnt lgkmcnt(0)
	v_mfma_f32_16x16x32_bf16 v[60:63], v[112:115], v[176:179], v[60:63]
	v_mfma_f32_16x16x32_bf16 v[56:59], v[136:139], v[176:179], v[56:59]
	v_mfma_f32_16x16x32_bf16 v[44:47], v[112:115], v[184:187], v[44:47]
	v_mfma_f32_16x16x32_bf16 v[40:43], v[136:139], v[184:187], v[40:43]
	v_mfma_f32_16x16x32_bf16 v[28:31], v[112:115], v[204:207], v[28:31]
	v_mfma_f32_16x16x32_bf16 v[24:27], v[136:139], v[204:207], v[24:27]
	v_mfma_f32_16x16x32_bf16 v[12:15], v[112:115], v[212:215], v[12:15]
	v_mfma_f32_16x16x32_bf16 v[8:11], v[136:139], v[212:215], v[8:11]
	v_mfma_f32_16x16x32_bf16 v[60:63], v[124:127], v[180:183], v[60:63]
	v_mfma_f32_16x16x32_bf16 v[56:59], v[140:143], v[180:183], v[56:59]
	v_mfma_f32_16x16x32_bf16 v[44:47], v[124:127], v[200:203], v[44:47]
	v_mfma_f32_16x16x32_bf16 v[40:43], v[140:143], v[200:203], v[40:43]
	v_mfma_f32_16x16x32_bf16 v[28:31], v[124:127], v[208:211], v[28:31]
	v_mfma_f32_16x16x32_bf16 v[24:27], v[140:143], v[208:211], v[24:27]
	v_mfma_f32_16x16x32_bf16 v[12:15], v[124:127], v[216:219], v[12:15]
	v_mfma_f32_16x16x32_bf16 v[8:11], v[140:143], v[216:219], v[8:11]
	v_mfma_f32_16x16x32_bf16 v[52:55], v[144:147], v[176:179], v[52:55]
	v_mfma_f32_16x16x32_bf16 v[48:51], v[168:171], v[176:179], v[48:51]
	v_mfma_f32_16x16x32_bf16 v[36:39], v[144:147], v[184:187], v[36:39]
	v_mfma_f32_16x16x32_bf16 v[32:35], v[168:171], v[184:187], v[32:35]
	v_mfma_f32_16x16x32_bf16 v[20:23], v[144:147], v[204:207], v[20:23]
	v_mfma_f32_16x16x32_bf16 v[16:19], v[168:171], v[204:207], v[16:19]
	v_mfma_f32_16x16x32_bf16 v[4:7], v[144:147], v[212:215], v[4:7]
	v_mfma_f32_16x16x32_bf16 v[0:3], v[168:171], v[212:215], v[0:3]
	v_mfma_f32_16x16x32_bf16 v[52:55], v[148:151], v[180:183], v[52:55]
	v_mfma_f32_16x16x32_bf16 v[48:51], v[172:175], v[180:183], v[48:51]
	v_mfma_f32_16x16x32_bf16 v[36:39], v[148:151], v[200:203], v[36:39]
	v_mfma_f32_16x16x32_bf16 v[32:35], v[172:175], v[200:203], v[32:35]
	v_mfma_f32_16x16x32_bf16 v[20:23], v[148:151], v[208:211], v[20:23]
	v_mfma_f32_16x16x32_bf16 v[16:19], v[172:175], v[208:211], v[16:19]
	v_mfma_f32_16x16x32_bf16 v[4:7], v[148:151], v[216:219], v[4:7]
	v_mfma_f32_16x16x32_bf16 v[0:3], v[172:175], v[216:219], v[0:3]
	s_barrier
	s_add_i32 s58, s58, 2
	s_add_u32 s56, s56, 0x100
	s_addc_u32 s57, s57, 0
	s_add_u32 s30, s30, 0x100
	s_addc_u32 s31, s31, 0
	s_cmp_gt_u32 s58, 61
	s_cbranch_scc0 .LBB0_451
	s_setprio 0
	s_and_b64 vcc, exec, s[16:17]
	s_cbranch_vccz .LBB0_454
	s_barrier

.LBB0_549:
	s_ashr_i32 s31, s30, 31
	s_lshl_b64 s[34:35], s[30:31], 20
	s_add_u32 s34, s40, s34
	s_addc_u32 s35, s41, s35
	s_and_b64 s[36:37], s[2:3], exec
	s_cselect_b32 s1, s35, s7
	s_cselect_b32 s31, s34, s6
	s_ashr_i32 s29, s28, 31
	s_lshl_b64 s[36:37], s[28:29], 20
	s_add_u32 s36, s42, s36
	s_addc_u32 s37, s43, s37
	s_and_b64 s[38:39], s[2:3], exec
	s_cselect_b32 s29, s37, s5
	s_cselect_b32 s61, s36, s4
	s_add_u32 s62, s4, 0x100
	s_addc_u32 s63, s5, 0
	s_add_u32 s4, s6, 0x80080
	v_mov_b32_e32 v0, 0
	s_addc_u32 s5, s7, 0
	s_mov_b32 s64, -2
	v_mov_b32_e32 v1, v0
	v_mov_b32_e32 v2, v0
	v_mov_b32_e32 v3, v0
	v_mov_b32_e32 v4, v0
	v_mov_b32_e32 v5, v0
	v_mov_b32_e32 v6, v0
	v_mov_b32_e32 v7, v0
	v_mov_b32_e32 v16, v0
	v_mov_b32_e32 v17, v0
	v_mov_b32_e32 v18, v0
	v_mov_b32_e32 v19, v0
	v_mov_b32_e32 v20, v0
	v_mov_b32_e32 v21, v0
	v_mov_b32_e32 v22, v0
	v_mov_b32_e32 v23, v0
	v_mov_b32_e32 v32, v0
	v_mov_b32_e32 v33, v0
	v_mov_b32_e32 v34, v0
	v_mov_b32_e32 v35, v0
	v_mov_b32_e32 v36, v0
	v_mov_b32_e32 v37, v0
	v_mov_b32_e32 v38, v0
	v_mov_b32_e32 v39, v0
	v_mov_b32_e32 v48, v0
	v_mov_b32_e32 v49, v0
	v_mov_b32_e32 v50, v0
	v_mov_b32_e32 v51, v0
	v_mov_b32_e32 v52, v0
	v_mov_b32_e32 v53, v0
	v_mov_b32_e32 v54, v0
	v_mov_b32_e32 v55, v0
	v_mov_b32_e32 v8, v0
	v_mov_b32_e32 v9, v0
	v_mov_b32_e32 v10, v0
	v_mov_b32_e32 v11, v0
	v_mov_b32_e32 v12, v0
	v_mov_b32_e32 v13, v0
	v_mov_b32_e32 v14, v0
	v_mov_b32_e32 v15, v0
	v_mov_b32_e32 v24, v0
	v_mov_b32_e32 v25, v0
	v_mov_b32_e32 v26, v0
	v_mov_b32_e32 v27, v0
	v_mov_b32_e32 v28, v0
	v_mov_b32_e32 v29, v0
	v_mov_b32_e32 v30, v0
	v_mov_b32_e32 v31, v0
	v_mov_b32_e32 v40, v0
	v_mov_b32_e32 v41, v0
	v_mov_b32_e32 v42, v0
	v_mov_b32_e32 v43, v0
	v_mov_b32_e32 v44, v0
	v_mov_b32_e32 v45, v0
	v_mov_b32_e32 v46, v0
	v_mov_b32_e32 v47, v0
	v_mov_b32_e32 v56, v0
	v_mov_b32_e32 v57, v0
	v_mov_b32_e32 v58, v0
	v_mov_b32_e32 v59, v0
	v_mov_b32_e32 v60, v0
	v_mov_b32_e32 v61, v0
	v_mov_b32_e32 v62, v0
	v_mov_b32_e32 v63, v0
	v_mov_b32_e32 v64, v0
	v_mov_b32_e32 v65, v0
	v_mov_b32_e32 v66, v0
	v_mov_b32_e32 v67, v0
	v_mov_b32_e32 v68, v0
	v_mov_b32_e32 v69, v0
	v_mov_b32_e32 v70, v0
	v_mov_b32_e32 v71, v0
	v_mov_b32_e32 v80, v0
	v_mov_b32_e32 v81, v0
	v_mov_b32_e32 v82, v0
	v_mov_b32_e32 v83, v0
	v_mov_b32_e32 v84, v0
	v_mov_b32_e32 v85, v0
	v_mov_b32_e32 v86, v0
	v_mov_b32_e32 v87, v0
	v_mov_b32_e32 v96, v0
	v_mov_b32_e32 v97, v0
	v_mov_b32_e32 v98, v0
	v_mov_b32_e32 v99, v0
	v_mov_b32_e32 v100, v0
	v_mov_b32_e32 v101, v0
	v_mov_b32_e32 v102, v0
	v_mov_b32_e32 v103, v0
	v_mov_b32_e32 v112, v0
	v_mov_b32_e32 v113, v0
	v_mov_b32_e32 v114, v0
	v_mov_b32_e32 v115, v0
	v_mov_b32_e32 v116, v0
	v_mov_b32_e32 v117, v0
	v_mov_b32_e32 v118, v0
	v_mov_b32_e32 v119, v0
	v_mov_b32_e32 v72, v0
	v_mov_b32_e32 v73, v0
	v_mov_b32_e32 v74, v0
	v_mov_b32_e32 v75, v0
	v_mov_b32_e32 v76, v0
	v_mov_b32_e32 v77, v0
	v_mov_b32_e32 v78, v0
	v_mov_b32_e32 v79, v0
	v_mov_b32_e32 v88, v0
	v_mov_b32_e32 v89, v0
	v_mov_b32_e32 v90, v0
	v_mov_b32_e32 v91, v0
	v_mov_b32_e32 v92, v0
	v_mov_b32_e32 v93, v0
	v_mov_b32_e32 v94, v0
	v_mov_b32_e32 v95, v0
	v_mov_b32_e32 v104, v0
	v_mov_b32_e32 v105, v0
	v_mov_b32_e32 v106, v0
	v_mov_b32_e32 v107, v0
	v_mov_b32_e32 v108, v0
	v_mov_b32_e32 v109, v0
	v_mov_b32_e32 v110, v0
	v_mov_b32_e32 v111, v0
	v_mov_b32_e32 v120, v0
	v_mov_b32_e32 v121, v0
	v_mov_b32_e32 v122, v0
	v_mov_b32_e32 v123, v0
	v_mov_b32_e32 v124, v0
	v_mov_b32_e32 v125, v0
	v_mov_b32_e32 v126, v0
	v_mov_b32_e32 v127, v0
	s_cmp_ge_u32 s81, 4
	s_cbranch_scc0 .Lsp_skip4
	s_setprio 1
.Lsp_skip4:
.LBB0_550:
	ds_read_b128 v[144:147], v161
	ds_read_b128 v[148:151], v161 offset:1024
	ds_read_b128 v[170:173], v161 offset:2048
	ds_read_b128 v[174:177], v161 offset:3072
	ds_read_b128 v[178:181], v163
	ds_read_b128 v[182:185], v163 offset:1024
	ds_read_b128 v[186:189], v163 offset:2048
	ds_read_b128 v[190:193], v163 offset:3072
	s_add_u32 s6, s4, 0xfff80080
	s_addc_u32 s7, s5, -1
	s_cmp_eq_u32 s64, 28
	s_cselect_b32 s39, s1, s7
	s_cselect_b32 s38, s31, s6
	s_cselect_b32 s7, s29, s63
	s_cselect_b32 s6, s61, s62
	v_lshl_add_u64 v[152:153], s[4:5], 0, v[138:139]
	s_add_i32 m0, s45, 0xc000
	ds_read_b128 v[194:197], v166
	ds_read_b128 v[198:201], v166 offset:1024
	ds_read_b128 v[202:205], v166 offset:2048
	ds_read_b128 v[206:209], v166 offset:3072
	ds_read_b128 v[210:213], v166 offset:4096
	ds_read_b128 v[214:217], v166 offset:5120
	ds_read_b128 v[218:221], v166 offset:6144
	ds_read_b128 v[222:225], v166 offset:7168
	global_load_lds_dwordx4 v[152:153], off
	v_lshl_add_u64 v[152:153], s[4:5], 0, v[136:137]
	s_add_i32 m0, s45, 0xe000
	s_nop 0
	global_load_lds_dwordx4 v[152:153], off
	s_waitcnt vmcnt(8)
	s_waitcnt lgkmcnt(0)
	s_barrier
	s_waitcnt lgkmcnt(0)
	v_mfma_i32_16x16x64_i8 v[124:127], v[144:147], v[194:197], v[124:127]
	v_mfma_i32_16x16x64_i8 v[120:123], v[170:173], v[194:197], v[120:123]
	v_mfma_i32_16x16x64_i8 v[108:111], v[144:147], v[202:205], v[108:111]
	v_mfma_i32_16x16x64_i8 v[104:107], v[170:173], v[202:205], v[104:107]
	v_mfma_i32_16x16x64_i8 v[92:95], v[144:147], v[210:213], v[92:95]
	v_mfma_i32_16x16x64_i8 v[88:91], v[170:173], v[210:213], v[88:91]
	v_mfma_i32_16x16x64_i8 v[76:79], v[144:147], v[218:221], v[76:79]
	v_mfma_i32_16x16x64_i8 v[72:75], v[170:173], v[218:221], v[72:75]
	v_mfma_i32_16x16x64_i8 v[124:127], v[148:151], v[198:201], v[124:127]
	v_mfma_i32_16x16x64_i8 v[120:123], v[174:177], v[198:201], v[120:123]
	v_mfma_i32_16x16x64_i8 v[108:111], v[148:151], v[206:209], v[108:111]
	v_mfma_i32_16x16x64_i8 v[104:107], v[174:177], v[206:209], v[104:107]
	v_mfma_i32_16x16x64_i8 v[92:95], v[148:151], v[214:217], v[92:95]
	v_mfma_i32_16x16x64_i8 v[88:91], v[174:177], v[214:217], v[88:91]
	v_mfma_i32_16x16x64_i8 v[76:79], v[148:151], v[222:225], v[76:79]
	v_mfma_i32_16x16x64_i8 v[72:75], v[174:177], v[222:225], v[72:75]
	v_mfma_i32_16x16x64_i8 v[116:119], v[178:181], v[194:197], v[116:119]
	v_mfma_i32_16x16x64_i8 v[112:115], v[186:189], v[194:197], v[112:115]
	v_mfma_i32_16x16x64_i8 v[100:103], v[178:181], v[202:205], v[100:103]
	v_mfma_i32_16x16x64_i8 v[96:99], v[186:189], v[202:205], v[96:99]
	v_mfma_i32_16x16x64_i8 v[84:87], v[178:181], v[210:213], v[84:87]
	v_mfma_i32_16x16x64_i8 v[80:83], v[186:189], v[210:213], v[80:83]
	v_mfma_i32_16x16x64_i8 v[68:71], v[178:181], v[218:221], v[68:71]
	v_mfma_i32_16x16x64_i8 v[64:67], v[186:189], v[218:221], v[64:67]
	v_mfma_i32_16x16x64_i8 v[116:119], v[182:185], v[198:201], v[116:119]
	v_mfma_i32_16x16x64_i8 v[112:115], v[190:193], v[198:201], v[112:115]
	v_mfma_i32_16x16x64_i8 v[100:103], v[182:185], v[206:209], v[100:103]
	v_mfma_i32_16x16x64_i8 v[96:99], v[190:193], v[206:209], v[96:99]
	v_mfma_i32_16x16x64_i8 v[84:87], v[182:185], v[214:217], v[84:87]
	v_mfma_i32_16x16x64_i8 v[80:83], v[190:193], v[214:217], v[80:83]
	v_mfma_i32_16x16x64_i8 v[68:71], v[182:185], v[222:225], v[68:71]
	v_mfma_i32_16x16x64_i8 v[64:67], v[190:193], v[222:225], v[64:67]
	s_barrier
	s_add_i32 s65, s53, s44
	v_lshl_add_u64 v[152:153], s[6:7], 0, v[130:131]
	s_mov_b32 m0, s65
	ds_read_b128 v[194:197], v166 offset:16384
	ds_read_b128 v[198:201], v166 offset:17408
	ds_read_b128 v[202:205], v166 offset:18432
	ds_read_b128 v[206:209], v166 offset:19456
	ds_read_b128 v[210:213], v166 offset:20480
	ds_read_b128 v[214:217], v166 offset:21504
	ds_read_b128 v[218:221], v166 offset:22528
	ds_read_b128 v[222:225], v166 offset:23552
	global_load_lds_dwordx4 v[152:153], off
	s_add_i32 m0, s65, 0x2000
	s_add_u32 s66, s6, 0x80000
	v_lshl_add_u64 v[164:165], s[6:7], 0, v[134:135]
	s_addc_u32 s67, s7, 0
	s_add_i32 s65, s54, s44
	global_load_lds_dwordx4 v[164:165], off
	v_lshl_add_u64 v[226:227], s[66:67], 0, v[130:131]
	s_mov_b32 m0, s65
	v_lshl_add_u64 v[228:229], s[38:39], 0, v[132:133]
	global_load_lds_dwordx4 v[226:227], off
	v_lshl_add_u64 v[226:227], s[66:67], 0, v[134:135]
	s_add_i32 m0, s65, 0x2000
	s_nop 0
	global_load_lds_dwordx4 v[226:227], off
	v_lshl_add_u64 v[226:227], s[38:39], 0, v[128:129]
	s_mov_b32 m0, s45
	s_nop 0
	global_load_lds_dwordx4 v[226:227], off
	s_mov_b32 m0, s46
	s_nop 0
	global_load_lds_dwordx4 v[228:229], off
	s_waitcnt vmcnt(8)
	s_waitcnt lgkmcnt(0)
	s_barrier
	s_waitcnt lgkmcnt(0)
	v_mfma_i32_16x16x64_i8 v[60:63], v[144:147], v[194:197], v[60:63]
	v_mfma_i32_16x16x64_i8 v[56:59], v[170:173], v[194:197], v[56:59]
	v_mfma_i32_16x16x64_i8 v[44:47], v[144:147], v[202:205], v[44:47]
	v_mfma_i32_16x16x64_i8 v[40:43], v[170:173], v[202:205], v[40:43]
	v_mfma_i32_16x16x64_i8 v[28:31], v[144:147], v[210:213], v[28:31]
	v_mfma_i32_16x16x64_i8 v[24:27], v[170:173], v[210:213], v[24:27]
	v_mfma_i32_16x16x64_i8 v[12:15], v[144:147], v[218:221], v[12:15]
	v_mfma_i32_16x16x64_i8 v[8:11], v[170:173], v[218:221], v[8:11]
	v_mfma_i32_16x16x64_i8 v[60:63], v[148:151], v[198:201], v[60:63]
	v_mfma_i32_16x16x64_i8 v[56:59], v[174:177], v[198:201], v[56:59]
	v_mfma_i32_16x16x64_i8 v[44:47], v[148:151], v[206:209], v[44:47]
	v_mfma_i32_16x16x64_i8 v[40:43], v[174:177], v[206:209], v[40:43]
	v_mfma_i32_16x16x64_i8 v[28:31], v[148:151], v[214:217], v[28:31]
	v_mfma_i32_16x16x64_i8 v[24:27], v[174:177], v[214:217], v[24:27]
	v_mfma_i32_16x16x64_i8 v[12:15], v[148:151], v[222:225], v[12:15]
	v_mfma_i32_16x16x64_i8 v[8:11], v[174:177], v[222:225], v[8:11]
	v_mfma_i32_16x16x64_i8 v[52:55], v[178:181], v[194:197], v[52:55]
	v_mfma_i32_16x16x64_i8 v[48:51], v[186:189], v[194:197], v[48:51]
	v_mfma_i32_16x16x64_i8 v[36:39], v[178:181], v[202:205], v[36:39]
	v_mfma_i32_16x16x64_i8 v[32:35], v[186:189], v[202:205], v[32:35]
	v_mfma_i32_16x16x64_i8 v[20:23], v[178:181], v[210:213], v[20:23]
	v_mfma_i32_16x16x64_i8 v[16:19], v[186:189], v[210:213], v[16:19]
	v_mfma_i32_16x16x64_i8 v[4:7], v[178:181], v[218:221], v[4:7]
	v_mfma_i32_16x16x64_i8 v[0:3], v[186:189], v[218:221], v[0:3]
	v_mfma_i32_16x16x64_i8 v[52:55], v[182:185], v[198:201], v[52:55]
	v_mfma_i32_16x16x64_i8 v[48:51], v[190:193], v[198:201], v[48:51]
	v_mfma_i32_16x16x64_i8 v[36:39], v[182:185], v[206:209], v[36:39]
	v_mfma_i32_16x16x64_i8 v[32:35], v[190:193], v[206:209], v[32:35]
	v_mfma_i32_16x16x64_i8 v[20:23], v[182:185], v[214:217], v[20:23]
	v_mfma_i32_16x16x64_i8 v[16:19], v[190:193], v[214:217], v[16:19]
	v_mfma_i32_16x16x64_i8 v[4:7], v[182:185], v[222:225], v[4:7]
	v_mfma_i32_16x16x64_i8 v[0:3], v[190:193], v[222:225], v[0:3]
	s_barrier
	s_add_i32 s65, 0, 0x18000
	v_add_u32_e32 v154, s65, v157
	s_add_i32 s66, 0, 0x1c000
	ds_read_b128 v[144:147], v154
	ds_read_b128 v[148:151], v154 offset:1024
	ds_read_b128 v[170:173], v154 offset:2048
	ds_read_b128 v[174:177], v154 offset:3072
	v_add_u32_e32 v154, s66, v157
	ds_read_b128 v[178:181], v154
	ds_read_b128 v[182:185], v154 offset:1024
	ds_read_b128 v[186:189], v154 offset:2048
	ds_read_b128 v[190:193], v154 offset:3072
	s_add_u32 s38, s38, 0x80000
	s_addc_u32 s39, s39, 0
	s_mov_b32 m0, s47
	v_lshl_add_u64 v[230:231], s[38:39], 0, v[128:129]
	ds_read_b128 v[194:197], v166 offset:32768
	ds_read_b128 v[198:201], v166 offset:33792
	ds_read_b128 v[202:205], v166 offset:34816
	ds_read_b128 v[206:209], v166 offset:35840
	ds_read_b128 v[210:213], v166 offset:36864
	ds_read_b128 v[214:217], v166 offset:37888
	ds_read_b128 v[218:221], v166 offset:38912
	ds_read_b128 v[222:225], v166 offset:39936
	global_load_lds_dwordx4 v[230:231], off
	v_lshl_add_u64 v[230:231], s[38:39], 0, v[132:133]
	s_mov_b32 m0, s48
	s_nop 0
	global_load_lds_dwordx4 v[230:231], off
	s_waitcnt vmcnt(8)
	s_waitcnt lgkmcnt(0)
	s_barrier
	s_waitcnt lgkmcnt(0)
	v_mfma_i32_16x16x64_i8 v[124:127], v[144:147], v[194:197], v[124:127]
	v_mfma_i32_16x16x64_i8 v[120:123], v[170:173], v[194:197], v[120:123]
	v_mfma_i32_16x16x64_i8 v[108:111], v[144:147], v[202:205], v[108:111]
	v_mfma_i32_16x16x64_i8 v[104:107], v[170:173], v[202:205], v[104:107]
	v_mfma_i32_16x16x64_i8 v[92:95], v[144:147], v[210:213], v[92:95]
	v_mfma_i32_16x16x64_i8 v[88:91], v[170:173], v[210:213], v[88:91]
	v_mfma_i32_16x16x64_i8 v[76:79], v[144:147], v[218:221], v[76:79]
	v_mfma_i32_16x16x64_i8 v[72:75], v[170:173], v[218:221], v[72:75]
	v_mfma_i32_16x16x64_i8 v[124:127], v[148:151], v[198:201], v[124:127]
	v_mfma_i32_16x16x64_i8 v[120:123], v[174:177], v[198:201], v[120:123]
	v_mfma_i32_16x16x64_i8 v[108:111], v[148:151], v[206:209], v[108:111]
	v_mfma_i32_16x16x64_i8 v[104:107], v[174:177], v[206:209], v[104:107]
	v_mfma_i32_16x16x64_i8 v[92:95], v[148:151], v[214:217], v[92:95]
	v_mfma_i32_16x16x64_i8 v[88:91], v[174:177], v[214:217], v[88:91]
	v_mfma_i32_16x16x64_i8 v[76:79], v[148:151], v[222:225], v[76:79]
	v_mfma_i32_16x16x64_i8 v[72:75], v[174:177], v[222:225], v[72:75]
	v_mfma_i32_16x16x64_i8 v[116:119], v[178:181], v[194:197], v[116:119]
	v_mfma_i32_16x16x64_i8 v[112:115], v[186:189], v[194:197], v[112:115]
	v_mfma_i32_16x16x64_i8 v[100:103], v[178:181], v[202:205], v[100:103]
	v_mfma_i32_16x16x64_i8 v[96:99], v[186:189], v[202:205], v[96:99]
	v_mfma_i32_16x16x64_i8 v[84:87], v[178:181], v[210:213], v[84:87]
	v_mfma_i32_16x16x64_i8 v[80:83], v[186:189], v[210:213], v[80:83]
	v_mfma_i32_16x16x64_i8 v[68:71], v[178:181], v[218:221], v[68:71]
	v_mfma_i32_16x16x64_i8 v[64:67], v[186:189], v[218:221], v[64:67]
	v_mfma_i32_16x16x64_i8 v[116:119], v[182:185], v[198:201], v[116:119]
	v_mfma_i32_16x16x64_i8 v[112:115], v[190:193], v[198:201], v[112:115]
	v_mfma_i32_16x16x64_i8 v[100:103], v[182:185], v[206:209], v[100:103]
	v_mfma_i32_16x16x64_i8 v[96:99], v[190:193], v[206:209], v[96:99]
	v_mfma_i32_16x16x64_i8 v[84:87], v[182:185], v[214:217], v[84:87]
	v_mfma_i32_16x16x64_i8 v[80:83], v[190:193], v[214:217], v[80:83]
	v_mfma_i32_16x16x64_i8 v[68:71], v[182:185], v[222:225], v[68:71]
	v_mfma_i32_16x16x64_i8 v[64:67], v[190:193], v[222:225], v[64:67]
	s_barrier
	s_add_i32 s38, s65, s44
	v_lshl_add_u64 v[152:153], v[152:153], 0, s[16:17]
	s_mov_b32 m0, s38
	ds_read_b128 v[194:197], v166 offset:49152
	ds_read_b128 v[198:201], v166 offset:50176
	ds_read_b128 v[202:205], v166 offset:51200
	ds_read_b128 v[206:209], v166 offset:52224
	ds_read_b128 v[210:213], v166 offset:53248
	ds_read_b128 v[214:217], v166 offset:54272
	ds_read_b128 v[218:221], v166 offset:55296
	ds_read_b128 v[222:225], v166 offset:56320
	global_load_lds_dwordx4 v[152:153], off
	s_add_i32 m0, s38, 0x2000
	s_add_u32 s6, s6, 0x80080
	v_lshl_add_u64 v[152:153], v[164:165], 0, s[16:17]
	s_addc_u32 s7, s7, 0
	s_add_i32 s38, s66, s44
	global_load_lds_dwordx4 v[152:153], off
	v_lshl_add_u64 v[152:153], s[6:7], 0, v[130:131]
	s_mov_b32 m0, s38
	s_nop 0
	global_load_lds_dwordx4 v[152:153], off
	v_lshl_add_u64 v[152:153], s[6:7], 0, v[134:135]
	s_add_i32 m0, s38, 0x2000
	s_nop 0
	global_load_lds_dwordx4 v[152:153], off
	v_lshl_add_u64 v[152:153], v[226:227], 0, s[16:17]
	s_mov_b32 m0, s50
	s_nop 0
	global_load_lds_dwordx4 v[152:153], off
	v_lshl_add_u64 v[152:153], v[228:229], 0, s[16:17]
	s_mov_b32 m0, s51
	s_nop 0
	global_load_lds_dwordx4 v[152:153], off
	s_waitcnt vmcnt(8)
	s_waitcnt lgkmcnt(0)
	s_barrier
	s_waitcnt lgkmcnt(0)
	v_mfma_i32_16x16x64_i8 v[60:63], v[144:147], v[194:197], v[60:63]
	v_mfma_i32_16x16x64_i8 v[56:59], v[170:173], v[194:197], v[56:59]
	v_mfma_i32_16x16x64_i8 v[44:47], v[144:147], v[202:205], v[44:47]
	v_mfma_i32_16x16x64_i8 v[40:43], v[170:173], v[202:205], v[40:43]
	v_mfma_i32_16x16x64_i8 v[28:31], v[144:147], v[210:213], v[28:31]
	v_mfma_i32_16x16x64_i8 v[24:27], v[170:173], v[210:213], v[24:27]
	v_mfma_i32_16x16x64_i8 v[12:15], v[144:147], v[218:221], v[12:15]
	v_mfma_i32_16x16x64_i8 v[8:11], v[170:173], v[218:221], v[8:11]
	v_mfma_i32_16x16x64_i8 v[60:63], v[148:151], v[198:201], v[60:63]
	v_mfma_i32_16x16x64_i8 v[56:59], v[174:177], v[198:201], v[56:59]
	v_mfma_i32_16x16x64_i8 v[44:47], v[148:151], v[206:209], v[44:47]
	v_mfma_i32_16x16x64_i8 v[40:43], v[174:177], v[206:209], v[40:43]
	v_mfma_i32_16x16x64_i8 v[28:31], v[148:151], v[214:217], v[28:31]
	v_mfma_i32_16x16x64_i8 v[24:27], v[174:177], v[214:217], v[24:27]
	v_mfma_i32_16x16x64_i8 v[12:15], v[148:151], v[222:225], v[12:15]
	v_mfma_i32_16x16x64_i8 v[8:11], v[174:177], v[222:225], v[8:11]
	v_mfma_i32_16x16x64_i8 v[52:55], v[178:181], v[194:197], v[52:55]
	v_mfma_i32_16x16x64_i8 v[48:51], v[186:189], v[194:197], v[48:51]
	v_mfma_i32_16x16x64_i8 v[36:39], v[178:181], v[202:205], v[36:39]
	v_mfma_i32_16x16x64_i8 v[32:35], v[186:189], v[202:205], v[32:35]
	v_mfma_i32_16x16x64_i8 v[20:23], v[178:181], v[210:213], v[20:23]
	v_mfma_i32_16x16x64_i8 v[16:19], v[186:189], v[210:213], v[16:19]
	v_mfma_i32_16x16x64_i8 v[4:7], v[178:181], v[218:221], v[4:7]
	v_mfma_i32_16x16x64_i8 v[0:3], v[186:189], v[218:221], v[0:3]
	v_mfma_i32_16x16x64_i8 v[52:55], v[182:185], v[198:201], v[52:55]
	v_mfma_i32_16x16x64_i8 v[48:51], v[190:193], v[198:201], v[48:51]
	v_mfma_i32_16x16x64_i8 v[36:39], v[182:185], v[206:209], v[36:39]
	v_mfma_i32_16x16x64_i8 v[32:35], v[190:193], v[206:209], v[32:35]
	v_mfma_i32_16x16x64_i8 v[20:23], v[182:185], v[214:217], v[20:23]
	v_mfma_i32_16x16x64_i8 v[16:19], v[190:193], v[214:217], v[16:19]
	v_mfma_i32_16x16x64_i8 v[4:7], v[182:185], v[222:225], v[4:7]
	v_mfma_i32_16x16x64_i8 v[0:3], v[190:193], v[222:225], v[0:3]
	s_barrier
	s_add_i32 s64, s64, 2
	s_add_u32 s62, s62, 0x100
	s_addc_u32 s63, s63, 0
	s_add_u32 s4, s4, 0x100
	s_addc_u32 s5, s5, 0
	s_cmp_gt_u32 s64, 29
	s_cbranch_scc0 .LBB0_550
	s_setprio 0
	s_and_b64 vcc, exec, s[18:19]
	s_cbranch_vccz .LBB0_553
	s_barrier

.LBB0_634:
	s_ashr_i32 s21, s20, 31
	s_mul_i32 s22, s20, 0x810000
	s_mov_b32 s23, 0
	s_add_u32 s22, s33, s22
	s_addc_u32 s23, s38, s23
	s_and_b64 s[24:25], s[4:5], exec
	s_cselect_b32 s21, s23, s35
	s_cselect_b32 s27, s22, s34
	s_ashr_i32 s19, s18, 31
	s_lshl_b64 s[24:25], s[18:19], 23
	s_add_u32 s24, s39, s24
	s_addc_u32 s25, s40, s25
	s_and_b64 s[36:37], s[4:5], exec
	s_cselect_b32 s19, s25, s31
	s_cselect_b32 s55, s24, s30
	s_add_u32 s56, s30, 0x100
	s_addc_u32 s57, s31, 0
	s_add_u32 s30, s34, 0x408080
	v_mov_b32_e32 v0, 0
	s_addc_u32 s31, s35, 0
	s_mov_b32 s58, -2
	s_waitcnt lgkmcnt(0)
	v_mov_b32_e32 v1, v0
	v_mov_b32_e32 v2, v0
	v_mov_b32_e32 v3, v0
	v_mov_b32_e32 v4, v0
	v_mov_b32_e32 v5, v0
	v_mov_b32_e32 v6, v0
	v_mov_b32_e32 v7, v0
	v_mov_b32_e32 v16, v0
	v_mov_b32_e32 v17, v0
	v_mov_b32_e32 v18, v0
	v_mov_b32_e32 v19, v0
	v_mov_b32_e32 v20, v0
	v_mov_b32_e32 v21, v0
	v_mov_b32_e32 v22, v0
	v_mov_b32_e32 v23, v0
	v_mov_b32_e32 v32, v0
	v_mov_b32_e32 v33, v0
	v_mov_b32_e32 v34, v0
	v_mov_b32_e32 v35, v0
	v_mov_b32_e32 v36, v0
	v_mov_b32_e32 v37, v0
	v_mov_b32_e32 v38, v0
	v_mov_b32_e32 v39, v0
	v_mov_b32_e32 v48, v0
	v_mov_b32_e32 v49, v0
	v_mov_b32_e32 v50, v0
	v_mov_b32_e32 v51, v0
	v_mov_b32_e32 v52, v0
	v_mov_b32_e32 v53, v0
	v_mov_b32_e32 v54, v0
	v_mov_b32_e32 v55, v0
	v_mov_b32_e32 v8, v0
	v_mov_b32_e32 v9, v0
	v_mov_b32_e32 v10, v0
	v_mov_b32_e32 v11, v0
	v_mov_b32_e32 v12, v0
	v_mov_b32_e32 v13, v0
	v_mov_b32_e32 v14, v0
	v_mov_b32_e32 v15, v0
	v_mov_b32_e32 v24, v0
	v_mov_b32_e32 v25, v0
	v_mov_b32_e32 v26, v0
	v_mov_b32_e32 v27, v0
	v_mov_b32_e32 v28, v0
	v_mov_b32_e32 v29, v0
	v_mov_b32_e32 v30, v0
	v_mov_b32_e32 v31, v0
	v_mov_b32_e32 v40, v0
	v_mov_b32_e32 v41, v0
	v_mov_b32_e32 v42, v0
	v_mov_b32_e32 v43, v0
	v_mov_b32_e32 v44, v0
	v_mov_b32_e32 v45, v0
	v_mov_b32_e32 v46, v0
	v_mov_b32_e32 v47, v0
	v_mov_b32_e32 v56, v0
	v_mov_b32_e32 v57, v0
	v_mov_b32_e32 v58, v0
	v_mov_b32_e32 v59, v0
	v_mov_b32_e32 v60, v0
	v_mov_b32_e32 v61, v0
	v_mov_b32_e32 v62, v0
	v_mov_b32_e32 v63, v0
	v_mov_b32_e32 v64, v0
	v_mov_b32_e32 v65, v0
	v_mov_b32_e32 v66, v0
	v_mov_b32_e32 v67, v0
	v_mov_b32_e32 v68, v0
	v_mov_b32_e32 v69, v0
	v_mov_b32_e32 v70, v0
	v_mov_b32_e32 v71, v0
	v_mov_b32_e32 v80, v0
	v_mov_b32_e32 v81, v0
	v_mov_b32_e32 v82, v0
	v_mov_b32_e32 v83, v0
	v_mov_b32_e32 v84, v0
	v_mov_b32_e32 v85, v0
	v_mov_b32_e32 v86, v0
	v_mov_b32_e32 v87, v0
	v_mov_b32_e32 v96, v0
	v_mov_b32_e32 v97, v0
	v_mov_b32_e32 v98, v0
	v_mov_b32_e32 v99, v0
	v_mov_b32_e32 v100, v0
	v_mov_b32_e32 v101, v0
	v_mov_b32_e32 v102, v0
	v_mov_b32_e32 v103, v0
	v_mov_b32_e32 v116, v0
	v_mov_b32_e32 v117, v0
	v_mov_b32_e32 v118, v0
	v_mov_b32_e32 v119, v0
	v_mov_b32_e32 v120, v0
	v_mov_b32_e32 v121, v0
	v_mov_b32_e32 v122, v0
	v_mov_b32_e32 v123, v0
	v_mov_b32_e32 v72, v0
	v_mov_b32_e32 v73, v0
	v_mov_b32_e32 v74, v0
	v_mov_b32_e32 v75, v0
	v_mov_b32_e32 v76, v0
	v_mov_b32_e32 v77, v0
	v_mov_b32_e32 v78, v0
	v_mov_b32_e32 v79, v0
	v_mov_b32_e32 v88, v0
	v_mov_b32_e32 v89, v0
	v_mov_b32_e32 v90, v0
	v_mov_b32_e32 v91, v0
	v_mov_b32_e32 v92, v0
	v_mov_b32_e32 v93, v0
	v_mov_b32_e32 v94, v0
	v_mov_b32_e32 v95, v0
	v_mov_b32_e32 v104, v0
	v_mov_b32_e32 v105, v0
	v_mov_b32_e32 v106, v0
	v_mov_b32_e32 v107, v0
	v_mov_b32_e32 v108, v0
	v_mov_b32_e32 v109, v0
	v_mov_b32_e32 v110, v0
	v_mov_b32_e32 v111, v0
	v_mov_b32_e32 v128, v0
	v_mov_b32_e32 v129, v0
	v_mov_b32_e32 v130, v0
	v_mov_b32_e32 v131, v0
	v_mov_b32_e32 v132, v0
	v_mov_b32_e32 v133, v0
	v_mov_b32_e32 v134, v0
	v_mov_b32_e32 v135, v0
	s_cmp_ge_u32 s81, 4
	s_cbranch_scc0 .Lsp_skip5
	s_setprio 1
.Lsp_skip5:
.LBB0_635:
	ds_read_b128 v[112:115], v193
	ds_read_b128 v[124:127], v193 offset:1024
	ds_read_b128 v[136:139], v193 offset:2048
	ds_read_b128 v[140:143], v193 offset:3072
	ds_read_b128 v[144:147], v194
	ds_read_b128 v[148:151], v194 offset:1024
	ds_read_b128 v[168:171], v194 offset:2048
	ds_read_b128 v[172:175], v194 offset:3072
	s_add_u32 s34, s30, 0xffbf8080
	s_addc_u32 s35, s31, -1
	s_cmpk_eq_i32 s58, 0xfc
	s_cselect_b32 s37, s21, s35
	s_cselect_b32 s36, s27, s34
	s_cselect_b32 s35, s19, s57
	s_cselect_b32 s34, s55, s56
	v_lshl_add_u64 v[188:189], s[30:31], 0, v[162:163]
	s_add_i32 m0, s29, 0xc000
	ds_read_b128 v[176:179], v195
	ds_read_b128 v[180:183], v195 offset:1024
	ds_read_b128 v[184:187], v195 offset:2048
	ds_read_b128 v[200:203], v195 offset:3072
	ds_read_b128 v[204:207], v195 offset:4096
	ds_read_b128 v[208:211], v195 offset:5120
	ds_read_b128 v[212:215], v195 offset:6144
	ds_read_b128 v[216:219], v195 offset:7168
	global_load_lds_dwordx4 v[188:189], off
	v_lshl_add_u64 v[188:189], s[30:31], 0, v[160:161]
	s_add_i32 m0, s29, 0xe000
	s_nop 0
	global_load_lds_dwordx4 v[188:189], off
	s_waitcnt vmcnt(8)
	s_waitcnt lgkmcnt(0)
	s_barrier
	s_waitcnt lgkmcnt(0)
	v_mfma_f32_16x16x32_bf16 v[132:135], v[112:115], v[176:179], v[132:135]
	v_mfma_f32_16x16x32_bf16 v[128:131], v[136:139], v[176:179], v[128:131]
	v_mfma_f32_16x16x32_bf16 v[108:111], v[112:115], v[184:187], v[108:111]
	v_mfma_f32_16x16x32_bf16 v[104:107], v[136:139], v[184:187], v[104:107]
	v_mfma_f32_16x16x32_bf16 v[92:95], v[112:115], v[204:207], v[92:95]
	v_mfma_f32_16x16x32_bf16 v[88:91], v[136:139], v[204:207], v[88:91]
	v_mfma_f32_16x16x32_bf16 v[76:79], v[112:115], v[212:215], v[76:79]
	v_mfma_f32_16x16x32_bf16 v[72:75], v[136:139], v[212:215], v[72:75]
	v_mfma_f32_16x16x32_bf16 v[132:135], v[124:127], v[180:183], v[132:135]
	v_mfma_f32_16x16x32_bf16 v[128:131], v[140:143], v[180:183], v[128:131]
	v_mfma_f32_16x16x32_bf16 v[108:111], v[124:127], v[200:203], v[108:111]
	v_mfma_f32_16x16x32_bf16 v[104:107], v[140:143], v[200:203], v[104:107]
	v_mfma_f32_16x16x32_bf16 v[92:95], v[124:127], v[208:211], v[92:95]
	v_mfma_f32_16x16x32_bf16 v[88:91], v[140:143], v[208:211], v[88:91]
	v_mfma_f32_16x16x32_bf16 v[76:79], v[124:127], v[216:219], v[76:79]
	v_mfma_f32_16x16x32_bf16 v[72:75], v[140:143], v[216:219], v[72:75]
	v_mfma_f32_16x16x32_bf16 v[120:123], v[144:147], v[176:179], v[120:123]
	v_mfma_f32_16x16x32_bf16 v[116:119], v[168:171], v[176:179], v[116:119]
	v_mfma_f32_16x16x32_bf16 v[100:103], v[144:147], v[184:187], v[100:103]
	v_mfma_f32_16x16x32_bf16 v[96:99], v[168:171], v[184:187], v[96:99]
	v_mfma_f32_16x16x32_bf16 v[84:87], v[144:147], v[204:207], v[84:87]
	v_mfma_f32_16x16x32_bf16 v[80:83], v[168:171], v[204:207], v[80:83]
	v_mfma_f32_16x16x32_bf16 v[68:71], v[144:147], v[212:215], v[68:71]
	v_mfma_f32_16x16x32_bf16 v[64:67], v[168:171], v[212:215], v[64:67]
	v_mfma_f32_16x16x32_bf16 v[120:123], v[148:151], v[180:183], v[120:123]
	v_mfma_f32_16x16x32_bf16 v[116:119], v[172:175], v[180:183], v[116:119]
	v_mfma_f32_16x16x32_bf16 v[100:103], v[148:151], v[200:203], v[100:103]
	v_mfma_f32_16x16x32_bf16 v[96:99], v[172:175], v[200:203], v[96:99]
	v_mfma_f32_16x16x32_bf16 v[84:87], v[148:151], v[208:211], v[84:87]
	v_mfma_f32_16x16x32_bf16 v[80:83], v[172:175], v[208:211], v[80:83]
	v_mfma_f32_16x16x32_bf16 v[68:71], v[148:151], v[216:219], v[68:71]
	v_mfma_f32_16x16x32_bf16 v[64:67], v[172:175], v[216:219], v[64:67]
	s_barrier
	s_add_i32 s59, s50, s41
	v_lshl_add_u64 v[188:189], s[34:35], 0, v[154:155]
	s_mov_b32 m0, s59
	ds_read_b128 v[176:179], v195 offset:16384
	ds_read_b128 v[180:183], v195 offset:17408
	ds_read_b128 v[184:187], v195 offset:18432
	ds_read_b128 v[200:203], v195 offset:19456
	ds_read_b128 v[204:207], v195 offset:20480
	ds_read_b128 v[208:211], v195 offset:21504
	ds_read_b128 v[212:215], v195 offset:22528
	ds_read_b128 v[216:219], v195 offset:23552
	global_load_lds_dwordx4 v[188:189], off
	s_add_i32 m0, s59, 0x2000
	s_add_u32 s60, s34, 0x400000
	v_lshl_add_u64 v[220:221], s[34:35], 0, v[158:159]
	s_addc_u32 s61, s35, 0
	s_add_i32 s59, s51, s41
	global_load_lds_dwordx4 v[220:221], off
	v_lshl_add_u64 v[222:223], s[60:61], 0, v[154:155]
	s_mov_b32 m0, s59
	v_lshl_add_u64 v[224:225], s[36:37], 0, v[156:157]
	global_load_lds_dwordx4 v[222:223], off
	v_lshl_add_u64 v[222:223], s[60:61], 0, v[158:159]
	s_add_i32 m0, s59, 0x2000
	s_nop 0
	global_load_lds_dwordx4 v[222:223], off
	v_lshl_add_u64 v[222:223], s[36:37], 0, v[152:153]
	s_mov_b32 m0, s29
	s_nop 0
	global_load_lds_dwordx4 v[222:223], off
	s_mov_b32 m0, s42
	s_nop 0
	global_load_lds_dwordx4 v[224:225], off
	s_waitcnt vmcnt(8)
	s_waitcnt lgkmcnt(0)
	s_barrier
	s_waitcnt lgkmcnt(0)
	v_mfma_f32_16x16x32_bf16 v[60:63], v[112:115], v[176:179], v[60:63]
	v_mfma_f32_16x16x32_bf16 v[56:59], v[136:139], v[176:179], v[56:59]
	v_mfma_f32_16x16x32_bf16 v[44:47], v[112:115], v[184:187], v[44:47]
	v_mfma_f32_16x16x32_bf16 v[40:43], v[136:139], v[184:187], v[40:43]
	v_mfma_f32_16x16x32_bf16 v[28:31], v[112:115], v[204:207], v[28:31]
	v_mfma_f32_16x16x32_bf16 v[24:27], v[136:139], v[204:207], v[24:27]
	v_mfma_f32_16x16x32_bf16 v[12:15], v[112:115], v[212:215], v[12:15]
	v_mfma_f32_16x16x32_bf16 v[8:11], v[136:139], v[212:215], v[8:11]
	v_mfma_f32_16x16x32_bf16 v[60:63], v[124:127], v[180:183], v[60:63]
	v_mfma_f32_16x16x32_bf16 v[56:59], v[140:143], v[180:183], v[56:59]
	v_mfma_f32_16x16x32_bf16 v[44:47], v[124:127], v[200:203], v[44:47]
	v_mfma_f32_16x16x32_bf16 v[40:43], v[140:143], v[200:203], v[40:43]
	v_mfma_f32_16x16x32_bf16 v[28:31], v[124:127], v[208:211], v[28:31]
	v_mfma_f32_16x16x32_bf16 v[24:27], v[140:143], v[208:211], v[24:27]
	v_mfma_f32_16x16x32_bf16 v[12:15], v[124:127], v[216:219], v[12:15]
	v_mfma_f32_16x16x32_bf16 v[8:11], v[140:143], v[216:219], v[8:11]
	v_mfma_f32_16x16x32_bf16 v[52:55], v[144:147], v[176:179], v[52:55]
	v_mfma_f32_16x16x32_bf16 v[48:51], v[168:171], v[176:179], v[48:51]
	v_mfma_f32_16x16x32_bf16 v[36:39], v[144:147], v[184:187], v[36:39]
	v_mfma_f32_16x16x32_bf16 v[32:35], v[168:171], v[184:187], v[32:35]
	v_mfma_f32_16x16x32_bf16 v[20:23], v[144:147], v[204:207], v[20:23]
	v_mfma_f32_16x16x32_bf16 v[16:19], v[168:171], v[204:207], v[16:19]
	v_mfma_f32_16x16x32_bf16 v[4:7], v[144:147], v[212:215], v[4:7]
	v_mfma_f32_16x16x32_bf16 v[0:3], v[168:171], v[212:215], v[0:3]
	v_mfma_f32_16x16x32_bf16 v[52:55], v[148:151], v[180:183], v[52:55]
	v_mfma_f32_16x16x32_bf16 v[48:51], v[172:175], v[180:183], v[48:51]
	v_mfma_f32_16x16x32_bf16 v[36:39], v[148:151], v[200:203], v[36:39]
	v_mfma_f32_16x16x32_bf16 v[32:35], v[172:175], v[200:203], v[32:35]
	v_mfma_f32_16x16x32_bf16 v[20:23], v[148:151], v[208:211], v[20:23]
	v_mfma_f32_16x16x32_bf16 v[16:19], v[172:175], v[208:211], v[16:19]
	v_mfma_f32_16x16x32_bf16 v[4:7], v[148:151], v[216:219], v[4:7]
	v_mfma_f32_16x16x32_bf16 v[0:3], v[172:175], v[216:219], v[0:3]
	s_barrier
	s_add_i32 s59, 0, 0x18000
	s_add_i32 s60, 0, 0x1c000
	v_add_u32_e32 v140, s59, v191
	v_add_u32_e32 v172, s60, v191
	ds_read_b128 v[112:115], v140
	ds_read_b128 v[124:127], v140 offset:1024
	ds_read_b128 v[136:139], v140 offset:2048
	ds_read_b128 v[140:143], v140 offset:3072
	ds_read_b128 v[144:147], v172
	ds_read_b128 v[148:151], v172 offset:1024
	ds_read_b128 v[168:171], v172 offset:2048
	ds_read_b128 v[172:175], v172 offset:3072
	s_add_u32 s36, s36, 0x408000
	s_addc_u32 s37, s37, 0
	s_mov_b32 m0, s43
	v_lshl_add_u64 v[226:227], s[36:37], 0, v[152:153]
	ds_read_b128 v[176:179], v195 offset:32768
	ds_read_b128 v[180:183], v195 offset:33792
	ds_read_b128 v[184:187], v195 offset:34816
	ds_read_b128 v[200:203], v195 offset:35840
	ds_read_b128 v[204:207], v195 offset:36864
	ds_read_b128 v[208:211], v195 offset:37888
	ds_read_b128 v[212:215], v195 offset:38912
	ds_read_b128 v[216:219], v195 offset:39936
	global_load_lds_dwordx4 v[226:227], off
	v_lshl_add_u64 v[226:227], s[36:37], 0, v[156:157]
	s_mov_b32 m0, s44
	s_nop 0
	global_load_lds_dwordx4 v[226:227], off
	s_waitcnt vmcnt(8)
	s_waitcnt lgkmcnt(0)
	s_barrier
	s_waitcnt lgkmcnt(0)
	v_mfma_f32_16x16x32_bf16 v[132:135], v[112:115], v[176:179], v[132:135]
	v_mfma_f32_16x16x32_bf16 v[128:131], v[136:139], v[176:179], v[128:131]
	v_mfma_f32_16x16x32_bf16 v[108:111], v[112:115], v[184:187], v[108:111]
	v_mfma_f32_16x16x32_bf16 v[104:107], v[136:139], v[184:187], v[104:107]
	v_mfma_f32_16x16x32_bf16 v[92:95], v[112:115], v[204:207], v[92:95]
	v_mfma_f32_16x16x32_bf16 v[88:91], v[136:139], v[204:207], v[88:91]
	v_mfma_f32_16x16x32_bf16 v[76:79], v[112:115], v[212:215], v[76:79]
	v_mfma_f32_16x16x32_bf16 v[72:75], v[136:139], v[212:215], v[72:75]
	v_mfma_f32_16x16x32_bf16 v[132:135], v[124:127], v[180:183], v[132:135]
	v_mfma_f32_16x16x32_bf16 v[128:131], v[140:143], v[180:183], v[128:131]
	v_mfma_f32_16x16x32_bf16 v[108:111], v[124:127], v[200:203], v[108:111]
	v_mfma_f32_16x16x32_bf16 v[104:107], v[140:143], v[200:203], v[104:107]
	v_mfma_f32_16x16x32_bf16 v[92:95], v[124:127], v[208:211], v[92:95]
	v_mfma_f32_16x16x32_bf16 v[88:91], v[140:143], v[208:211], v[88:91]
	v_mfma_f32_16x16x32_bf16 v[76:79], v[124:127], v[216:219], v[76:79]
	v_mfma_f32_16x16x32_bf16 v[72:75], v[140:143], v[216:219], v[72:75]
	v_mfma_f32_16x16x32_bf16 v[120:123], v[144:147], v[176:179], v[120:123]
	v_mfma_f32_16x16x32_bf16 v[116:119], v[168:171], v[176:179], v[116:119]
	v_mfma_f32_16x16x32_bf16 v[100:103], v[144:147], v[184:187], v[100:103]
	v_mfma_f32_16x16x32_bf16 v[96:99], v[168:171], v[184:187], v[96:99]
	v_mfma_f32_16x16x32_bf16 v[84:87], v[144:147], v[204:207], v[84:87]
	v_mfma_f32_16x16x32_bf16 v[80:83], v[168:171], v[204:207], v[80:83]
	v_mfma_f32_16x16x32_bf16 v[68:71], v[144:147], v[212:215], v[68:71]
	v_mfma_f32_16x16x32_bf16 v[64:67], v[168:171], v[212:215], v[64:67]
	v_mfma_f32_16x16x32_bf16 v[120:123], v[148:151], v[180:183], v[120:123]
	v_mfma_f32_16x16x32_bf16 v[116:119], v[172:175], v[180:183], v[116:119]
	v_mfma_f32_16x16x32_bf16 v[100:103], v[148:151], v[200:203], v[100:103]
	v_mfma_f32_16x16x32_bf16 v[96:99], v[172:175], v[200:203], v[96:99]
	v_mfma_f32_16x16x32_bf16 v[84:87], v[148:151], v[208:211], v[84:87]
	v_mfma_f32_16x16x32_bf16 v[80:83], v[172:175], v[208:211], v[80:83]
	v_mfma_f32_16x16x32_bf16 v[68:71], v[148:151], v[216:219], v[68:71]
	v_mfma_f32_16x16x32_bf16 v[64:67], v[172:175], v[216:219], v[64:67]
	s_barrier
	s_add_i32 s36, s59, s41
	v_lshl_add_u64 v[188:189], v[188:189], 0, s[14:15]
	s_mov_b32 m0, s36
	ds_read_b128 v[176:179], v195 offset:49152
	ds_read_b128 v[180:183], v195 offset:50176
	ds_read_b128 v[184:187], v195 offset:51200
	ds_read_b128 v[200:203], v195 offset:52224
	ds_read_b128 v[204:207], v195 offset:53248
	ds_read_b128 v[208:211], v195 offset:54272
	ds_read_b128 v[212:215], v195 offset:55296
	ds_read_b128 v[216:219], v195 offset:56320
	global_load_lds_dwordx4 v[188:189], off
	s_add_i32 m0, s36, 0x2000
	s_add_u32 s34, s34, 0x400080
	v_lshl_add_u64 v[188:189], v[220:221], 0, s[14:15]
	s_addc_u32 s35, s35, 0
	s_add_i32 s36, s60, s41
	global_load_lds_dwordx4 v[188:189], off
	v_lshl_add_u64 v[188:189], s[34:35], 0, v[154:155]
	s_mov_b32 m0, s36
	s_nop 0
	global_load_lds_dwordx4 v[188:189], off
	v_lshl_add_u64 v[188:189], s[34:35], 0, v[158:159]
	s_add_i32 m0, s36, 0x2000
	s_nop 0
	global_load_lds_dwordx4 v[188:189], off
	v_lshl_add_u64 v[188:189], v[222:223], 0, s[14:15]
	s_mov_b32 m0, s46
	s_nop 0
	global_load_lds_dwordx4 v[188:189], off
	v_lshl_add_u64 v[188:189], v[224:225], 0, s[14:15]
	s_mov_b32 m0, s47
	s_nop 0
	global_load_lds_dwordx4 v[188:189], off
	s_waitcnt vmcnt(8)
	s_waitcnt lgkmcnt(0)
	s_barrier
	s_waitcnt lgkmcnt(0)
	v_mfma_f32_16x16x32_bf16 v[60:63], v[112:115], v[176:179], v[60:63]
	v_mfma_f32_16x16x32_bf16 v[56:59], v[136:139], v[176:179], v[56:59]
	v_mfma_f32_16x16x32_bf16 v[44:47], v[112:115], v[184:187], v[44:47]
	v_mfma_f32_16x16x32_bf16 v[40:43], v[136:139], v[184:187], v[40:43]
	v_mfma_f32_16x16x32_bf16 v[28:31], v[112:115], v[204:207], v[28:31]
	v_mfma_f32_16x16x32_bf16 v[24:27], v[136:139], v[204:207], v[24:27]
	v_mfma_f32_16x16x32_bf16 v[12:15], v[112:115], v[212:215], v[12:15]
	v_mfma_f32_16x16x32_bf16 v[8:11], v[136:139], v[212:215], v[8:11]
	v_mfma_f32_16x16x32_bf16 v[60:63], v[124:127], v[180:183], v[60:63]
	v_mfma_f32_16x16x32_bf16 v[56:59], v[140:143], v[180:183], v[56:59]
	v_mfma_f32_16x16x32_bf16 v[44:47], v[124:127], v[200:203], v[44:47]
	v_mfma_f32_16x16x32_bf16 v[40:43], v[140:143], v[200:203], v[40:43]
	v_mfma_f32_16x16x32_bf16 v[28:31], v[124:127], v[208:211], v[28:31]
	v_mfma_f32_16x16x32_bf16 v[24:27], v[140:143], v[208:211], v[24:27]
	v_mfma_f32_16x16x32_bf16 v[12:15], v[124:127], v[216:219], v[12:15]
	v_mfma_f32_16x16x32_bf16 v[8:11], v[140:143], v[216:219], v[8:11]
	v_mfma_f32_16x16x32_bf16 v[52:55], v[144:147], v[176:179], v[52:55]
	v_mfma_f32_16x16x32_bf16 v[48:51], v[168:171], v[176:179], v[48:51]
	v_mfma_f32_16x16x32_bf16 v[36:39], v[144:147], v[184:187], v[36:39]
	v_mfma_f32_16x16x32_bf16 v[32:35], v[168:171], v[184:187], v[32:35]
	v_mfma_f32_16x16x32_bf16 v[20:23], v[144:147], v[204:207], v[20:23]
	v_mfma_f32_16x16x32_bf16 v[16:19], v[168:171], v[204:207], v[16:19]
	v_mfma_f32_16x16x32_bf16 v[4:7], v[144:147], v[212:215], v[4:7]
	v_mfma_f32_16x16x32_bf16 v[0:3], v[168:171], v[212:215], v[0:3]
	v_mfma_f32_16x16x32_bf16 v[52:55], v[148:151], v[180:183], v[52:55]
	v_mfma_f32_16x16x32_bf16 v[48:51], v[172:175], v[180:183], v[48:51]
	v_mfma_f32_16x16x32_bf16 v[36:39], v[148:151], v[200:203], v[36:39]
	v_mfma_f32_16x16x32_bf16 v[32:35], v[172:175], v[200:203], v[32:35]
	v_mfma_f32_16x16x32_bf16 v[20:23], v[148:151], v[208:211], v[20:23]
	v_mfma_f32_16x16x32_bf16 v[16:19], v[172:175], v[208:211], v[16:19]
	v_mfma_f32_16x16x32_bf16 v[4:7], v[148:151], v[216:219], v[4:7]
	v_mfma_f32_16x16x32_bf16 v[0:3], v[172:175], v[216:219], v[0:3]
	s_barrier
	s_add_i32 s58, s58, 2
	s_add_u32 s56, s56, 0x100
	s_addc_u32 s57, s57, 0
	s_add_u32 s30, s30, 0x100
	s_addc_u32 s31, s31, 0
	s_cmpk_gt_u32 s58, 0xfd
	s_cbranch_scc0 .LBB0_635
	s_setprio 0
	s_and_b64 vcc, exec, s[16:17]
	s_cbranch_vccz .LBB0_638
	s_barrier

.LBB0_725:
	s_ashr_i32 s23, s22, 31
	s_lshl_b64 s[24:25], s[22:23], 20
	s_add_u32 s24, s30, s24
	s_addc_u32 s25, s31, s25
	s_and_b64 s[26:27], s[2:3], exec
	s_cselect_b32 s1, s25, s7
	s_cselect_b32 s23, s24, s6
	s_ashr_i32 s21, s20, 31
	s_lshl_b64 s[26:27], s[20:21], 20
	s_add_u32 s26, s33, s26
	s_addc_u32 s27, s34, s27
	s_and_b64 s[28:29], s[2:3], exec
	s_cselect_b32 s21, s27, s5
	s_cselect_b32 s51, s26, s4
	s_add_u32 s52, s4, 0x100
	s_addc_u32 s53, s5, 0
	s_add_u32 s4, s6, 0x80080
	v_mov_b32_e32 v0, 0
	s_addc_u32 s5, s7, 0
	s_mov_b32 s54, -2
	v_mov_b32_e32 v1, v0
	v_mov_b32_e32 v2, v0
	v_mov_b32_e32 v3, v0
	v_mov_b32_e32 v4, v0
	v_mov_b32_e32 v5, v0
	v_mov_b32_e32 v6, v0
	v_mov_b32_e32 v7, v0
	v_mov_b32_e32 v16, v0
	v_mov_b32_e32 v17, v0
	v_mov_b32_e32 v18, v0
	v_mov_b32_e32 v19, v0
	v_mov_b32_e32 v20, v0
	v_mov_b32_e32 v21, v0
	v_mov_b32_e32 v22, v0
	v_mov_b32_e32 v23, v0
	v_mov_b32_e32 v32, v0
	v_mov_b32_e32 v33, v0
	v_mov_b32_e32 v34, v0
	v_mov_b32_e32 v35, v0
	v_mov_b32_e32 v36, v0
	v_mov_b32_e32 v37, v0
	v_mov_b32_e32 v38, v0
	v_mov_b32_e32 v39, v0
	v_mov_b32_e32 v48, v0
	v_mov_b32_e32 v49, v0
	v_mov_b32_e32 v50, v0
	v_mov_b32_e32 v51, v0
	v_mov_b32_e32 v52, v0
	v_mov_b32_e32 v53, v0
	v_mov_b32_e32 v54, v0
	v_mov_b32_e32 v55, v0
	v_mov_b32_e32 v8, v0
	v_mov_b32_e32 v9, v0
	v_mov_b32_e32 v10, v0
	v_mov_b32_e32 v11, v0
	v_mov_b32_e32 v12, v0
	v_mov_b32_e32 v13, v0
	v_mov_b32_e32 v14, v0
	v_mov_b32_e32 v15, v0
	v_mov_b32_e32 v24, v0
	v_mov_b32_e32 v25, v0
	v_mov_b32_e32 v26, v0
	v_mov_b32_e32 v27, v0
	v_mov_b32_e32 v28, v0
	v_mov_b32_e32 v29, v0
	v_mov_b32_e32 v30, v0
	v_mov_b32_e32 v31, v0
	v_mov_b32_e32 v40, v0
	v_mov_b32_e32 v41, v0
	v_mov_b32_e32 v42, v0
	v_mov_b32_e32 v43, v0
	v_mov_b32_e32 v44, v0
	v_mov_b32_e32 v45, v0
	v_mov_b32_e32 v46, v0
	v_mov_b32_e32 v47, v0
	v_mov_b32_e32 v56, v0
	v_mov_b32_e32 v57, v0
	v_mov_b32_e32 v58, v0
	v_mov_b32_e32 v59, v0
	v_mov_b32_e32 v60, v0
	v_mov_b32_e32 v61, v0
	v_mov_b32_e32 v62, v0
	v_mov_b32_e32 v63, v0
	v_mov_b32_e32 v64, v0
	v_mov_b32_e32 v65, v0
	v_mov_b32_e32 v66, v0
	v_mov_b32_e32 v67, v0
	v_mov_b32_e32 v68, v0
	v_mov_b32_e32 v69, v0
	v_mov_b32_e32 v70, v0
	v_mov_b32_e32 v71, v0
	v_mov_b32_e32 v80, v0
	v_mov_b32_e32 v81, v0
	v_mov_b32_e32 v82, v0
	v_mov_b32_e32 v83, v0
	v_mov_b32_e32 v84, v0
	v_mov_b32_e32 v85, v0
	v_mov_b32_e32 v86, v0
	v_mov_b32_e32 v87, v0
	v_mov_b32_e32 v96, v0
	v_mov_b32_e32 v97, v0
	v_mov_b32_e32 v98, v0
	v_mov_b32_e32 v99, v0
	v_mov_b32_e32 v100, v0
	v_mov_b32_e32 v101, v0
	v_mov_b32_e32 v102, v0
	v_mov_b32_e32 v103, v0
	v_mov_b32_e32 v112, v0
	v_mov_b32_e32 v113, v0
	v_mov_b32_e32 v114, v0
	v_mov_b32_e32 v115, v0
	v_mov_b32_e32 v116, v0
	v_mov_b32_e32 v117, v0
	v_mov_b32_e32 v118, v0
	v_mov_b32_e32 v119, v0
	v_mov_b32_e32 v72, v0
	v_mov_b32_e32 v73, v0
	v_mov_b32_e32 v74, v0
	v_mov_b32_e32 v75, v0
	v_mov_b32_e32 v76, v0
	v_mov_b32_e32 v77, v0
	v_mov_b32_e32 v78, v0
	v_mov_b32_e32 v79, v0
	v_mov_b32_e32 v88, v0
	v_mov_b32_e32 v89, v0
	v_mov_b32_e32 v90, v0
	v_mov_b32_e32 v91, v0
	v_mov_b32_e32 v92, v0
	v_mov_b32_e32 v93, v0
	v_mov_b32_e32 v94, v0
	v_mov_b32_e32 v95, v0
	v_mov_b32_e32 v104, v0
	v_mov_b32_e32 v105, v0
	v_mov_b32_e32 v106, v0
	v_mov_b32_e32 v107, v0
	v_mov_b32_e32 v108, v0
	v_mov_b32_e32 v109, v0
	v_mov_b32_e32 v110, v0
	v_mov_b32_e32 v111, v0
	v_mov_b32_e32 v120, v0
	v_mov_b32_e32 v121, v0
	v_mov_b32_e32 v122, v0
	v_mov_b32_e32 v123, v0
	v_mov_b32_e32 v124, v0
	v_mov_b32_e32 v125, v0
	v_mov_b32_e32 v126, v0
	v_mov_b32_e32 v127, v0
	s_cmp_ge_u32 s81, 4
	s_cbranch_scc0 .Lsp_skip6
	s_setprio 1
.Lsp_skip6:
.LBB0_726:
	ds_read_b128 v[144:147], v161
	ds_read_b128 v[148:151], v161 offset:1024
	ds_read_b128 v[168:171], v161 offset:2048
	ds_read_b128 v[172:175], v161 offset:3072
	ds_read_b128 v[176:179], v163
	ds_read_b128 v[180:183], v163 offset:1024
	ds_read_b128 v[184:187], v163 offset:2048
	ds_read_b128 v[188:191], v163 offset:3072
	s_add_u32 s6, s4, 0xfff80080
	s_addc_u32 s7, s5, -1
	s_cmp_eq_u32 s54, 28
	s_cselect_b32 s29, s1, s7
	s_cselect_b32 s28, s23, s6
	s_cselect_b32 s7, s21, s53
	s_cselect_b32 s6, s51, s52
	v_lshl_add_u64 v[152:153], s[4:5], 0, v[138:139]
	s_add_i32 m0, s38, 0xc000
	ds_read_b128 v[192:195], v165
	ds_read_b128 v[196:199], v165 offset:1024
	ds_read_b128 v[200:203], v165 offset:2048
	ds_read_b128 v[204:207], v165 offset:3072
	ds_read_b128 v[208:211], v165 offset:4096
	ds_read_b128 v[212:215], v165 offset:5120
	ds_read_b128 v[216:219], v165 offset:6144
	ds_read_b128 v[220:223], v165 offset:7168
	global_load_lds_dwordx4 v[152:153], off
	v_lshl_add_u64 v[152:153], s[4:5], 0, v[136:137]
	s_add_i32 m0, s38, 0xe000
	s_nop 0
	global_load_lds_dwordx4 v[152:153], off
	s_waitcnt vmcnt(8)
	s_waitcnt lgkmcnt(0)
	s_barrier
	s_waitcnt lgkmcnt(0)
	v_mfma_i32_16x16x64_i8 v[124:127], v[144:147], v[192:195], v[124:127]
	v_mfma_i32_16x16x64_i8 v[120:123], v[168:171], v[192:195], v[120:123]
	v_mfma_i32_16x16x64_i8 v[108:111], v[144:147], v[200:203], v[108:111]
	v_mfma_i32_16x16x64_i8 v[104:107], v[168:171], v[200:203], v[104:107]
	v_mfma_i32_16x16x64_i8 v[92:95], v[144:147], v[208:211], v[92:95]
	v_mfma_i32_16x16x64_i8 v[88:91], v[168:171], v[208:211], v[88:91]
	v_mfma_i32_16x16x64_i8 v[76:79], v[144:147], v[216:219], v[76:79]
	v_mfma_i32_16x16x64_i8 v[72:75], v[168:171], v[216:219], v[72:75]
	v_mfma_i32_16x16x64_i8 v[124:127], v[148:151], v[196:199], v[124:127]
	v_mfma_i32_16x16x64_i8 v[120:123], v[172:175], v[196:199], v[120:123]
	v_mfma_i32_16x16x64_i8 v[108:111], v[148:151], v[204:207], v[108:111]
	v_mfma_i32_16x16x64_i8 v[104:107], v[172:175], v[204:207], v[104:107]
	v_mfma_i32_16x16x64_i8 v[92:95], v[148:151], v[212:215], v[92:95]
	v_mfma_i32_16x16x64_i8 v[88:91], v[172:175], v[212:215], v[88:91]
	v_mfma_i32_16x16x64_i8 v[76:79], v[148:151], v[220:223], v[76:79]
	v_mfma_i32_16x16x64_i8 v[72:75], v[172:175], v[220:223], v[72:75]
	v_mfma_i32_16x16x64_i8 v[116:119], v[176:179], v[192:195], v[116:119]
	v_mfma_i32_16x16x64_i8 v[112:115], v[184:187], v[192:195], v[112:115]
	v_mfma_i32_16x16x64_i8 v[100:103], v[176:179], v[200:203], v[100:103]
	v_mfma_i32_16x16x64_i8 v[96:99], v[184:187], v[200:203], v[96:99]
	v_mfma_i32_16x16x64_i8 v[84:87], v[176:179], v[208:211], v[84:87]
	v_mfma_i32_16x16x64_i8 v[80:83], v[184:187], v[208:211], v[80:83]
	v_mfma_i32_16x16x64_i8 v[68:71], v[176:179], v[216:219], v[68:71]
	v_mfma_i32_16x16x64_i8 v[64:67], v[184:187], v[216:219], v[64:67]
	v_mfma_i32_16x16x64_i8 v[116:119], v[180:183], v[196:199], v[116:119]
	v_mfma_i32_16x16x64_i8 v[112:115], v[188:191], v[196:199], v[112:115]
	v_mfma_i32_16x16x64_i8 v[100:103], v[180:183], v[204:207], v[100:103]
	v_mfma_i32_16x16x64_i8 v[96:99], v[188:191], v[204:207], v[96:99]
	v_mfma_i32_16x16x64_i8 v[84:87], v[180:183], v[212:215], v[84:87]
	v_mfma_i32_16x16x64_i8 v[80:83], v[188:191], v[212:215], v[80:83]
	v_mfma_i32_16x16x64_i8 v[68:71], v[180:183], v[220:223], v[68:71]
	v_mfma_i32_16x16x64_i8 v[64:67], v[188:191], v[220:223], v[64:67]
	s_barrier
	s_add_i32 s55, s46, s35
	v_lshl_add_u64 v[152:153], s[6:7], 0, v[132:133]
	s_mov_b32 m0, s55
	ds_read_b128 v[192:195], v165 offset:16384
	ds_read_b128 v[196:199], v165 offset:17408
	ds_read_b128 v[200:203], v165 offset:18432
	ds_read_b128 v[204:207], v165 offset:19456
	ds_read_b128 v[208:211], v165 offset:20480
	ds_read_b128 v[212:215], v165 offset:21504
	ds_read_b128 v[216:219], v165 offset:22528
	ds_read_b128 v[220:223], v165 offset:23552
	global_load_lds_dwordx4 v[152:153], off
	s_add_i32 m0, s55, 0x2000
	s_add_u32 s56, s6, 0x80000
	v_lshl_add_u64 v[224:225], s[6:7], 0, v[128:129]
	s_addc_u32 s57, s7, 0
	s_add_i32 s55, s47, s35
	global_load_lds_dwordx4 v[224:225], off
	v_lshl_add_u64 v[226:227], s[56:57], 0, v[132:133]
	s_mov_b32 m0, s55
	v_lshl_add_u64 v[228:229], s[28:29], 0, v[130:131]
	global_load_lds_dwordx4 v[226:227], off
	v_lshl_add_u64 v[226:227], s[56:57], 0, v[128:129]
	s_add_i32 m0, s55, 0x2000
	s_nop 0
	global_load_lds_dwordx4 v[226:227], off
	v_lshl_add_u64 v[226:227], s[28:29], 0, v[134:135]
	s_mov_b32 m0, s38
	s_nop 0
	global_load_lds_dwordx4 v[226:227], off
	s_mov_b32 m0, s39
	s_nop 0
	global_load_lds_dwordx4 v[228:229], off
	s_waitcnt vmcnt(8)
	s_waitcnt lgkmcnt(0)
	s_barrier
	s_waitcnt lgkmcnt(0)
	v_mfma_i32_16x16x64_i8 v[60:63], v[144:147], v[192:195], v[60:63]
	v_mfma_i32_16x16x64_i8 v[56:59], v[168:171], v[192:195], v[56:59]
	v_mfma_i32_16x16x64_i8 v[44:47], v[144:147], v[200:203], v[44:47]
	v_mfma_i32_16x16x64_i8 v[40:43], v[168:171], v[200:203], v[40:43]
	v_mfma_i32_16x16x64_i8 v[28:31], v[144:147], v[208:211], v[28:31]
	v_mfma_i32_16x16x64_i8 v[24:27], v[168:171], v[208:211], v[24:27]
	v_mfma_i32_16x16x64_i8 v[12:15], v[144:147], v[216:219], v[12:15]
	v_mfma_i32_16x16x64_i8 v[8:11], v[168:171], v[216:219], v[8:11]
	v_mfma_i32_16x16x64_i8 v[60:63], v[148:151], v[196:199], v[60:63]
	v_mfma_i32_16x16x64_i8 v[56:59], v[172:175], v[196:199], v[56:59]
	v_mfma_i32_16x16x64_i8 v[44:47], v[148:151], v[204:207], v[44:47]
	v_mfma_i32_16x16x64_i8 v[40:43], v[172:175], v[204:207], v[40:43]
	v_mfma_i32_16x16x64_i8 v[28:31], v[148:151], v[212:215], v[28:31]
	v_mfma_i32_16x16x64_i8 v[24:27], v[172:175], v[212:215], v[24:27]
	v_mfma_i32_16x16x64_i8 v[12:15], v[148:151], v[220:223], v[12:15]
	v_mfma_i32_16x16x64_i8 v[8:11], v[172:175], v[220:223], v[8:11]
	v_mfma_i32_16x16x64_i8 v[52:55], v[176:179], v[192:195], v[52:55]
	v_mfma_i32_16x16x64_i8 v[48:51], v[184:187], v[192:195], v[48:51]
	v_mfma_i32_16x16x64_i8 v[36:39], v[176:179], v[200:203], v[36:39]
	v_mfma_i32_16x16x64_i8 v[32:35], v[184:187], v[200:203], v[32:35]
	v_mfma_i32_16x16x64_i8 v[20:23], v[176:179], v[208:211], v[20:23]
	v_mfma_i32_16x16x64_i8 v[16:19], v[184:187], v[208:211], v[16:19]
	v_mfma_i32_16x16x64_i8 v[4:7], v[176:179], v[216:219], v[4:7]
	v_mfma_i32_16x16x64_i8 v[0:3], v[184:187], v[216:219], v[0:3]
	v_mfma_i32_16x16x64_i8 v[52:55], v[180:183], v[196:199], v[52:55]
	v_mfma_i32_16x16x64_i8 v[48:51], v[188:191], v[196:199], v[48:51]
	v_mfma_i32_16x16x64_i8 v[36:39], v[180:183], v[204:207], v[36:39]
	v_mfma_i32_16x16x64_i8 v[32:35], v[188:191], v[204:207], v[32:35]
	v_mfma_i32_16x16x64_i8 v[20:23], v[180:183], v[212:215], v[20:23]
	v_mfma_i32_16x16x64_i8 v[16:19], v[188:191], v[212:215], v[16:19]
	v_mfma_i32_16x16x64_i8 v[4:7], v[180:183], v[220:223], v[4:7]
	v_mfma_i32_16x16x64_i8 v[0:3], v[188:191], v[220:223], v[0:3]
	s_barrier
	s_add_i32 s55, 0, 0x18000
	v_add_u32_e32 v154, s55, v157
	s_add_i32 s56, 0, 0x1c000
	ds_read_b128 v[144:147], v154
	ds_read_b128 v[148:151], v154 offset:1024
	ds_read_b128 v[168:171], v154 offset:2048
	ds_read_b128 v[172:175], v154 offset:3072
	v_add_u32_e32 v154, s56, v157
	ds_read_b128 v[176:179], v154
	ds_read_b128 v[180:183], v154 offset:1024
	ds_read_b128 v[184:187], v154 offset:2048
	ds_read_b128 v[188:191], v154 offset:3072
	s_add_u32 s28, s28, 0x80000
	s_addc_u32 s29, s29, 0
	s_mov_b32 m0, s40
	v_lshl_add_u64 v[230:231], s[28:29], 0, v[134:135]
	ds_read_b128 v[192:195], v165 offset:32768
	ds_read_b128 v[196:199], v165 offset:33792
	ds_read_b128 v[200:203], v165 offset:34816
	ds_read_b128 v[204:207], v165 offset:35840
	ds_read_b128 v[208:211], v165 offset:36864
	ds_read_b128 v[212:215], v165 offset:37888
	ds_read_b128 v[216:219], v165 offset:38912
	ds_read_b128 v[220:223], v165 offset:39936
	global_load_lds_dwordx4 v[230:231], off
	v_lshl_add_u64 v[230:231], s[28:29], 0, v[130:131]
	s_mov_b32 m0, s41
	s_nop 0
	global_load_lds_dwordx4 v[230:231], off
	s_waitcnt vmcnt(8)
	s_waitcnt lgkmcnt(0)
	s_barrier
	s_waitcnt lgkmcnt(0)
	v_mfma_i32_16x16x64_i8 v[124:127], v[144:147], v[192:195], v[124:127]
	v_mfma_i32_16x16x64_i8 v[120:123], v[168:171], v[192:195], v[120:123]
	v_mfma_i32_16x16x64_i8 v[108:111], v[144:147], v[200:203], v[108:111]
	v_mfma_i32_16x16x64_i8 v[104:107], v[168:171], v[200:203], v[104:107]
	v_mfma_i32_16x16x64_i8 v[92:95], v[144:147], v[208:211], v[92:95]
	v_mfma_i32_16x16x64_i8 v[88:91], v[168:171], v[208:211], v[88:91]
	v_mfma_i32_16x16x64_i8 v[76:79], v[144:147], v[216:219], v[76:79]
	v_mfma_i32_16x16x64_i8 v[72:75], v[168:171], v[216:219], v[72:75]
	v_mfma_i32_16x16x64_i8 v[124:127], v[148:151], v[196:199], v[124:127]
	v_mfma_i32_16x16x64_i8 v[120:123], v[172:175], v[196:199], v[120:123]
	v_mfma_i32_16x16x64_i8 v[108:111], v[148:151], v[204:207], v[108:111]
	v_mfma_i32_16x16x64_i8 v[104:107], v[172:175], v[204:207], v[104:107]
	v_mfma_i32_16x16x64_i8 v[92:95], v[148:151], v[212:215], v[92:95]
	v_mfma_i32_16x16x64_i8 v[88:91], v[172:175], v[212:215], v[88:91]
	v_mfma_i32_16x16x64_i8 v[76:79], v[148:151], v[220:223], v[76:79]
	v_mfma_i32_16x16x64_i8 v[72:75], v[172:175], v[220:223], v[72:75]
	v_mfma_i32_16x16x64_i8 v[116:119], v[176:179], v[192:195], v[116:119]
	v_mfma_i32_16x16x64_i8 v[112:115], v[184:187], v[192:195], v[112:115]
	v_mfma_i32_16x16x64_i8 v[100:103], v[176:179], v[200:203], v[100:103]
	v_mfma_i32_16x16x64_i8 v[96:99], v[184:187], v[200:203], v[96:99]
	v_mfma_i32_16x16x64_i8 v[84:87], v[176:179], v[208:211], v[84:87]
	v_mfma_i32_16x16x64_i8 v[80:83], v[184:187], v[208:211], v[80:83]
	v_mfma_i32_16x16x64_i8 v[68:71], v[176:179], v[216:219], v[68:71]
	v_mfma_i32_16x16x64_i8 v[64:67], v[184:187], v[216:219], v[64:67]
	v_mfma_i32_16x16x64_i8 v[116:119], v[180:183], v[196:199], v[116:119]
	v_mfma_i32_16x16x64_i8 v[112:115], v[188:191], v[196:199], v[112:115]
	v_mfma_i32_16x16x64_i8 v[100:103], v[180:183], v[204:207], v[100:103]
	v_mfma_i32_16x16x64_i8 v[96:99], v[188:191], v[204:207], v[96:99]
	v_mfma_i32_16x16x64_i8 v[84:87], v[180:183], v[212:215], v[84:87]
	v_mfma_i32_16x16x64_i8 v[80:83], v[188:191], v[212:215], v[80:83]
	v_mfma_i32_16x16x64_i8 v[68:71], v[180:183], v[220:223], v[68:71]
	v_mfma_i32_16x16x64_i8 v[64:67], v[188:191], v[220:223], v[64:67]
	s_barrier
	s_add_i32 s28, s55, s35
	v_lshl_add_u64 v[152:153], v[152:153], 0, s[16:17]
	s_mov_b32 m0, s28
	ds_read_b128 v[192:195], v165 offset:49152
	ds_read_b128 v[196:199], v165 offset:50176
	ds_read_b128 v[200:203], v165 offset:51200
	ds_read_b128 v[204:207], v165 offset:52224
	ds_read_b128 v[208:211], v165 offset:53248
	ds_read_b128 v[212:215], v165 offset:54272
	ds_read_b128 v[216:219], v165 offset:55296
	ds_read_b128 v[220:223], v165 offset:56320
	global_load_lds_dwordx4 v[152:153], off
	s_add_i32 m0, s28, 0x2000
	s_add_u32 s6, s6, 0x80080
	v_lshl_add_u64 v[152:153], v[224:225], 0, s[16:17]
	s_addc_u32 s7, s7, 0
	s_add_i32 s28, s56, s35
	global_load_lds_dwordx4 v[152:153], off
	v_lshl_add_u64 v[152:153], s[6:7], 0, v[132:133]
	s_mov_b32 m0, s28
	s_nop 0
	global_load_lds_dwordx4 v[152:153], off
	v_lshl_add_u64 v[152:153], s[6:7], 0, v[128:129]
	s_add_i32 m0, s28, 0x2000
	s_nop 0
	global_load_lds_dwordx4 v[152:153], off
	v_lshl_add_u64 v[152:153], v[226:227], 0, s[16:17]
	s_mov_b32 m0, s43
	s_nop 0
	global_load_lds_dwordx4 v[152:153], off
	v_lshl_add_u64 v[152:153], v[228:229], 0, s[16:17]
	s_mov_b32 m0, s44
	s_nop 0
	global_load_lds_dwordx4 v[152:153], off
	s_waitcnt vmcnt(8)
	s_waitcnt lgkmcnt(0)
	s_barrier
	s_waitcnt lgkmcnt(0)
	v_mfma_i32_16x16x64_i8 v[60:63], v[144:147], v[192:195], v[60:63]
	v_mfma_i32_16x16x64_i8 v[56:59], v[168:171], v[192:195], v[56:59]
	v_mfma_i32_16x16x64_i8 v[44:47], v[144:147], v[200:203], v[44:47]
	v_mfma_i32_16x16x64_i8 v[40:43], v[168:171], v[200:203], v[40:43]
	v_mfma_i32_16x16x64_i8 v[28:31], v[144:147], v[208:211], v[28:31]
	v_mfma_i32_16x16x64_i8 v[24:27], v[168:171], v[208:211], v[24:27]
	v_mfma_i32_16x16x64_i8 v[12:15], v[144:147], v[216:219], v[12:15]
	v_mfma_i32_16x16x64_i8 v[8:11], v[168:171], v[216:219], v[8:11]
	v_mfma_i32_16x16x64_i8 v[60:63], v[148:151], v[196:199], v[60:63]
	v_mfma_i32_16x16x64_i8 v[56:59], v[172:175], v[196:199], v[56:59]
	v_mfma_i32_16x16x64_i8 v[44:47], v[148:151], v[204:207], v[44:47]
	v_mfma_i32_16x16x64_i8 v[40:43], v[172:175], v[204:207], v[40:43]
	v_mfma_i32_16x16x64_i8 v[28:31], v[148:151], v[212:215], v[28:31]
	v_mfma_i32_16x16x64_i8 v[24:27], v[172:175], v[212:215], v[24:27]
	v_mfma_i32_16x16x64_i8 v[12:15], v[148:151], v[220:223], v[12:15]
	v_mfma_i32_16x16x64_i8 v[8:11], v[172:175], v[220:223], v[8:11]
	v_mfma_i32_16x16x64_i8 v[52:55], v[176:179], v[192:195], v[52:55]
	v_mfma_i32_16x16x64_i8 v[48:51], v[184:187], v[192:195], v[48:51]
	v_mfma_i32_16x16x64_i8 v[36:39], v[176:179], v[200:203], v[36:39]
	v_mfma_i32_16x16x64_i8 v[32:35], v[184:187], v[200:203], v[32:35]
	v_mfma_i32_16x16x64_i8 v[20:23], v[176:179], v[208:211], v[20:23]
	v_mfma_i32_16x16x64_i8 v[16:19], v[184:187], v[208:211], v[16:19]
	v_mfma_i32_16x16x64_i8 v[4:7], v[176:179], v[216:219], v[4:7]
	v_mfma_i32_16x16x64_i8 v[0:3], v[184:187], v[216:219], v[0:3]
	v_mfma_i32_16x16x64_i8 v[52:55], v[180:183], v[196:199], v[52:55]
	v_mfma_i32_16x16x64_i8 v[48:51], v[188:191], v[196:199], v[48:51]
	v_mfma_i32_16x16x64_i8 v[36:39], v[180:183], v[204:207], v[36:39]
	v_mfma_i32_16x16x64_i8 v[32:35], v[188:191], v[204:207], v[32:35]
	v_mfma_i32_16x16x64_i8 v[20:23], v[180:183], v[212:215], v[20:23]
	v_mfma_i32_16x16x64_i8 v[16:19], v[188:191], v[212:215], v[16:19]
	v_mfma_i32_16x16x64_i8 v[4:7], v[180:183], v[220:223], v[4:7]
	v_mfma_i32_16x16x64_i8 v[0:3], v[188:191], v[220:223], v[0:3]
	s_barrier
	s_add_i32 s54, s54, 2
	s_add_u32 s52, s52, 0x100
	s_addc_u32 s53, s53, 0
	s_add_u32 s4, s4, 0x100
	s_addc_u32 s5, s5, 0
	s_cmp_gt_u32 s54, 29
	s_cbranch_scc0 .LBB0_726
	s_setprio 0
	s_and_b64 vcc, exec, s[18:19]
	s_cbranch_vccz .LBB0_729
	s_barrier

.LBB0_1254:
	s_ashr_i32 s23, s22, 31
	s_lshl_b64 s[24:25], s[22:23], 19
	s_add_u32 s24, s19, s24
	s_addc_u32 s25, s33, s25
	s_and_b64 s[26:27], s[4:5], exec
	s_cselect_b32 s23, s25, s37
	s_cselect_b32 s29, s24, s36
	s_ashr_i32 s21, s20, 31
	s_lshl_b64 s[26:27], s[20:21], 19
	s_add_u32 s26, s40, s26
	s_addc_u32 s27, s41, s27
	s_and_b64 s[38:39], s[4:5], exec
	s_cselect_b32 s21, s27, s35
	s_cselect_b32 s56, s26, s34
	s_add_u32 s57, s34, 0x100
	s_addc_u32 s58, s35, 0
	s_add_u32 s34, s36, 0x40080
	v_mov_b32_e32 v32, 0
	s_addc_u32 s35, s37, 0
	s_mov_b32 s59, -2
	v_mov_b32_e32 v33, v32
	v_mov_b32_e32 v34, v32
	v_mov_b32_e32 v35, v32
	v_mov_b32_e32 v36, v32
	v_mov_b32_e32 v37, v32
	v_mov_b32_e32 v38, v32
	v_mov_b32_e32 v39, v32
	v_mov_b32_e32 v48, v32
	v_mov_b32_e32 v49, v32
	v_mov_b32_e32 v50, v32
	v_mov_b32_e32 v51, v32
	v_mov_b32_e32 v52, v32
	v_mov_b32_e32 v53, v32
	v_mov_b32_e32 v54, v32
	v_mov_b32_e32 v55, v32
	v_mov_b32_e32 v64, v32
	v_mov_b32_e32 v65, v32
	v_mov_b32_e32 v66, v32
	v_mov_b32_e32 v67, v32
	v_mov_b32_e32 v68, v32
	v_mov_b32_e32 v69, v32
	v_mov_b32_e32 v70, v32
	v_mov_b32_e32 v71, v32
	v_mov_b32_e32 v80, v32
	v_mov_b32_e32 v81, v32
	v_mov_b32_e32 v82, v32
	v_mov_b32_e32 v83, v32
	v_mov_b32_e32 v84, v32
	v_mov_b32_e32 v85, v32
	v_mov_b32_e32 v86, v32
	v_mov_b32_e32 v87, v32
	v_mov_b32_e32 v40, v32
	v_mov_b32_e32 v41, v32
	v_mov_b32_e32 v42, v32
	v_mov_b32_e32 v43, v32
	v_mov_b32_e32 v44, v32
	v_mov_b32_e32 v45, v32
	v_mov_b32_e32 v46, v32
	v_mov_b32_e32 v47, v32
	v_mov_b32_e32 v56, v32
	v_mov_b32_e32 v57, v32
	v_mov_b32_e32 v58, v32
	v_mov_b32_e32 v59, v32
	v_mov_b32_e32 v60, v32
	v_mov_b32_e32 v61, v32
	v_mov_b32_e32 v62, v32
	v_mov_b32_e32 v63, v32
	v_mov_b32_e32 v72, v32
	v_mov_b32_e32 v73, v32
	v_mov_b32_e32 v74, v32
	v_mov_b32_e32 v75, v32
	v_mov_b32_e32 v76, v32
	v_mov_b32_e32 v77, v32
	v_mov_b32_e32 v78, v32
	v_mov_b32_e32 v79, v32
	v_mov_b32_e32 v88, v32
	v_mov_b32_e32 v89, v32
	v_mov_b32_e32 v90, v32
	v_mov_b32_e32 v91, v32
	v_mov_b32_e32 v92, v32
	v_mov_b32_e32 v93, v32
	v_mov_b32_e32 v94, v32
	v_mov_b32_e32 v95, v32
	v_mov_b32_e32 v96, v32
	v_mov_b32_e32 v97, v32
	v_mov_b32_e32 v98, v32
	v_mov_b32_e32 v99, v32
	v_mov_b32_e32 v100, v32
	v_mov_b32_e32 v101, v32
	v_mov_b32_e32 v102, v32
	v_mov_b32_e32 v103, v32
	v_mov_b32_e32 v112, v32
	v_mov_b32_e32 v113, v32
	v_mov_b32_e32 v114, v32
	v_mov_b32_e32 v115, v32
	v_mov_b32_e32 v116, v32
	v_mov_b32_e32 v117, v32
	v_mov_b32_e32 v118, v32
	v_mov_b32_e32 v119, v32
	v_mov_b32_e32 v128, v32
	v_mov_b32_e32 v129, v32
	v_mov_b32_e32 v130, v32
	v_mov_b32_e32 v131, v32
	v_mov_b32_e32 v132, v32
	v_mov_b32_e32 v133, v32
	v_mov_b32_e32 v134, v32
	v_mov_b32_e32 v135, v32
	v_mov_b32_e32 v144, v32
	v_mov_b32_e32 v145, v32
	v_mov_b32_e32 v146, v32
	v_mov_b32_e32 v147, v32
	v_mov_b32_e32 v148, v32
	v_mov_b32_e32 v149, v32
	v_mov_b32_e32 v150, v32
	v_mov_b32_e32 v151, v32
	v_mov_b32_e32 v104, v32
	v_mov_b32_e32 v105, v32
	v_mov_b32_e32 v106, v32
	v_mov_b32_e32 v107, v32
	v_mov_b32_e32 v108, v32
	v_mov_b32_e32 v109, v32
	v_mov_b32_e32 v110, v32
	v_mov_b32_e32 v111, v32
	v_mov_b32_e32 v120, v32
	v_mov_b32_e32 v121, v32
	v_mov_b32_e32 v122, v32
	v_mov_b32_e32 v123, v32
	v_mov_b32_e32 v124, v32
	v_mov_b32_e32 v125, v32
	v_mov_b32_e32 v126, v32
	v_mov_b32_e32 v127, v32
	v_mov_b32_e32 v136, v32
	v_mov_b32_e32 v137, v32
	v_mov_b32_e32 v138, v32
	v_mov_b32_e32 v139, v32
	v_mov_b32_e32 v140, v32
	v_mov_b32_e32 v141, v32
	v_mov_b32_e32 v142, v32
	v_mov_b32_e32 v143, v32
	v_mov_b32_e32 v152, v32
	v_mov_b32_e32 v153, v32
	v_mov_b32_e32 v154, v32
	v_mov_b32_e32 v155, v32
	v_mov_b32_e32 v156, v32
	v_mov_b32_e32 v157, v32
	v_mov_b32_e32 v158, v32
	v_mov_b32_e32 v159, v32
	s_cmp_ge_u32 s81, 4
	s_cbranch_scc0 .Lsp_skip7
	s_setprio 1
.Lsp_skip7:
.LBB0_1255:
	ds_read_b128 v[16:19], v193
	ds_read_b128 v[20:23], v193 offset:1024
	ds_read_b128 v[24:27], v193 offset:2048
	ds_read_b128 v[28:31], v193 offset:3072
	s_waitcnt lgkmcnt(0)
	ds_read_b128 v[0:3], v194
	ds_read_b128 v[4:7], v194 offset:1024
	ds_read_b128 v[8:11], v194 offset:2048
	ds_read_b128 v[12:15], v194 offset:3072
	s_add_u32 s36, s34, 0xfffc0080
	s_addc_u32 s37, s35, -1
	s_cmp_eq_u32 s59, 12
	s_cselect_b32 s39, s23, s37
	s_cselect_b32 s38, s29, s36
	s_cselect_b32 s37, s21, s58
	s_cselect_b32 s36, s56, s57
	v_lshl_add_u64 v[184:185], s[34:35], 0, v[170:171]
	s_add_i32 m0, s31, 0xc000
	ds_read_b128 v[176:179], v195
	ds_read_b128 v[180:183], v195 offset:1024
	ds_read_b128 v[200:203], v195 offset:2048
	ds_read_b128 v[204:207], v195 offset:3072
	ds_read_b128 v[208:211], v195 offset:4096
	ds_read_b128 v[212:215], v195 offset:5120
	ds_read_b128 v[216:219], v195 offset:6144
	ds_read_b128 v[220:223], v195 offset:7168
	global_load_lds_dwordx4 v[184:185], off
	v_lshl_add_u64 v[184:185], s[34:35], 0, v[168:169]
	s_add_i32 m0, s31, 0xe000
	s_nop 0
	global_load_lds_dwordx4 v[184:185], off
	s_waitcnt vmcnt(8)
	s_waitcnt lgkmcnt(0)
	s_barrier
	s_waitcnt lgkmcnt(0)
	v_mfma_scale_f32_16x16x128_f8f6f4 v[156:159], v[16:23], v[176:183], v[156:159], v196, v196 op_sel_hi:[0,0,0]
	v_mfma_scale_f32_16x16x128_f8f6f4 v[152:155], v[24:31], v[176:183], v[152:155], v196, v196 op_sel_hi:[0,0,0]
	v_mfma_scale_f32_16x16x128_f8f6f4 v[140:143], v[16:23], v[200:207], v[140:143], v196, v196 op_sel_hi:[0,0,0]
	v_mfma_scale_f32_16x16x128_f8f6f4 v[136:139], v[24:31], v[200:207], v[136:139], v196, v196 op_sel_hi:[0,0,0]
	v_mfma_scale_f32_16x16x128_f8f6f4 v[124:127], v[16:23], v[208:215], v[124:127], v196, v196 op_sel_hi:[0,0,0]
	v_mfma_scale_f32_16x16x128_f8f6f4 v[120:123], v[24:31], v[208:215], v[120:123], v196, v196 op_sel_hi:[0,0,0]
	v_mfma_scale_f32_16x16x128_f8f6f4 v[108:111], v[16:23], v[216:223], v[108:111], v196, v196 op_sel_hi:[0,0,0]
	v_mfma_scale_f32_16x16x128_f8f6f4 v[104:107], v[24:31], v[216:223], v[104:107], v196, v196 op_sel_hi:[0,0,0]
	v_mfma_scale_f32_16x16x128_f8f6f4 v[148:151], v[0:7], v[176:183], v[148:151], v196, v196 op_sel_hi:[0,0,0]
	v_mfma_scale_f32_16x16x128_f8f6f4 v[144:147], v[8:15], v[176:183], v[144:147], v196, v196 op_sel_hi:[0,0,0]
	v_mfma_scale_f32_16x16x128_f8f6f4 v[132:135], v[0:7], v[200:207], v[132:135], v196, v196 op_sel_hi:[0,0,0]
	v_mfma_scale_f32_16x16x128_f8f6f4 v[128:131], v[8:15], v[200:207], v[128:131], v196, v196 op_sel_hi:[0,0,0]
	v_mfma_scale_f32_16x16x128_f8f6f4 v[116:119], v[0:7], v[208:215], v[116:119], v196, v196 op_sel_hi:[0,0,0]
	v_mfma_scale_f32_16x16x128_f8f6f4 v[112:115], v[8:15], v[208:215], v[112:115], v196, v196 op_sel_hi:[0,0,0]
	v_mfma_scale_f32_16x16x128_f8f6f4 v[100:103], v[0:7], v[216:223], v[100:103], v196, v196 op_sel_hi:[0,0,0]
	v_mfma_scale_f32_16x16x128_f8f6f4 v[96:99], v[8:15], v[216:223], v[96:99], v196, v196 op_sel_hi:[0,0,0]
	s_barrier
	s_add_i32 s60, s51, s42
	v_lshl_add_u64 v[176:177], s[36:37], 0, v[162:163]
	s_mov_b32 m0, s60
	ds_read_b128 v[200:203], v195 offset:16384
	ds_read_b128 v[204:207], v195 offset:17408
	ds_read_b128 v[208:211], v195 offset:18432
	ds_read_b128 v[212:215], v195 offset:19456
	ds_read_b128 v[216:219], v195 offset:20480
	ds_read_b128 v[220:223], v195 offset:21504
	ds_read_b128 v[224:227], v195 offset:22528
	ds_read_b128 v[228:231], v195 offset:23552
	global_load_lds_dwordx4 v[176:177], off
	s_add_i32 m0, s60, 0x2000
	s_add_u32 s60, s36, 0x40000
	v_lshl_add_u64 v[178:179], s[36:37], 0, v[166:167]
	s_addc_u32 s61, s37, 0
	s_add_i32 s62, s52, s42
	global_load_lds_dwordx4 v[178:179], off
	v_lshl_add_u64 v[180:181], s[60:61], 0, v[162:163]
	s_mov_b32 m0, s62
	v_lshl_add_u64 v[182:183], s[38:39], 0, v[164:165]
	global_load_lds_dwordx4 v[180:181], off
	v_lshl_add_u64 v[180:181], s[60:61], 0, v[166:167]
	s_add_i32 m0, s62, 0x2000
	s_nop 0
	global_load_lds_dwordx4 v[180:181], off
	v_lshl_add_u64 v[180:181], s[38:39], 0, v[160:161]
	s_mov_b32 m0, s31
	s_nop 0
	global_load_lds_dwordx4 v[180:181], off
	s_mov_b32 m0, s43
	s_nop 0
	global_load_lds_dwordx4 v[182:183], off
	s_waitcnt vmcnt(8)
	s_waitcnt lgkmcnt(0)
	s_barrier
	s_waitcnt lgkmcnt(0)
	v_mfma_scale_f32_16x16x128_f8f6f4 v[92:95], v[16:23], v[200:207], v[92:95], v196, v196 op_sel_hi:[0,0,0]
	v_mfma_scale_f32_16x16x128_f8f6f4 v[88:91], v[24:31], v[200:207], v[88:91], v196, v196 op_sel_hi:[0,0,0]
	v_mfma_scale_f32_16x16x128_f8f6f4 v[76:79], v[16:23], v[208:215], v[76:79], v196, v196 op_sel_hi:[0,0,0]
	v_mfma_scale_f32_16x16x128_f8f6f4 v[72:75], v[24:31], v[208:215], v[72:75], v196, v196 op_sel_hi:[0,0,0]
	v_mfma_scale_f32_16x16x128_f8f6f4 v[60:63], v[16:23], v[216:223], v[60:63], v196, v196 op_sel_hi:[0,0,0]
	v_mfma_scale_f32_16x16x128_f8f6f4 v[56:59], v[24:31], v[216:223], v[56:59], v196, v196 op_sel_hi:[0,0,0]
	v_mfma_scale_f32_16x16x128_f8f6f4 v[44:47], v[16:23], v[224:231], v[44:47], v196, v196 op_sel_hi:[0,0,0]
	v_mfma_scale_f32_16x16x128_f8f6f4 v[40:43], v[24:31], v[224:231], v[40:43], v196, v196 op_sel_hi:[0,0,0]
	v_mfma_scale_f32_16x16x128_f8f6f4 v[84:87], v[0:7], v[200:207], v[84:87], v196, v196 op_sel_hi:[0,0,0]
	v_mfma_scale_f32_16x16x128_f8f6f4 v[80:83], v[8:15], v[200:207], v[80:83], v196, v196 op_sel_hi:[0,0,0]
	v_mfma_scale_f32_16x16x128_f8f6f4 v[68:71], v[0:7], v[208:215], v[68:71], v196, v196 op_sel_hi:[0,0,0]
	v_mfma_scale_f32_16x16x128_f8f6f4 v[64:67], v[8:15], v[208:215], v[64:67], v196, v196 op_sel_hi:[0,0,0]
	v_mfma_scale_f32_16x16x128_f8f6f4 v[52:55], v[0:7], v[216:223], v[52:55], v196, v196 op_sel_hi:[0,0,0]
	v_mfma_scale_f32_16x16x128_f8f6f4 v[48:51], v[8:15], v[216:223], v[48:51], v196, v196 op_sel_hi:[0,0,0]
	v_mfma_scale_f32_16x16x128_f8f6f4 v[36:39], v[0:7], v[224:231], v[36:39], v196, v196 op_sel_hi:[0,0,0]
	v_mfma_scale_f32_16x16x128_f8f6f4 v[32:35], v[8:15], v[224:231], v[32:35], v196, v196 op_sel_hi:[0,0,0]
	s_barrier
	s_add_i32 s60, 0, 0x18000
	s_add_i32 s61, 0, 0x1c000
	v_add_u32_e32 v12, s60, v191
	v_add_u32_e32 v28, s61, v191
	ds_read_b128 v[0:3], v12
	ds_read_b128 v[4:7], v12 offset:1024
	ds_read_b128 v[8:11], v12 offset:2048
	ds_read_b128 v[12:15], v12 offset:3072
	ds_read_b128 v[16:19], v28
	ds_read_b128 v[20:23], v28 offset:1024
	ds_read_b128 v[24:27], v28 offset:2048
	ds_read_b128 v[28:31], v28 offset:3072
	s_add_u32 s38, s38, 0x40000
	s_addc_u32 s39, s39, 0
	s_mov_b32 m0, s44
	v_lshl_add_u64 v[184:185], s[38:39], 0, v[160:161]
	ds_read_b128 v[200:203], v195 offset:32768
	ds_read_b128 v[204:207], v195 offset:33792
	ds_read_b128 v[208:211], v195 offset:34816
	ds_read_b128 v[212:215], v195 offset:35840
	ds_read_b128 v[216:219], v195 offset:36864
	ds_read_b128 v[220:223], v195 offset:37888
	ds_read_b128 v[224:227], v195 offset:38912
	ds_read_b128 v[228:231], v195 offset:39936
	global_load_lds_dwordx4 v[184:185], off
	v_lshl_add_u64 v[184:185], s[38:39], 0, v[164:165]
	s_mov_b32 m0, s45
	s_nop 0
	global_load_lds_dwordx4 v[184:185], off
	s_waitcnt vmcnt(8)
	s_waitcnt lgkmcnt(0)
	s_barrier
	s_waitcnt lgkmcnt(0)
	v_mfma_scale_f32_16x16x128_f8f6f4 v[156:159], v[0:7], v[200:207], v[156:159], v196, v196 op_sel_hi:[0,0,0]
	v_mfma_scale_f32_16x16x128_f8f6f4 v[152:155], v[8:15], v[200:207], v[152:155], v196, v196 op_sel_hi:[0,0,0]
	v_mfma_scale_f32_16x16x128_f8f6f4 v[140:143], v[0:7], v[208:215], v[140:143], v196, v196 op_sel_hi:[0,0,0]
	v_mfma_scale_f32_16x16x128_f8f6f4 v[136:139], v[8:15], v[208:215], v[136:139], v196, v196 op_sel_hi:[0,0,0]
	v_mfma_scale_f32_16x16x128_f8f6f4 v[124:127], v[0:7], v[216:223], v[124:127], v196, v196 op_sel_hi:[0,0,0]
	v_mfma_scale_f32_16x16x128_f8f6f4 v[120:123], v[8:15], v[216:223], v[120:123], v196, v196 op_sel_hi:[0,0,0]
	v_mfma_scale_f32_16x16x128_f8f6f4 v[108:111], v[0:7], v[224:231], v[108:111], v196, v196 op_sel_hi:[0,0,0]
	v_mfma_scale_f32_16x16x128_f8f6f4 v[104:107], v[8:15], v[224:231], v[104:107], v196, v196 op_sel_hi:[0,0,0]
	v_mfma_scale_f32_16x16x128_f8f6f4 v[148:151], v[16:23], v[200:207], v[148:151], v196, v196 op_sel_hi:[0,0,0]
	v_mfma_scale_f32_16x16x128_f8f6f4 v[144:147], v[24:31], v[200:207], v[144:147], v196, v196 op_sel_hi:[0,0,0]
	v_mfma_scale_f32_16x16x128_f8f6f4 v[132:135], v[16:23], v[208:215], v[132:135], v196, v196 op_sel_hi:[0,0,0]
	v_mfma_scale_f32_16x16x128_f8f6f4 v[128:131], v[24:31], v[208:215], v[128:131], v196, v196 op_sel_hi:[0,0,0]
	v_mfma_scale_f32_16x16x128_f8f6f4 v[116:119], v[16:23], v[216:223], v[116:119], v196, v196 op_sel_hi:[0,0,0]
	v_mfma_scale_f32_16x16x128_f8f6f4 v[112:115], v[24:31], v[216:223], v[112:115], v196, v196 op_sel_hi:[0,0,0]
	v_mfma_scale_f32_16x16x128_f8f6f4 v[100:103], v[16:23], v[224:231], v[100:103], v196, v196 op_sel_hi:[0,0,0]
	v_mfma_scale_f32_16x16x128_f8f6f4 v[96:99], v[24:31], v[224:231], v[96:99], v196, v196 op_sel_hi:[0,0,0]
	s_barrier
	s_add_i32 s38, s60, s42
	v_lshl_add_u64 v[176:177], v[176:177], 0, s[14:15]
	s_mov_b32 m0, s38
	ds_read_b128 v[200:203], v195 offset:49152
	ds_read_b128 v[204:207], v195 offset:50176
	ds_read_b128 v[208:211], v195 offset:51200
	ds_read_b128 v[212:215], v195 offset:52224
	ds_read_b128 v[216:219], v195 offset:53248
	ds_read_b128 v[220:223], v195 offset:54272
	ds_read_b128 v[224:227], v195 offset:55296
	ds_read_b128 v[228:231], v195 offset:56320
	global_load_lds_dwordx4 v[176:177], off
	s_add_i32 m0, s38, 0x2000
	s_add_u32 s36, s36, 0x40080
	v_lshl_add_u64 v[176:177], v[178:179], 0, s[14:15]
	s_addc_u32 s37, s37, 0
	s_add_i32 s38, s61, s42
	global_load_lds_dwordx4 v[176:177], off
	v_lshl_add_u64 v[176:177], s[36:37], 0, v[162:163]
	s_mov_b32 m0, s38
	s_nop 0
	global_load_lds_dwordx4 v[176:177], off
	v_lshl_add_u64 v[176:177], s[36:37], 0, v[166:167]
	s_add_i32 m0, s38, 0x2000
	s_nop 0
	global_load_lds_dwordx4 v[176:177], off
	v_lshl_add_u64 v[176:177], v[180:181], 0, s[14:15]
	s_mov_b32 m0, s47
	s_nop 0
	global_load_lds_dwordx4 v[176:177], off
	v_lshl_add_u64 v[176:177], v[182:183], 0, s[14:15]
	s_mov_b32 m0, s48
	s_nop 0
	global_load_lds_dwordx4 v[176:177], off
	s_waitcnt vmcnt(8)
	s_waitcnt lgkmcnt(0)
	s_barrier
	s_waitcnt lgkmcnt(0)
	v_mfma_scale_f32_16x16x128_f8f6f4 v[92:95], v[0:7], v[200:207], v[92:95], v196, v196 op_sel_hi:[0,0,0]
	v_mfma_scale_f32_16x16x128_f8f6f4 v[88:91], v[8:15], v[200:207], v[88:91], v196, v196 op_sel_hi:[0,0,0]
	v_mfma_scale_f32_16x16x128_f8f6f4 v[76:79], v[0:7], v[208:215], v[76:79], v196, v196 op_sel_hi:[0,0,0]
	v_mfma_scale_f32_16x16x128_f8f6f4 v[72:75], v[8:15], v[208:215], v[72:75], v196, v196 op_sel_hi:[0,0,0]
	v_mfma_scale_f32_16x16x128_f8f6f4 v[60:63], v[0:7], v[216:223], v[60:63], v196, v196 op_sel_hi:[0,0,0]
	v_mfma_scale_f32_16x16x128_f8f6f4 v[56:59], v[8:15], v[216:223], v[56:59], v196, v196 op_sel_hi:[0,0,0]
	v_mfma_scale_f32_16x16x128_f8f6f4 v[44:47], v[0:7], v[224:231], v[44:47], v196, v196 op_sel_hi:[0,0,0]
	v_mfma_scale_f32_16x16x128_f8f6f4 v[40:43], v[8:15], v[224:231], v[40:43], v196, v196 op_sel_hi:[0,0,0]
	v_mfma_scale_f32_16x16x128_f8f6f4 v[84:87], v[16:23], v[200:207], v[84:87], v196, v196 op_sel_hi:[0,0,0]
	v_mfma_scale_f32_16x16x128_f8f6f4 v[80:83], v[24:31], v[200:207], v[80:83], v196, v196 op_sel_hi:[0,0,0]
	v_mfma_scale_f32_16x16x128_f8f6f4 v[68:71], v[16:23], v[208:215], v[68:71], v196, v196 op_sel_hi:[0,0,0]
	v_mfma_scale_f32_16x16x128_f8f6f4 v[64:67], v[24:31], v[208:215], v[64:67], v196, v196 op_sel_hi:[0,0,0]
	v_mfma_scale_f32_16x16x128_f8f6f4 v[52:55], v[16:23], v[216:223], v[52:55], v196, v196 op_sel_hi:[0,0,0]
	v_mfma_scale_f32_16x16x128_f8f6f4 v[48:51], v[24:31], v[216:223], v[48:51], v196, v196 op_sel_hi:[0,0,0]
	v_mfma_scale_f32_16x16x128_f8f6f4 v[36:39], v[16:23], v[224:231], v[36:39], v196, v196 op_sel_hi:[0,0,0]
	v_mfma_scale_f32_16x16x128_f8f6f4 v[32:35], v[24:31], v[224:231], v[32:35], v196, v196 op_sel_hi:[0,0,0]
	s_barrier
	s_add_i32 s59, s59, 2
	s_add_u32 s57, s57, 0x100
	s_addc_u32 s58, s58, 0
	s_add_u32 s34, s34, 0x100
	s_addc_u32 s35, s35, 0
	s_cmp_gt_u32 s59, 13
	s_cbranch_scc0 .LBB0_1255
	s_setprio 0
	s_and_b64 vcc, exec, s[16:17]
	s_cbranch_vccz .LBB0_1258
	s_barrier

.LBB0_1355:
	s_ashr_i32 s23, s22, 31
	s_lshl_b64 s[24:25], s[22:23], 20
	s_add_u32 s24, s38, s24
	s_addc_u32 s25, s39, s25
	s_and_b64 s[26:27], s[2:3], exec
	s_cselect_b32 s1, s25, s35
	s_cselect_b32 s23, s24, s34
	s_ashr_i32 s21, s20, 31
	s_lshl_b64 s[26:27], s[20:21], 20
	s_add_u32 s26, s40, s26
	s_addc_u32 s27, s41, s27
	s_and_b64 s[36:37], s[2:3], exec
	s_cselect_b32 s21, s27, s31
	s_cselect_b32 s29, s26, s30
	s_add_u32 s33, s30, 0x100
	s_addc_u32 s57, s31, 0
	s_add_u32 s30, s34, 0x80080
	v_mov_b32_e32 v0, 0
	s_addc_u32 s31, s35, 0
	s_mov_b32 s58, -2
	v_mov_b32_e32 v1, v0
	v_mov_b32_e32 v2, v0
	v_mov_b32_e32 v3, v0
	v_mov_b32_e32 v4, v0
	v_mov_b32_e32 v5, v0
	v_mov_b32_e32 v6, v0
	v_mov_b32_e32 v7, v0
	v_mov_b32_e32 v16, v0
	v_mov_b32_e32 v17, v0
	v_mov_b32_e32 v18, v0
	v_mov_b32_e32 v19, v0
	v_mov_b32_e32 v20, v0
	v_mov_b32_e32 v21, v0
	v_mov_b32_e32 v22, v0
	v_mov_b32_e32 v23, v0
	v_mov_b32_e32 v32, v0
	v_mov_b32_e32 v33, v0
	v_mov_b32_e32 v34, v0
	v_mov_b32_e32 v35, v0
	v_mov_b32_e32 v36, v0
	v_mov_b32_e32 v37, v0
	v_mov_b32_e32 v38, v0
	v_mov_b32_e32 v39, v0
	v_mov_b32_e32 v48, v0
	v_mov_b32_e32 v49, v0
	v_mov_b32_e32 v50, v0
	v_mov_b32_e32 v51, v0
	v_mov_b32_e32 v52, v0
	v_mov_b32_e32 v53, v0
	v_mov_b32_e32 v54, v0
	v_mov_b32_e32 v55, v0
	v_mov_b32_e32 v8, v0
	v_mov_b32_e32 v9, v0
	v_mov_b32_e32 v10, v0
	v_mov_b32_e32 v11, v0
	v_mov_b32_e32 v12, v0
	v_mov_b32_e32 v13, v0
	v_mov_b32_e32 v14, v0
	v_mov_b32_e32 v15, v0
	v_mov_b32_e32 v24, v0
	v_mov_b32_e32 v25, v0
	v_mov_b32_e32 v26, v0
	v_mov_b32_e32 v27, v0
	v_mov_b32_e32 v28, v0
	v_mov_b32_e32 v29, v0
	v_mov_b32_e32 v30, v0
	v_mov_b32_e32 v31, v0
	v_mov_b32_e32 v40, v0
	v_mov_b32_e32 v41, v0
	v_mov_b32_e32 v42, v0
	v_mov_b32_e32 v43, v0
	v_mov_b32_e32 v44, v0
	v_mov_b32_e32 v45, v0
	v_mov_b32_e32 v46, v0
	v_mov_b32_e32 v47, v0
	v_mov_b32_e32 v56, v0
	v_mov_b32_e32 v57, v0
	v_mov_b32_e32 v58, v0
	v_mov_b32_e32 v59, v0
	v_mov_b32_e32 v60, v0
	v_mov_b32_e32 v61, v0
	v_mov_b32_e32 v62, v0
	v_mov_b32_e32 v63, v0
	v_mov_b32_e32 v64, v0
	v_mov_b32_e32 v65, v0
	v_mov_b32_e32 v66, v0
	v_mov_b32_e32 v67, v0
	v_mov_b32_e32 v68, v0
	v_mov_b32_e32 v69, v0
	v_mov_b32_e32 v70, v0
	v_mov_b32_e32 v71, v0
	v_mov_b32_e32 v80, v0
	v_mov_b32_e32 v81, v0
	v_mov_b32_e32 v82, v0
	v_mov_b32_e32 v83, v0
	v_mov_b32_e32 v84, v0
	v_mov_b32_e32 v85, v0
	v_mov_b32_e32 v86, v0
	v_mov_b32_e32 v87, v0
	v_mov_b32_e32 v96, v0
	v_mov_b32_e32 v97, v0
	v_mov_b32_e32 v98, v0
	v_mov_b32_e32 v99, v0
	v_mov_b32_e32 v100, v0
	v_mov_b32_e32 v101, v0
	v_mov_b32_e32 v102, v0
	v_mov_b32_e32 v103, v0
	v_mov_b32_e32 v112, v0
	v_mov_b32_e32 v113, v0
	v_mov_b32_e32 v114, v0
	v_mov_b32_e32 v115, v0
	v_mov_b32_e32 v116, v0
	v_mov_b32_e32 v117, v0
	v_mov_b32_e32 v118, v0
	v_mov_b32_e32 v119, v0
	v_mov_b32_e32 v72, v0
	v_mov_b32_e32 v73, v0
	v_mov_b32_e32 v74, v0
	v_mov_b32_e32 v75, v0
	v_mov_b32_e32 v76, v0
	v_mov_b32_e32 v77, v0
	v_mov_b32_e32 v78, v0
	v_mov_b32_e32 v79, v0
	v_mov_b32_e32 v88, v0
	v_mov_b32_e32 v89, v0
	v_mov_b32_e32 v90, v0
	v_mov_b32_e32 v91, v0
	v_mov_b32_e32 v92, v0
	v_mov_b32_e32 v93, v0
	v_mov_b32_e32 v94, v0
	v_mov_b32_e32 v95, v0
	v_mov_b32_e32 v104, v0
	v_mov_b32_e32 v105, v0
	v_mov_b32_e32 v106, v0
	v_mov_b32_e32 v107, v0
	v_mov_b32_e32 v108, v0
	v_mov_b32_e32 v109, v0
	v_mov_b32_e32 v110, v0
	v_mov_b32_e32 v111, v0
	v_mov_b32_e32 v120, v0
	v_mov_b32_e32 v121, v0
	v_mov_b32_e32 v122, v0
	v_mov_b32_e32 v123, v0
	v_mov_b32_e32 v124, v0
	v_mov_b32_e32 v125, v0
	v_mov_b32_e32 v126, v0
	v_mov_b32_e32 v127, v0
	s_cmp_ge_u32 s81, 4
	s_cbranch_scc0 .Lsp_skip8
	s_setprio 1
.Lsp_skip8:
.LBB0_1356:
	ds_read_b128 v[144:147], v180
	ds_read_b128 v[148:151], v180 offset:1024
	ds_read_b128 v[152:155], v180 offset:2048
	ds_read_b128 v[156:159], v180 offset:3072
	ds_read_b128 v[160:163], v181
	ds_read_b128 v[164:167], v181 offset:1024
	ds_read_b128 v[168:171], v181 offset:2048
	ds_read_b128 v[172:175], v181 offset:3072
	s_add_u32 s34, s30, 0xfff80080
	s_addc_u32 s35, s31, -1
	s_cmp_eq_u32 s58, 28
	s_cselect_b32 s37, s1, s35
	s_cselect_b32 s36, s23, s34
	s_cselect_b32 s35, s21, s57
	s_cselect_b32 s34, s29, s33
	v_lshl_add_u64 v[218:219], s[30:31], 0, v[138:139]
	s_add_i32 m0, s43, 0xc000
	ds_read_b128 v[186:189], v182
	ds_read_b128 v[190:193], v182 offset:1024
	ds_read_b128 v[194:197], v182 offset:2048
	ds_read_b128 v[198:201], v182 offset:3072
	ds_read_b128 v[202:205], v182 offset:4096
	ds_read_b128 v[206:209], v182 offset:5120
	ds_read_b128 v[210:213], v182 offset:6144
	ds_read_b128 v[214:217], v182 offset:7168
	global_load_lds_dwordx4 v[218:219], off
	v_lshl_add_u64 v[218:219], s[30:31], 0, v[136:137]
	s_add_i32 m0, s43, 0xe000
	s_nop 0
	global_load_lds_dwordx4 v[218:219], off
	s_waitcnt vmcnt(8)
	s_waitcnt lgkmcnt(0)
	s_barrier
	s_waitcnt lgkmcnt(0)
	v_mfma_i32_16x16x64_i8 v[124:127], v[144:147], v[186:189], v[124:127]
	v_mfma_i32_16x16x64_i8 v[120:123], v[152:155], v[186:189], v[120:123]
	v_mfma_i32_16x16x64_i8 v[108:111], v[144:147], v[194:197], v[108:111]
	v_mfma_i32_16x16x64_i8 v[104:107], v[152:155], v[194:197], v[104:107]
	v_mfma_i32_16x16x64_i8 v[92:95], v[144:147], v[202:205], v[92:95]
	v_mfma_i32_16x16x64_i8 v[88:91], v[152:155], v[202:205], v[88:91]
	v_mfma_i32_16x16x64_i8 v[76:79], v[144:147], v[210:213], v[76:79]
	v_mfma_i32_16x16x64_i8 v[72:75], v[152:155], v[210:213], v[72:75]
	v_mfma_i32_16x16x64_i8 v[124:127], v[148:151], v[190:193], v[124:127]
	v_mfma_i32_16x16x64_i8 v[120:123], v[156:159], v[190:193], v[120:123]
	v_mfma_i32_16x16x64_i8 v[108:111], v[148:151], v[198:201], v[108:111]
	v_mfma_i32_16x16x64_i8 v[104:107], v[156:159], v[198:201], v[104:107]
	v_mfma_i32_16x16x64_i8 v[92:95], v[148:151], v[206:209], v[92:95]
	v_mfma_i32_16x16x64_i8 v[88:91], v[156:159], v[206:209], v[88:91]
	v_mfma_i32_16x16x64_i8 v[76:79], v[148:151], v[214:217], v[76:79]
	v_mfma_i32_16x16x64_i8 v[72:75], v[156:159], v[214:217], v[72:75]
	v_mfma_i32_16x16x64_i8 v[116:119], v[160:163], v[186:189], v[116:119]
	v_mfma_i32_16x16x64_i8 v[112:115], v[168:171], v[186:189], v[112:115]
	v_mfma_i32_16x16x64_i8 v[100:103], v[160:163], v[194:197], v[100:103]
	v_mfma_i32_16x16x64_i8 v[96:99], v[168:171], v[194:197], v[96:99]
	v_mfma_i32_16x16x64_i8 v[84:87], v[160:163], v[202:205], v[84:87]
	v_mfma_i32_16x16x64_i8 v[80:83], v[168:171], v[202:205], v[80:83]
	v_mfma_i32_16x16x64_i8 v[68:71], v[160:163], v[210:213], v[68:71]
	v_mfma_i32_16x16x64_i8 v[64:67], v[168:171], v[210:213], v[64:67]
	v_mfma_i32_16x16x64_i8 v[116:119], v[164:167], v[190:193], v[116:119]
	v_mfma_i32_16x16x64_i8 v[112:115], v[172:175], v[190:193], v[112:115]
	v_mfma_i32_16x16x64_i8 v[100:103], v[164:167], v[198:201], v[100:103]
	v_mfma_i32_16x16x64_i8 v[96:99], v[172:175], v[198:201], v[96:99]
	v_mfma_i32_16x16x64_i8 v[84:87], v[164:167], v[206:209], v[84:87]
	v_mfma_i32_16x16x64_i8 v[80:83], v[172:175], v[206:209], v[80:83]
	v_mfma_i32_16x16x64_i8 v[68:71], v[164:167], v[214:217], v[68:71]
	v_mfma_i32_16x16x64_i8 v[64:67], v[172:175], v[214:217], v[64:67]
	s_barrier
	s_add_i32 s59, s52, s42
	v_lshl_add_u64 v[218:219], s[34:35], 0, v[130:131]
	s_mov_b32 m0, s59
	ds_read_b128 v[186:189], v182 offset:16384
	ds_read_b128 v[190:193], v182 offset:17408
	ds_read_b128 v[194:197], v182 offset:18432
	ds_read_b128 v[198:201], v182 offset:19456
	ds_read_b128 v[202:205], v182 offset:20480
	ds_read_b128 v[206:209], v182 offset:21504
	ds_read_b128 v[210:213], v182 offset:22528
	ds_read_b128 v[214:217], v182 offset:23552
	global_load_lds_dwordx4 v[218:219], off
	s_add_i32 m0, s59, 0x2000
	s_add_u32 s60, s34, 0x80000
	v_lshl_add_u64 v[220:221], s[34:35], 0, v[134:135]
	s_addc_u32 s61, s35, 0
	s_add_i32 s59, s53, s42
	global_load_lds_dwordx4 v[220:221], off
	v_lshl_add_u64 v[222:223], s[60:61], 0, v[130:131]
	s_mov_b32 m0, s59
	v_lshl_add_u64 v[224:225], s[36:37], 0, v[132:133]
	global_load_lds_dwordx4 v[222:223], off
	v_lshl_add_u64 v[222:223], s[60:61], 0, v[134:135]
	s_add_i32 m0, s59, 0x2000
	s_nop 0
	global_load_lds_dwordx4 v[222:223], off
	v_lshl_add_u64 v[222:223], s[36:37], 0, v[128:129]
	s_mov_b32 m0, s43
	s_nop 0
	global_load_lds_dwordx4 v[222:223], off
	s_mov_b32 m0, s44
	s_nop 0
	global_load_lds_dwordx4 v[224:225], off
	s_waitcnt vmcnt(8)
	s_waitcnt lgkmcnt(0)
	s_barrier
	s_waitcnt lgkmcnt(0)
	v_mfma_i32_16x16x64_i8 v[60:63], v[144:147], v[186:189], v[60:63]
	v_mfma_i32_16x16x64_i8 v[56:59], v[152:155], v[186:189], v[56:59]
	v_mfma_i32_16x16x64_i8 v[44:47], v[144:147], v[194:197], v[44:47]
	v_mfma_i32_16x16x64_i8 v[40:43], v[152:155], v[194:197], v[40:43]
	v_mfma_i32_16x16x64_i8 v[28:31], v[144:147], v[202:205], v[28:31]
	v_mfma_i32_16x16x64_i8 v[24:27], v[152:155], v[202:205], v[24:27]
	v_mfma_i32_16x16x64_i8 v[12:15], v[144:147], v[210:213], v[12:15]
	v_mfma_i32_16x16x64_i8 v[8:11], v[152:155], v[210:213], v[8:11]
	v_mfma_i32_16x16x64_i8 v[60:63], v[148:151], v[190:193], v[60:63]
	v_mfma_i32_16x16x64_i8 v[56:59], v[156:159], v[190:193], v[56:59]
	v_mfma_i32_16x16x64_i8 v[44:47], v[148:151], v[198:201], v[44:47]
	v_mfma_i32_16x16x64_i8 v[40:43], v[156:159], v[198:201], v[40:43]
	v_mfma_i32_16x16x64_i8 v[28:31], v[148:151], v[206:209], v[28:31]
	v_mfma_i32_16x16x64_i8 v[24:27], v[156:159], v[206:209], v[24:27]
	v_mfma_i32_16x16x64_i8 v[12:15], v[148:151], v[214:217], v[12:15]
	v_mfma_i32_16x16x64_i8 v[8:11], v[156:159], v[214:217], v[8:11]
	v_mfma_i32_16x16x64_i8 v[52:55], v[160:163], v[186:189], v[52:55]
	v_mfma_i32_16x16x64_i8 v[48:51], v[168:171], v[186:189], v[48:51]
	v_mfma_i32_16x16x64_i8 v[36:39], v[160:163], v[194:197], v[36:39]
	v_mfma_i32_16x16x64_i8 v[32:35], v[168:171], v[194:197], v[32:35]
	v_mfma_i32_16x16x64_i8 v[20:23], v[160:163], v[202:205], v[20:23]
	v_mfma_i32_16x16x64_i8 v[16:19], v[168:171], v[202:205], v[16:19]
	v_mfma_i32_16x16x64_i8 v[4:7], v[160:163], v[210:213], v[4:7]
	v_mfma_i32_16x16x64_i8 v[0:3], v[168:171], v[210:213], v[0:3]
	v_mfma_i32_16x16x64_i8 v[52:55], v[164:167], v[190:193], v[52:55]
	v_mfma_i32_16x16x64_i8 v[48:51], v[172:175], v[190:193], v[48:51]
	v_mfma_i32_16x16x64_i8 v[36:39], v[164:167], v[198:201], v[36:39]
	v_mfma_i32_16x16x64_i8 v[32:35], v[172:175], v[198:201], v[32:35]
	v_mfma_i32_16x16x64_i8 v[20:23], v[164:167], v[206:209], v[20:23]
	v_mfma_i32_16x16x64_i8 v[16:19], v[172:175], v[206:209], v[16:19]
	v_mfma_i32_16x16x64_i8 v[4:7], v[164:167], v[214:217], v[4:7]
	v_mfma_i32_16x16x64_i8 v[0:3], v[172:175], v[214:217], v[0:3]
	s_barrier
	s_add_i32 s59, 0, 0x18000
	s_add_i32 s60, 0, 0x1c000
	v_add_u32_e32 v156, s59, v178
	v_add_u32_e32 v172, s60, v178
	ds_read_b128 v[144:147], v156
	ds_read_b128 v[148:151], v156 offset:1024
	ds_read_b128 v[152:155], v156 offset:2048
	ds_read_b128 v[156:159], v156 offset:3072
	ds_read_b128 v[160:163], v172
	ds_read_b128 v[164:167], v172 offset:1024
	ds_read_b128 v[168:171], v172 offset:2048
	ds_read_b128 v[172:175], v172 offset:3072
	s_add_u32 s36, s36, 0x80000
	s_addc_u32 s37, s37, 0
	s_mov_b32 m0, s45
	v_lshl_add_u64 v[226:227], s[36:37], 0, v[128:129]
	ds_read_b128 v[186:189], v182 offset:32768
	ds_read_b128 v[190:193], v182 offset:33792
	ds_read_b128 v[194:197], v182 offset:34816
	ds_read_b128 v[198:201], v182 offset:35840
	ds_read_b128 v[202:205], v182 offset:36864
	ds_read_b128 v[206:209], v182 offset:37888
	ds_read_b128 v[210:213], v182 offset:38912
	ds_read_b128 v[214:217], v182 offset:39936
	global_load_lds_dwordx4 v[226:227], off
	v_lshl_add_u64 v[226:227], s[36:37], 0, v[132:133]
	s_mov_b32 m0, s46
	s_nop 0
	global_load_lds_dwordx4 v[226:227], off
	s_waitcnt vmcnt(8)
	s_waitcnt lgkmcnt(0)
	s_barrier
	s_waitcnt lgkmcnt(0)
	v_mfma_i32_16x16x64_i8 v[124:127], v[144:147], v[186:189], v[124:127]
	v_mfma_i32_16x16x64_i8 v[120:123], v[152:155], v[186:189], v[120:123]
	v_mfma_i32_16x16x64_i8 v[108:111], v[144:147], v[194:197], v[108:111]
	v_mfma_i32_16x16x64_i8 v[104:107], v[152:155], v[194:197], v[104:107]
	v_mfma_i32_16x16x64_i8 v[92:95], v[144:147], v[202:205], v[92:95]
	v_mfma_i32_16x16x64_i8 v[88:91], v[152:155], v[202:205], v[88:91]
	v_mfma_i32_16x16x64_i8 v[76:79], v[144:147], v[210:213], v[76:79]
	v_mfma_i32_16x16x64_i8 v[72:75], v[152:155], v[210:213], v[72:75]
	v_mfma_i32_16x16x64_i8 v[124:127], v[148:151], v[190:193], v[124:127]
	v_mfma_i32_16x16x64_i8 v[120:123], v[156:159], v[190:193], v[120:123]
	v_mfma_i32_16x16x64_i8 v[108:111], v[148:151], v[198:201], v[108:111]
	v_mfma_i32_16x16x64_i8 v[104:107], v[156:159], v[198:201], v[104:107]
	v_mfma_i32_16x16x64_i8 v[92:95], v[148:151], v[206:209], v[92:95]
	v_mfma_i32_16x16x64_i8 v[88:91], v[156:159], v[206:209], v[88:91]
	v_mfma_i32_16x16x64_i8 v[76:79], v[148:151], v[214:217], v[76:79]
	v_mfma_i32_16x16x64_i8 v[72:75], v[156:159], v[214:217], v[72:75]
	v_mfma_i32_16x16x64_i8 v[116:119], v[160:163], v[186:189], v[116:119]
	v_mfma_i32_16x16x64_i8 v[112:115], v[168:171], v[186:189], v[112:115]
	v_mfma_i32_16x16x64_i8 v[100:103], v[160:163], v[194:197], v[100:103]
	v_mfma_i32_16x16x64_i8 v[96:99], v[168:171], v[194:197], v[96:99]
	v_mfma_i32_16x16x64_i8 v[84:87], v[160:163], v[202:205], v[84:87]
	v_mfma_i32_16x16x64_i8 v[80:83], v[168:171], v[202:205], v[80:83]
	v_mfma_i32_16x16x64_i8 v[68:71], v[160:163], v[210:213], v[68:71]
	v_mfma_i32_16x16x64_i8 v[64:67], v[168:171], v[210:213], v[64:67]
	v_mfma_i32_16x16x64_i8 v[116:119], v[164:167], v[190:193], v[116:119]
	v_mfma_i32_16x16x64_i8 v[112:115], v[172:175], v[190:193], v[112:115]
	v_mfma_i32_16x16x64_i8 v[100:103], v[164:167], v[198:201], v[100:103]
	v_mfma_i32_16x16x64_i8 v[96:99], v[172:175], v[198:201], v[96:99]
	v_mfma_i32_16x16x64_i8 v[84:87], v[164:167], v[206:209], v[84:87]
	v_mfma_i32_16x16x64_i8 v[80:83], v[172:175], v[206:209], v[80:83]
	v_mfma_i32_16x16x64_i8 v[68:71], v[164:167], v[214:217], v[68:71]
	v_mfma_i32_16x16x64_i8 v[64:67], v[172:175], v[214:217], v[64:67]
	s_barrier
	s_add_i32 s36, s59, s42
	v_lshl_add_u64 v[218:219], v[218:219], 0, s[16:17]
	s_mov_b32 m0, s36
	ds_read_b128 v[186:189], v182 offset:49152
	ds_read_b128 v[190:193], v182 offset:50176
	ds_read_b128 v[194:197], v182 offset:51200
	ds_read_b128 v[198:201], v182 offset:52224
	ds_read_b128 v[202:205], v182 offset:53248
	ds_read_b128 v[206:209], v182 offset:54272
	ds_read_b128 v[210:213], v182 offset:55296
	ds_read_b128 v[214:217], v182 offset:56320
	global_load_lds_dwordx4 v[218:219], off
	s_add_i32 m0, s36, 0x2000
	s_add_u32 s34, s34, 0x80080
	v_lshl_add_u64 v[218:219], v[220:221], 0, s[16:17]
	s_addc_u32 s35, s35, 0
	s_add_i32 s36, s60, s42
	global_load_lds_dwordx4 v[218:219], off
	v_lshl_add_u64 v[218:219], s[34:35], 0, v[130:131]
	s_mov_b32 m0, s36
	s_nop 0
	global_load_lds_dwordx4 v[218:219], off
	v_lshl_add_u64 v[218:219], s[34:35], 0, v[134:135]
	s_add_i32 m0, s36, 0x2000
	s_nop 0
	global_load_lds_dwordx4 v[218:219], off
	v_lshl_add_u64 v[218:219], v[222:223], 0, s[16:17]
	s_mov_b32 m0, s48
	s_nop 0
	global_load_lds_dwordx4 v[218:219], off
	v_lshl_add_u64 v[218:219], v[224:225], 0, s[16:17]
	s_mov_b32 m0, s49
	s_nop 0
	global_load_lds_dwordx4 v[218:219], off
	s_waitcnt vmcnt(8)
	s_waitcnt lgkmcnt(0)
	s_barrier
	s_waitcnt lgkmcnt(0)
	v_mfma_i32_16x16x64_i8 v[60:63], v[144:147], v[186:189], v[60:63]
	v_mfma_i32_16x16x64_i8 v[56:59], v[152:155], v[186:189], v[56:59]
	v_mfma_i32_16x16x64_i8 v[44:47], v[144:147], v[194:197], v[44:47]
	v_mfma_i32_16x16x64_i8 v[40:43], v[152:155], v[194:197], v[40:43]
	v_mfma_i32_16x16x64_i8 v[28:31], v[144:147], v[202:205], v[28:31]
	v_mfma_i32_16x16x64_i8 v[24:27], v[152:155], v[202:205], v[24:27]
	v_mfma_i32_16x16x64_i8 v[12:15], v[144:147], v[210:213], v[12:15]
	v_mfma_i32_16x16x64_i8 v[8:11], v[152:155], v[210:213], v[8:11]
	v_mfma_i32_16x16x64_i8 v[60:63], v[148:151], v[190:193], v[60:63]
	v_mfma_i32_16x16x64_i8 v[56:59], v[156:159], v[190:193], v[56:59]
	v_mfma_i32_16x16x64_i8 v[44:47], v[148:151], v[198:201], v[44:47]
	v_mfma_i32_16x16x64_i8 v[40:43], v[156:159], v[198:201], v[40:43]
	v_mfma_i32_16x16x64_i8 v[28:31], v[148:151], v[206:209], v[28:31]
	v_mfma_i32_16x16x64_i8 v[24:27], v[156:159], v[206:209], v[24:27]
	v_mfma_i32_16x16x64_i8 v[12:15], v[148:151], v[214:217], v[12:15]
	v_mfma_i32_16x16x64_i8 v[8:11], v[156:159], v[214:217], v[8:11]
	v_mfma_i32_16x16x64_i8 v[52:55], v[160:163], v[186:189], v[52:55]
	v_mfma_i32_16x16x64_i8 v[48:51], v[168:171], v[186:189], v[48:51]
	v_mfma_i32_16x16x64_i8 v[36:39], v[160:163], v[194:197], v[36:39]
	v_mfma_i32_16x16x64_i8 v[32:35], v[168:171], v[194:197], v[32:35]
	v_mfma_i32_16x16x64_i8 v[20:23], v[160:163], v[202:205], v[20:23]
	v_mfma_i32_16x16x64_i8 v[16:19], v[168:171], v[202:205], v[16:19]
	v_mfma_i32_16x16x64_i8 v[4:7], v[160:163], v[210:213], v[4:7]
	v_mfma_i32_16x16x64_i8 v[0:3], v[168:171], v[210:213], v[0:3]
	v_mfma_i32_16x16x64_i8 v[52:55], v[164:167], v[190:193], v[52:55]
	v_mfma_i32_16x16x64_i8 v[48:51], v[172:175], v[190:193], v[48:51]
	v_mfma_i32_16x16x64_i8 v[36:39], v[164:167], v[198:201], v[36:39]
	v_mfma_i32_16x16x64_i8 v[32:35], v[172:175], v[198:201], v[32:35]
	v_mfma_i32_16x16x64_i8 v[20:23], v[164:167], v[206:209], v[20:23]
	v_mfma_i32_16x16x64_i8 v[16:19], v[172:175], v[206:209], v[16:19]
	v_mfma_i32_16x16x64_i8 v[4:7], v[164:167], v[214:217], v[4:7]
	v_mfma_i32_16x16x64_i8 v[0:3], v[172:175], v[214:217], v[0:3]
	s_barrier
	s_add_i32 s58, s58, 2
	s_add_u32 s33, s33, 0x100
	s_addc_u32 s57, s57, 0
	s_add_u32 s30, s30, 0x100
	s_addc_u32 s31, s31, 0
	s_cmp_gt_u32 s58, 29
	s_cbranch_scc0 .LBB0_1356
	s_setprio 0
	s_and_b64 vcc, exec, s[18:19]
	s_cbranch_vccz .LBB0_1359
	s_barrier

.LBB0_1840:
	s_ashr_i32 s19, s18, 31
	s_lshl_b64 s[20:21], s[18:19], 22
	s_add_u32 s20, s15, s20
	s_addc_u32 s21, s33, s21
	s_and_b64 s[22:23], s[4:5], exec
	s_cselect_b32 s19, s21, s31
	s_cselect_b32 s25, s20, s30
	s_ashr_i32 s17, s16, 31
	s_lshl_b64 s[22:23], s[16:17], 22
	s_add_u32 s22, s36, s22
	s_addc_u32 s23, s37, s23
	s_and_b64 s[34:35], s[4:5], exec
	s_cselect_b32 s17, s23, s29
	s_cselect_b32 s50, s22, s28
	s_add_u32 s51, s28, 0x100
	s_addc_u32 s52, s29, 0
	s_add_u32 s28, s30, 0x200080
	s_waitcnt vmcnt(0) lgkmcnt(0)
	v_mov_b64_e32 v[18:19], v[2:3]
	v_mov_b64_e32 v[22:23], v[6:7]
	v_mov_b64_e32 v[34:35], v[2:3]
	v_mov_b64_e32 v[38:39], v[6:7]
	v_mov_b64_e32 v[50:51], v[2:3]
	v_mov_b64_e32 v[54:55], v[6:7]
	v_mov_b64_e32 v[26:27], v[10:11]
	v_mov_b64_e32 v[30:31], v[14:15]
	v_mov_b64_e32 v[42:43], v[10:11]
	v_mov_b64_e32 v[46:47], v[14:15]
	v_mov_b64_e32 v[58:59], v[10:11]
	v_mov_b64_e32 v[62:63], v[14:15]
	v_mov_b64_e32 v[66:67], v[2:3]
	v_mov_b64_e32 v[70:71], v[6:7]
	v_mov_b64_e32 v[82:83], v[2:3]
	v_mov_b64_e32 v[86:87], v[6:7]
	v_mov_b64_e32 v[98:99], v[2:3]
	v_mov_b64_e32 v[102:103], v[6:7]
	v_mov_b64_e32 v[122:123], v[2:3]
	v_mov_b64_e32 v[130:131], v[6:7]
	v_mov_b64_e32 v[74:75], v[10:11]
	v_mov_b64_e32 v[78:79], v[14:15]
	v_mov_b64_e32 v[90:91], v[10:11]
	v_mov_b64_e32 v[94:95], v[14:15]
	v_mov_b64_e32 v[110:111], v[10:11]
	v_mov_b64_e32 v[114:115], v[14:15]
	v_mov_b64_e32 v[106:107], v[10:11]
	v_mov_b64_e32 v[118:119], v[14:15]
	s_addc_u32 s29, s31, 0
	s_mov_b32 s53, -2
	v_mov_b64_e32 v[16:17], v[0:1]
	v_mov_b64_e32 v[20:21], v[4:5]
	v_mov_b64_e32 v[32:33], v[0:1]
	v_mov_b64_e32 v[36:37], v[4:5]
	v_mov_b64_e32 v[48:49], v[0:1]
	v_mov_b64_e32 v[52:53], v[4:5]
	v_mov_b64_e32 v[24:25], v[8:9]
	v_mov_b64_e32 v[28:29], v[12:13]
	v_mov_b64_e32 v[40:41], v[8:9]
	v_mov_b64_e32 v[44:45], v[12:13]
	v_mov_b64_e32 v[56:57], v[8:9]
	v_mov_b64_e32 v[60:61], v[12:13]
	v_mov_b64_e32 v[64:65], v[0:1]
	v_mov_b64_e32 v[68:69], v[4:5]
	v_mov_b64_e32 v[80:81], v[0:1]
	v_mov_b64_e32 v[84:85], v[4:5]
	v_mov_b64_e32 v[96:97], v[0:1]
	v_mov_b64_e32 v[100:101], v[4:5]
	v_mov_b64_e32 v[120:121], v[0:1]
	v_mov_b64_e32 v[128:129], v[4:5]
	v_mov_b64_e32 v[72:73], v[8:9]
	v_mov_b64_e32 v[76:77], v[12:13]
	v_mov_b64_e32 v[88:89], v[8:9]
	v_mov_b64_e32 v[92:93], v[12:13]
	v_mov_b64_e32 v[108:109], v[8:9]
	v_mov_b64_e32 v[112:113], v[12:13]
	v_mov_b64_e32 v[104:105], v[8:9]
	v_mov_b64_e32 v[116:117], v[12:13]
	s_cmp_ge_u32 s81, 4
	s_cbranch_scc0 .Lsp_skip9
	s_setprio 1
.Lsp_skip9:
.LBB0_1841:
	v_add_u32_e32 v140, s47, v181
	v_add_u32_e32 v174, s48, v181
	ds_read_b128 v[124:127], v140
	ds_read_b128 v[132:135], v140 offset:1024
	ds_read_b128 v[136:139], v140 offset:2048
	ds_read_b128 v[140:143], v140 offset:3072
	ds_read_b128 v[162:165], v174
	ds_read_b128 v[166:169], v174 offset:1024
	ds_read_b128 v[170:173], v174 offset:2048
	ds_read_b128 v[174:177], v174 offset:3072
	s_add_u32 s30, s28, 0xffe00080
	s_addc_u32 s31, s29, -1
	s_cmpk_eq_i32 s53, 0x7c
	s_cselect_b32 s35, s19, s31
	s_cselect_b32 s34, s25, s30
	s_cselect_b32 s31, s17, s52
	s_cselect_b32 s30, s50, s51
	v_lshl_add_u64 v[178:179], s[28:29], 0, v[156:157]
	s_add_i32 m0, s27, 0xc000
	ds_read_b128 v[186:189], v183
	ds_read_b128 v[190:193], v183 offset:1024
	ds_read_b128 v[194:197], v183 offset:2048
	ds_read_b128 v[198:201], v183 offset:3072
	ds_read_b128 v[202:205], v183 offset:4096
	ds_read_b128 v[206:209], v183 offset:5120
	ds_read_b128 v[210:213], v183 offset:6144
	ds_read_b128 v[214:217], v183 offset:7168
	global_load_lds_dwordx4 v[178:179], off
	v_lshl_add_u64 v[178:179], s[28:29], 0, v[154:155]
	s_add_i32 m0, s27, 0xe000
	s_nop 0
	global_load_lds_dwordx4 v[178:179], off
	s_waitcnt vmcnt(8)
	s_waitcnt lgkmcnt(0)
	s_barrier
	s_waitcnt lgkmcnt(0)
	v_mfma_i32_16x16x64_i8 v[116:119], v[124:127], v[186:189], v[116:119]
	v_mfma_i32_16x16x64_i8 v[104:107], v[136:139], v[186:189], v[104:107]
	v_mfma_i32_16x16x64_i8 v[112:115], v[124:127], v[194:197], v[112:115]
	v_mfma_i32_16x16x64_i8 v[108:111], v[136:139], v[194:197], v[108:111]
	v_mfma_i32_16x16x64_i8 v[92:95], v[124:127], v[202:205], v[92:95]
	v_mfma_i32_16x16x64_i8 v[88:91], v[136:139], v[202:205], v[88:91]
	v_mfma_i32_16x16x64_i8 v[76:79], v[124:127], v[210:213], v[76:79]
	v_mfma_i32_16x16x64_i8 v[72:75], v[136:139], v[210:213], v[72:75]
	v_mfma_i32_16x16x64_i8 v[116:119], v[132:135], v[190:193], v[116:119]
	v_mfma_i32_16x16x64_i8 v[104:107], v[140:143], v[190:193], v[104:107]
	v_mfma_i32_16x16x64_i8 v[112:115], v[132:135], v[198:201], v[112:115]
	v_mfma_i32_16x16x64_i8 v[108:111], v[140:143], v[198:201], v[108:111]
	v_mfma_i32_16x16x64_i8 v[92:95], v[132:135], v[206:209], v[92:95]
	v_mfma_i32_16x16x64_i8 v[88:91], v[140:143], v[206:209], v[88:91]
	v_mfma_i32_16x16x64_i8 v[76:79], v[132:135], v[214:217], v[76:79]
	v_mfma_i32_16x16x64_i8 v[72:75], v[140:143], v[214:217], v[72:75]
	v_mfma_i32_16x16x64_i8 v[128:131], v[162:165], v[186:189], v[128:131]
	v_mfma_i32_16x16x64_i8 v[120:123], v[170:173], v[186:189], v[120:123]
	v_mfma_i32_16x16x64_i8 v[100:103], v[162:165], v[194:197], v[100:103]
	v_mfma_i32_16x16x64_i8 v[96:99], v[170:173], v[194:197], v[96:99]
	v_mfma_i32_16x16x64_i8 v[84:87], v[162:165], v[202:205], v[84:87]
	v_mfma_i32_16x16x64_i8 v[80:83], v[170:173], v[202:205], v[80:83]
	v_mfma_i32_16x16x64_i8 v[68:71], v[162:165], v[210:213], v[68:71]
	v_mfma_i32_16x16x64_i8 v[64:67], v[170:173], v[210:213], v[64:67]
	v_mfma_i32_16x16x64_i8 v[128:131], v[166:169], v[190:193], v[128:131]
	v_mfma_i32_16x16x64_i8 v[120:123], v[174:177], v[190:193], v[120:123]
	v_mfma_i32_16x16x64_i8 v[100:103], v[166:169], v[198:201], v[100:103]
	v_mfma_i32_16x16x64_i8 v[96:99], v[174:177], v[198:201], v[96:99]
	v_mfma_i32_16x16x64_i8 v[84:87], v[166:169], v[206:209], v[84:87]
	v_mfma_i32_16x16x64_i8 v[80:83], v[174:177], v[206:209], v[80:83]
	v_mfma_i32_16x16x64_i8 v[68:71], v[166:169], v[214:217], v[68:71]
	v_mfma_i32_16x16x64_i8 v[64:67], v[174:177], v[214:217], v[64:67]
	s_barrier
	s_add_i32 s54, s47, s38
	v_lshl_add_u64 v[178:179], s[30:31], 0, v[146:147]
	s_mov_b32 m0, s54
	ds_read_b128 v[186:189], v183 offset:16384
	ds_read_b128 v[190:193], v183 offset:17408
	ds_read_b128 v[194:197], v183 offset:18432
	ds_read_b128 v[198:201], v183 offset:19456
	ds_read_b128 v[202:205], v183 offset:20480
	ds_read_b128 v[206:209], v183 offset:21504
	ds_read_b128 v[210:213], v183 offset:22528
	ds_read_b128 v[214:217], v183 offset:23552
	global_load_lds_dwordx4 v[178:179], off
	s_add_i32 m0, s54, 0x2000
	s_add_u32 s54, s30, 0x200000
	v_lshl_add_u64 v[218:219], s[30:31], 0, v[150:151]
	s_addc_u32 s55, s31, 0
	s_add_i32 s56, s48, s38
	global_load_lds_dwordx4 v[218:219], off
	v_lshl_add_u64 v[220:221], s[54:55], 0, v[146:147]
	s_mov_b32 m0, s56
	v_lshl_add_u64 v[222:223], s[34:35], 0, v[148:149]
	global_load_lds_dwordx4 v[220:221], off
	v_lshl_add_u64 v[220:221], s[54:55], 0, v[150:151]
	s_add_i32 m0, s56, 0x2000
	s_nop 0
	global_load_lds_dwordx4 v[220:221], off
	v_lshl_add_u64 v[220:221], s[34:35], 0, v[144:145]
	s_mov_b32 m0, s27
	s_nop 0
	global_load_lds_dwordx4 v[220:221], off
	s_mov_b32 m0, s39
	s_nop 0
	global_load_lds_dwordx4 v[222:223], off
	s_waitcnt vmcnt(8)
	s_waitcnt lgkmcnt(0)
	s_barrier
	s_waitcnt lgkmcnt(0)
	v_mfma_i32_16x16x64_i8 v[60:63], v[124:127], v[186:189], v[60:63]
	v_mfma_i32_16x16x64_i8 v[56:59], v[136:139], v[186:189], v[56:59]
	v_mfma_i32_16x16x64_i8 v[44:47], v[124:127], v[194:197], v[44:47]
	v_mfma_i32_16x16x64_i8 v[40:43], v[136:139], v[194:197], v[40:43]
	v_mfma_i32_16x16x64_i8 v[28:31], v[124:127], v[202:205], v[28:31]
	v_mfma_i32_16x16x64_i8 v[24:27], v[136:139], v[202:205], v[24:27]
	v_mfma_i32_16x16x64_i8 v[12:15], v[124:127], v[210:213], v[12:15]
	v_mfma_i32_16x16x64_i8 v[8:11], v[136:139], v[210:213], v[8:11]
	v_mfma_i32_16x16x64_i8 v[60:63], v[132:135], v[190:193], v[60:63]
	v_mfma_i32_16x16x64_i8 v[56:59], v[140:143], v[190:193], v[56:59]
	v_mfma_i32_16x16x64_i8 v[44:47], v[132:135], v[198:201], v[44:47]
	v_mfma_i32_16x16x64_i8 v[40:43], v[140:143], v[198:201], v[40:43]
	v_mfma_i32_16x16x64_i8 v[28:31], v[132:135], v[206:209], v[28:31]
	v_mfma_i32_16x16x64_i8 v[24:27], v[140:143], v[206:209], v[24:27]
	v_mfma_i32_16x16x64_i8 v[12:15], v[132:135], v[214:217], v[12:15]
	v_mfma_i32_16x16x64_i8 v[8:11], v[140:143], v[214:217], v[8:11]
	v_mfma_i32_16x16x64_i8 v[52:55], v[162:165], v[186:189], v[52:55]
	v_mfma_i32_16x16x64_i8 v[48:51], v[170:173], v[186:189], v[48:51]
	v_mfma_i32_16x16x64_i8 v[36:39], v[162:165], v[194:197], v[36:39]
	v_mfma_i32_16x16x64_i8 v[32:35], v[170:173], v[194:197], v[32:35]
	v_mfma_i32_16x16x64_i8 v[20:23], v[162:165], v[202:205], v[20:23]
	v_mfma_i32_16x16x64_i8 v[16:19], v[170:173], v[202:205], v[16:19]
	v_mfma_i32_16x16x64_i8 v[4:7], v[162:165], v[210:213], v[4:7]
	v_mfma_i32_16x16x64_i8 v[0:3], v[170:173], v[210:213], v[0:3]
	v_mfma_i32_16x16x64_i8 v[52:55], v[166:169], v[190:193], v[52:55]
	v_mfma_i32_16x16x64_i8 v[48:51], v[174:177], v[190:193], v[48:51]
	v_mfma_i32_16x16x64_i8 v[36:39], v[166:169], v[198:201], v[36:39]
	v_mfma_i32_16x16x64_i8 v[32:35], v[174:177], v[198:201], v[32:35]
	v_mfma_i32_16x16x64_i8 v[20:23], v[166:169], v[206:209], v[20:23]
	v_mfma_i32_16x16x64_i8 v[16:19], v[174:177], v[206:209], v[16:19]
	v_mfma_i32_16x16x64_i8 v[4:7], v[166:169], v[214:217], v[4:7]
	v_mfma_i32_16x16x64_i8 v[0:3], v[174:177], v[214:217], v[0:3]
	s_barrier
	s_add_i32 s54, 0, 0x18000
	s_add_i32 s55, 0, 0x1c000
	v_add_u32_e32 v140, s54, v181
	v_add_u32_e32 v174, s55, v181
	ds_read_b128 v[124:127], v140
	ds_read_b128 v[132:135], v140 offset:1024
	ds_read_b128 v[136:139], v140 offset:2048
	ds_read_b128 v[140:143], v140 offset:3072
	ds_read_b128 v[162:165], v174
	ds_read_b128 v[166:169], v174 offset:1024
	ds_read_b128 v[170:173], v174 offset:2048
	ds_read_b128 v[174:177], v174 offset:3072
	s_add_u32 s34, s34, 0x200000
	s_addc_u32 s35, s35, 0
	s_mov_b32 m0, s40
	v_lshl_add_u64 v[224:225], s[34:35], 0, v[144:145]
	ds_read_b128 v[186:189], v183 offset:32768
	ds_read_b128 v[190:193], v183 offset:33792
	ds_read_b128 v[194:197], v183 offset:34816
	ds_read_b128 v[198:201], v183 offset:35840
	ds_read_b128 v[202:205], v183 offset:36864
	ds_read_b128 v[206:209], v183 offset:37888
	ds_read_b128 v[210:213], v183 offset:38912
	ds_read_b128 v[214:217], v183 offset:39936
	global_load_lds_dwordx4 v[224:225], off
	v_lshl_add_u64 v[224:225], s[34:35], 0, v[148:149]
	s_mov_b32 m0, s41
	s_nop 0
	global_load_lds_dwordx4 v[224:225], off
	s_waitcnt vmcnt(8)
	s_waitcnt lgkmcnt(0)
	s_barrier
	s_waitcnt lgkmcnt(0)
	v_mfma_i32_16x16x64_i8 v[116:119], v[124:127], v[186:189], v[116:119]
	v_mfma_i32_16x16x64_i8 v[104:107], v[136:139], v[186:189], v[104:107]
	v_mfma_i32_16x16x64_i8 v[112:115], v[124:127], v[194:197], v[112:115]
	v_mfma_i32_16x16x64_i8 v[108:111], v[136:139], v[194:197], v[108:111]
	v_mfma_i32_16x16x64_i8 v[92:95], v[124:127], v[202:205], v[92:95]
	v_mfma_i32_16x16x64_i8 v[88:91], v[136:139], v[202:205], v[88:91]
	v_mfma_i32_16x16x64_i8 v[76:79], v[124:127], v[210:213], v[76:79]
	v_mfma_i32_16x16x64_i8 v[72:75], v[136:139], v[210:213], v[72:75]
	v_mfma_i32_16x16x64_i8 v[116:119], v[132:135], v[190:193], v[116:119]
	v_mfma_i32_16x16x64_i8 v[104:107], v[140:143], v[190:193], v[104:107]
	v_mfma_i32_16x16x64_i8 v[112:115], v[132:135], v[198:201], v[112:115]
	v_mfma_i32_16x16x64_i8 v[108:111], v[140:143], v[198:201], v[108:111]
	v_mfma_i32_16x16x64_i8 v[92:95], v[132:135], v[206:209], v[92:95]
	v_mfma_i32_16x16x64_i8 v[88:91], v[140:143], v[206:209], v[88:91]
	v_mfma_i32_16x16x64_i8 v[76:79], v[132:135], v[214:217], v[76:79]
	v_mfma_i32_16x16x64_i8 v[72:75], v[140:143], v[214:217], v[72:75]
	v_mfma_i32_16x16x64_i8 v[128:131], v[162:165], v[186:189], v[128:131]
	v_mfma_i32_16x16x64_i8 v[120:123], v[170:173], v[186:189], v[120:123]
	v_mfma_i32_16x16x64_i8 v[100:103], v[162:165], v[194:197], v[100:103]
	v_mfma_i32_16x16x64_i8 v[96:99], v[170:173], v[194:197], v[96:99]
	v_mfma_i32_16x16x64_i8 v[84:87], v[162:165], v[202:205], v[84:87]
	v_mfma_i32_16x16x64_i8 v[80:83], v[170:173], v[202:205], v[80:83]
	v_mfma_i32_16x16x64_i8 v[68:71], v[162:165], v[210:213], v[68:71]
	v_mfma_i32_16x16x64_i8 v[64:67], v[170:173], v[210:213], v[64:67]
	v_mfma_i32_16x16x64_i8 v[128:131], v[166:169], v[190:193], v[128:131]
	v_mfma_i32_16x16x64_i8 v[120:123], v[174:177], v[190:193], v[120:123]
	v_mfma_i32_16x16x64_i8 v[100:103], v[166:169], v[198:201], v[100:103]
	v_mfma_i32_16x16x64_i8 v[96:99], v[174:177], v[198:201], v[96:99]
	v_mfma_i32_16x16x64_i8 v[84:87], v[166:169], v[206:209], v[84:87]
	v_mfma_i32_16x16x64_i8 v[80:83], v[174:177], v[206:209], v[80:83]
	v_mfma_i32_16x16x64_i8 v[68:71], v[166:169], v[214:217], v[68:71]
	v_mfma_i32_16x16x64_i8 v[64:67], v[174:177], v[214:217], v[64:67]
	s_barrier
	s_add_i32 s34, s54, s38
	v_lshl_add_u64 v[178:179], v[178:179], 0, s[10:11]
	s_mov_b32 m0, s34
	ds_read_b128 v[186:189], v183 offset:49152
	ds_read_b128 v[190:193], v183 offset:50176
	ds_read_b128 v[194:197], v183 offset:51200
	ds_read_b128 v[198:201], v183 offset:52224
	ds_read_b128 v[202:205], v183 offset:53248
	ds_read_b128 v[206:209], v183 offset:54272
	ds_read_b128 v[210:213], v183 offset:55296
	ds_read_b128 v[214:217], v183 offset:56320
	global_load_lds_dwordx4 v[178:179], off
	s_add_i32 m0, s34, 0x2000
	s_add_u32 s30, s30, 0x200080
	v_lshl_add_u64 v[178:179], v[218:219], 0, s[10:11]
	s_addc_u32 s31, s31, 0
	s_add_i32 s34, s55, s38
	global_load_lds_dwordx4 v[178:179], off
	v_lshl_add_u64 v[178:179], s[30:31], 0, v[146:147]
	s_mov_b32 m0, s34
	s_nop 0
	global_load_lds_dwordx4 v[178:179], off
	v_lshl_add_u64 v[178:179], s[30:31], 0, v[150:151]
	s_add_i32 m0, s34, 0x2000
	s_nop 0
	global_load_lds_dwordx4 v[178:179], off
	v_lshl_add_u64 v[178:179], v[220:221], 0, s[10:11]
	s_mov_b32 m0, s43
	s_nop 0
	global_load_lds_dwordx4 v[178:179], off
	v_lshl_add_u64 v[178:179], v[222:223], 0, s[10:11]
	s_mov_b32 m0, s44
	s_nop 0
	global_load_lds_dwordx4 v[178:179], off
	s_waitcnt vmcnt(8)
	s_waitcnt lgkmcnt(0)
	s_barrier
	s_waitcnt lgkmcnt(0)
	v_mfma_i32_16x16x64_i8 v[60:63], v[124:127], v[186:189], v[60:63]
	v_mfma_i32_16x16x64_i8 v[56:59], v[136:139], v[186:189], v[56:59]
	v_mfma_i32_16x16x64_i8 v[44:47], v[124:127], v[194:197], v[44:47]
	v_mfma_i32_16x16x64_i8 v[40:43], v[136:139], v[194:197], v[40:43]
	v_mfma_i32_16x16x64_i8 v[28:31], v[124:127], v[202:205], v[28:31]
	v_mfma_i32_16x16x64_i8 v[24:27], v[136:139], v[202:205], v[24:27]
	v_mfma_i32_16x16x64_i8 v[12:15], v[124:127], v[210:213], v[12:15]
	v_mfma_i32_16x16x64_i8 v[8:11], v[136:139], v[210:213], v[8:11]
	v_mfma_i32_16x16x64_i8 v[60:63], v[132:135], v[190:193], v[60:63]
	v_mfma_i32_16x16x64_i8 v[56:59], v[140:143], v[190:193], v[56:59]
	v_mfma_i32_16x16x64_i8 v[44:47], v[132:135], v[198:201], v[44:47]
	v_mfma_i32_16x16x64_i8 v[40:43], v[140:143], v[198:201], v[40:43]
	v_mfma_i32_16x16x64_i8 v[28:31], v[132:135], v[206:209], v[28:31]
	v_mfma_i32_16x16x64_i8 v[24:27], v[140:143], v[206:209], v[24:27]
	v_mfma_i32_16x16x64_i8 v[12:15], v[132:135], v[214:217], v[12:15]
	v_mfma_i32_16x16x64_i8 v[8:11], v[140:143], v[214:217], v[8:11]
	v_mfma_i32_16x16x64_i8 v[52:55], v[162:165], v[186:189], v[52:55]
	v_mfma_i32_16x16x64_i8 v[48:51], v[170:173], v[186:189], v[48:51]
	v_mfma_i32_16x16x64_i8 v[36:39], v[162:165], v[194:197], v[36:39]
	v_mfma_i32_16x16x64_i8 v[32:35], v[170:173], v[194:197], v[32:35]
	v_mfma_i32_16x16x64_i8 v[20:23], v[162:165], v[202:205], v[20:23]
	v_mfma_i32_16x16x64_i8 v[16:19], v[170:173], v[202:205], v[16:19]
	v_mfma_i32_16x16x64_i8 v[4:7], v[162:165], v[210:213], v[4:7]
	v_mfma_i32_16x16x64_i8 v[0:3], v[170:173], v[210:213], v[0:3]
	v_mfma_i32_16x16x64_i8 v[52:55], v[166:169], v[190:193], v[52:55]
	v_mfma_i32_16x16x64_i8 v[48:51], v[174:177], v[190:193], v[48:51]
	v_mfma_i32_16x16x64_i8 v[36:39], v[166:169], v[198:201], v[36:39]
	v_mfma_i32_16x16x64_i8 v[32:35], v[174:177], v[198:201], v[32:35]
	v_mfma_i32_16x16x64_i8 v[20:23], v[166:169], v[206:209], v[20:23]
	v_mfma_i32_16x16x64_i8 v[16:19], v[174:177], v[206:209], v[16:19]
	v_mfma_i32_16x16x64_i8 v[4:7], v[166:169], v[214:217], v[4:7]
	v_mfma_i32_16x16x64_i8 v[0:3], v[174:177], v[214:217], v[0:3]
	s_barrier
	s_add_i32 s53, s53, 2
	s_add_u32 s51, s51, 0x100
	s_addc_u32 s52, s52, 0
	s_add_u32 s28, s28, 0x100
	s_addc_u32 s29, s29, 0
	s_cmpk_gt_u32 s53, 0x7d
	s_cbranch_scc0 .LBB0_1841
	s_setprio 0
	s_and_b64 vcc, exec, s[12:13]
	s_cbranch_vccz .LBB0_1844
	s_barrier
